# v23 + GEMM K-loops: per-trip scalar tile bookkeeping moved out of the first load phase to under the following MFMA block
# speedup vs baseline: 1.0046x; 1.0043x over previous
; #define G_STAGE(bufoff, gbase, v0, v1) do { \
;     __builtin_amdgcn_global_load_lds((const unsigned*)((const char*)(gbase) + (v0)), (LAS unsigned*)(lds + (bufoff) + ldsw), 16, 0, 0); \
;     __builtin_amdgcn_global_load_lds((const unsigned*)((const char*)(gbase) + (v1)), (LAS unsigned*)(lds + (bufoff) + ldsw + 8192), 16, 0, 0); } while (0)
; #define G_LDA(dst, b, h) do { _Pragma("unroll") for (int m = 0; m < 4; ++m) _Pragma("unroll") for (int k = 0; k < 2; ++k) dst[m][k] = *(const LAS h8*)(lds + G_SA(b, h) + aoff + m * 2048 + k * 1024); } while (0)
; #define G_LDB(dst, b, h) do { _Pragma("unroll") for (int n = 0; n < 2; ++n) _Pragma("unroll") for (int k = 0; k < 2; ++k) dst[n][k] = *(const LAS h8*)(lds + G_SB(b, h) + boff + n * 2048 + k * 1024); } while (0)
; #define G_MMA(ai, bj, At, Bt) do { __builtin_amdgcn_s_setprio(1); _Pragma("unroll") for (int m = 0; m < 4; ++m) _Pragma("unroll") for (int n = 0; n < 2; ++n) _Pragma("unroll") for (int k = 0; k < 2; ++k) \
;     acc[ai][bj][m][n] = __builtin_amdgcn_mfma_f32_16x16x32_f16(Bt[n][k], At[m][k], acc[ai][bj][m][n], 0, 0, 0); __builtin_amdgcn_s_setprio(0); } while (0)
; #define G_WAIT_V(n) asm volatile("s_waitcnt vmcnt(" #n ")" ::: "memory")
; #define G_WAIT_L(n) asm volatile("s_waitcnt lgkmcnt(" #n ")" ::: "memory")
; #define G_BAR __builtin_amdgcn_s_barrier()
; #define G_SCHED __builtin_amdgcn_sched_barrier(0)
; template <bool PERM, class Sched, class Epi>
; DI void gemm256(LAS unsigned char* lds, const Sched& S, const Epi& E, int wv_) {
;     ...
;       const bool last = (t == nt - 2);
;       const char* a1 = cA + (size_t)(t + 1) * kstep;
;       const char* a2 = last ? nA : cA + (size_t)(t + 2) * kstep;
;       const char* b2 = last ? nB : cB + (size_t)(t + 2) * kstep;
;       const char* a3 = a2 + kstep;
;       const char* b3 = b2 + kstep;
;       G_LDB(B0, 0, 0); G_SCHED; G_LDA(At, 0, 0); G_STAGE(G_SA(1, 1), a1 + chA, cvA0, cvA1);
;       G_WAIT_L(8); G_BAR; G_WAIT_L(0); G_MMA(0, 0, At, B0); G_BAR; G_SCHED;
;       G_LDB(B1, 0, 1); G_STAGE(G_SB(0, 0), b2, cvB0, cvB1);
;       G_BAR; G_WAIT_L(0); G_MMA(0, 1, At, B1); G_BAR;
;       G_LDA(At, 0, 1); G_STAGE(G_SA(0, 0), a2, cvA0, cvA1);
;       G_BAR; G_WAIT_L(0); G_MMA(1, 0, At, B0); G_BAR; G_SCHED;
;       G_STAGE(G_SB(0, 1), b2 + chB, cvB0, cvB1);
;       G_WAIT_V(6); G_BAR; G_MMA(1, 1, At, B1); G_BAR;
.LBB0_1503:
	s_add_i32 s91, s12, 2
	ds_read_b128 v[146:149], v218
	ds_read_b128 v[150:153], v218 offset:1024
	ds_read_b128 v[154:157], v218 offset:2048
	ds_read_b128 v[158:161], v218 offset:3072
	s_mov_b32 m0, s59
	v_lshl_add_u64 v[194:195], s[10:11], 0, v[138:139]
	ds_read_b128 v[162:165], v142
	ds_read_b128 v[166:169], v142 offset:1024
	ds_read_b128 v[170:173], v142 offset:2048
	ds_read_b128 v[174:177], v142 offset:3072
	ds_read_b128 v[178:181], v142 offset:4096
	ds_read_b128 v[182:185], v142 offset:5120
	ds_read_b128 v[186:189], v142 offset:6144
	ds_read_b128 v[190:193], v142 offset:7168
	global_load_lds_dwordx4 v[194:195], off
	s_mov_b32 m0, s60
	v_lshl_add_u64 v[194:195], s[10:11], 0, v[140:141]
	global_load_lds_dwordx4 v[194:195], off
	s_waitcnt lgkmcnt(8)
	s_barrier
	s_waitcnt lgkmcnt(0)
	s_waitcnt lgkmcnt(0)
	v_mfma_f32_16x16x32_f16 v[122:125], v[146:149], v[162:165], v[122:125]
	s_add_u32 s13, s10, 0xfffc0080
	s_addc_u32 s14, s11, -1
	s_cmp_eq_u32 s75, s12
	s_cselect_b32 s12, s90, s46
	s_cselect_b32 s15, s16, s14
	s_cselect_b32 s14, s17, s13
	s_cselect_b32 s13, s85, s74
	v_mfma_f32_16x16x32_f16 v[126:129], v[154:157], v[162:165], v[126:129]
	v_mfma_f32_16x16x32_f16 v[114:117], v[146:149], v[170:173], v[114:117]
	v_mfma_f32_16x16x32_f16 v[118:121], v[154:157], v[170:173], v[118:121]
	v_mfma_f32_16x16x32_f16 v[106:109], v[146:149], v[178:181], v[106:109]
	v_mfma_f32_16x16x32_f16 v[110:113], v[154:157], v[178:181], v[110:113]
	v_mfma_f32_16x16x32_f16 v[98:101], v[146:149], v[186:189], v[98:101]
	v_mfma_f32_16x16x32_f16 v[102:105], v[154:157], v[186:189], v[102:105]
	v_mfma_f32_16x16x32_f16 v[122:125], v[150:153], v[166:169], v[122:125]
	v_mfma_f32_16x16x32_f16 v[126:129], v[158:161], v[166:169], v[126:129]
	v_mfma_f32_16x16x32_f16 v[114:117], v[150:153], v[174:177], v[114:117]
	v_mfma_f32_16x16x32_f16 v[118:121], v[158:161], v[174:177], v[118:121]
	v_mfma_f32_16x16x32_f16 v[106:109], v[150:153], v[182:185], v[106:109]
	v_mfma_f32_16x16x32_f16 v[110:113], v[158:161], v[182:185], v[110:113]
	v_mfma_f32_16x16x32_f16 v[98:101], v[150:153], v[190:193], v[98:101]
	v_mfma_f32_16x16x32_f16 v[102:105], v[158:161], v[190:193], v[102:105]
	s_barrier
	s_mov_b32 m0, s20
	v_lshl_add_u64 v[210:211], s[12:13], 0, v[132:133]
	ds_read_b128 v[194:197], v219
	ds_read_b128 v[198:201], v219 offset:1024
	ds_read_b128 v[202:205], v219 offset:2048
	ds_read_b128 v[206:209], v219 offset:3072
	global_load_lds_dwordx4 v[210:211], off
	s_mov_b32 m0, s21
	v_lshl_add_u64 v[212:213], s[12:13], 0, v[136:137]
	global_load_lds_dwordx4 v[212:213], off
	s_barrier
	s_waitcnt lgkmcnt(0)
	s_waitcnt lgkmcnt(0)
	v_mfma_f32_16x16x32_f16 v[58:61], v[194:197], v[162:165], v[58:61]
	v_mfma_f32_16x16x32_f16 v[62:65], v[202:205], v[162:165], v[62:65]
	v_mfma_f32_16x16x32_f16 v[50:53], v[194:197], v[170:173], v[50:53]
	v_mfma_f32_16x16x32_f16 v[54:57], v[202:205], v[170:173], v[54:57]
	v_mfma_f32_16x16x32_f16 v[42:45], v[194:197], v[178:181], v[42:45]
	v_mfma_f32_16x16x32_f16 v[46:49], v[202:205], v[178:181], v[46:49]
	v_mfma_f32_16x16x32_f16 v[34:37], v[194:197], v[186:189], v[34:37]
	v_mfma_f32_16x16x32_f16 v[38:41], v[202:205], v[186:189], v[38:41]
	v_mfma_f32_16x16x32_f16 v[58:61], v[198:201], v[166:169], v[58:61]
	v_mfma_f32_16x16x32_f16 v[62:65], v[206:209], v[166:169], v[62:65]
	v_mfma_f32_16x16x32_f16 v[50:53], v[198:201], v[174:177], v[50:53]
	v_mfma_f32_16x16x32_f16 v[54:57], v[206:209], v[174:177], v[54:57]
	v_mfma_f32_16x16x32_f16 v[42:45], v[198:201], v[182:185], v[42:45]
	v_mfma_f32_16x16x32_f16 v[46:49], v[206:209], v[182:185], v[46:49]
	v_mfma_f32_16x16x32_f16 v[34:37], v[198:201], v[190:193], v[34:37]
	v_mfma_f32_16x16x32_f16 v[38:41], v[206:209], v[190:193], v[38:41]
	s_mov_b32 m0, s19
	v_lshl_add_u64 v[214:215], s[14:15], 0, v[130:131]
	s_barrier
	ds_read_b128 v[162:165], v142 offset:16384
	ds_read_b128 v[166:169], v142 offset:17408
	ds_read_b128 v[170:173], v142 offset:18432
	ds_read_b128 v[174:177], v142 offset:19456
	ds_read_b128 v[178:181], v142 offset:20480
	ds_read_b128 v[182:185], v142 offset:21504
	ds_read_b128 v[186:189], v142 offset:22528
	ds_read_b128 v[190:193], v142 offset:23552
	global_load_lds_dwordx4 v[214:215], off
	s_mov_b32 m0, s22
	v_lshl_add_u64 v[216:217], s[14:15], 0, v[134:135]
	global_load_lds_dwordx4 v[216:217], off
	s_barrier
	s_waitcnt lgkmcnt(0)
	s_waitcnt lgkmcnt(0)
	v_mfma_f32_16x16x32_f16 v[90:93], v[146:149], v[162:165], v[90:93]
	v_mfma_f32_16x16x32_f16 v[94:97], v[154:157], v[162:165], v[94:97]
	v_mfma_f32_16x16x32_f16 v[82:85], v[146:149], v[170:173], v[82:85]
	v_mfma_f32_16x16x32_f16 v[86:89], v[154:157], v[170:173], v[86:89]
	v_mfma_f32_16x16x32_f16 v[74:77], v[146:149], v[178:181], v[74:77]
	v_mfma_f32_16x16x32_f16 v[78:81], v[154:157], v[178:181], v[78:81]
	v_mfma_f32_16x16x32_f16 v[66:69], v[146:149], v[186:189], v[66:69]
	v_mfma_f32_16x16x32_f16 v[70:73], v[154:157], v[186:189], v[70:73]
	v_mfma_f32_16x16x32_f16 v[90:93], v[150:153], v[166:169], v[90:93]
	v_mfma_f32_16x16x32_f16 v[94:97], v[158:161], v[166:169], v[94:97]
	v_mfma_f32_16x16x32_f16 v[82:85], v[150:153], v[174:177], v[82:85]
	v_mfma_f32_16x16x32_f16 v[86:89], v[158:161], v[174:177], v[86:89]
	v_mfma_f32_16x16x32_f16 v[74:77], v[150:153], v[182:185], v[74:77]
	v_mfma_f32_16x16x32_f16 v[78:81], v[158:161], v[182:185], v[78:81]
	v_mfma_f32_16x16x32_f16 v[66:69], v[150:153], v[190:193], v[66:69]
	v_mfma_f32_16x16x32_f16 v[70:73], v[158:161], v[190:193], v[70:73]
	s_barrier
	s_add_u32 vcc_lo, s12, 0x40000
	s_addc_u32 vcc_hi, s13, 0
	s_mov_b32 m0, s23
	v_lshl_add_u64 v[146:147], vcc, 0, v[132:133]
	global_load_lds_dwordx4 v[146:147], off
	s_mov_b32 m0, s24
	v_lshl_add_u64 v[146:147], vcc, 0, v[136:137]
	global_load_lds_dwordx4 v[146:147], off
	s_waitcnt vmcnt(6)
	s_barrier
; #define G_STAGE(bufoff, gbase, v0, v1) do { \
;     __builtin_amdgcn_global_load_lds((const unsigned*)((const char*)(gbase) + (v0)), (LAS unsigned*)(lds + (bufoff) + ldsw), 16, 0, 0); \
;     __builtin_amdgcn_global_load_lds((const unsigned*)((const char*)(gbase) + (v1)), (LAS unsigned*)(lds + (bufoff) + ldsw + 8192), 16, 0, 0); } while (0)
; #define G_LDA(dst, b, h) do { _Pragma("unroll") for (int m = 0; m < 4; ++m) _Pragma("unroll") for (int k = 0; k < 2; ++k) dst[m][k] = *(const LAS h8*)(lds + G_SA(b, h) + aoff + m * 2048 + k * 1024); } while (0)
; #define G_LDB(dst, b, h) do { _Pragma("unroll") for (int n = 0; n < 2; ++n) _Pragma("unroll") for (int k = 0; k < 2; ++k) dst[n][k] = *(const LAS h8*)(lds + G_SB(b, h) + boff + n * 2048 + k * 1024); } while (0)
; #define G_MMA(ai, bj, At, Bt) do { __builtin_amdgcn_s_setprio(1); _Pragma("unroll") for (int m = 0; m < 4; ++m) _Pragma("unroll") for (int n = 0; n < 2; ++n) _Pragma("unroll") for (int k = 0; k < 2; ++k) \
;     acc[ai][bj][m][n] = __builtin_amdgcn_mfma_f32_16x16x32_f16(Bt[n][k], At[m][k], acc[ai][bj][m][n], 0, 0, 0); __builtin_amdgcn_s_setprio(0); } while (0)
; #define G_WAIT_V(n) asm volatile("s_waitcnt vmcnt(" #n ")" ::: "memory")
; #define G_WAIT_L(n) asm volatile("s_waitcnt lgkmcnt(" #n ")" ::: "memory")
; #define G_BAR __builtin_amdgcn_s_barrier()
; #define G_SCHED __builtin_amdgcn_sched_barrier(0)
; template <bool PERM, class Sched, class Epi>
; DI void gemm256(LAS unsigned char* lds, const Sched& S, const Epi& E, int wv_) {
;     ...
;       G_WAIT_V(6); G_BAR; G_MMA(1, 1, At, B1); G_BAR;
;       G_LDB(B0, 1, 0); G_SCHED; G_LDA(At, 1, 0); G_STAGE(G_SA(0, 1), a2 + chA, cvA0, cvA1);
;       G_WAIT_L(8); G_BAR; G_WAIT_L(0); G_MMA(0, 0, At, B0); G_BAR; G_SCHED;
;       G_LDB(B1, 1, 1); G_STAGE(G_SB(1, 0), b3, cvB0, cvB1);
	v_mfma_f32_16x16x32_f16 v[26:29], v[194:197], v[162:165], v[26:29]
	v_mfma_f32_16x16x32_f16 v[30:33], v[202:205], v[162:165], v[30:33]
	v_mfma_f32_16x16x32_f16 v[18:21], v[194:197], v[170:173], v[18:21]
	v_mfma_f32_16x16x32_f16 v[22:25], v[202:205], v[170:173], v[22:25]
	v_mfma_f32_16x16x32_f16 v[10:13], v[194:197], v[178:181], v[10:13]
	v_mfma_f32_16x16x32_f16 v[14:17], v[202:205], v[178:181], v[14:17]
	v_mfma_f32_16x16x32_f16 v[6:9], v[194:197], v[186:189], v[6:9]
	v_mfma_f32_16x16x32_f16 v[2:5], v[202:205], v[186:189], v[2:5]
	v_mfma_f32_16x16x32_f16 v[26:29], v[198:201], v[166:169], v[26:29]
	v_mfma_f32_16x16x32_f16 v[30:33], v[206:209], v[166:169], v[30:33]
	v_mfma_f32_16x16x32_f16 v[18:21], v[198:201], v[174:177], v[18:21]
	v_mfma_f32_16x16x32_f16 v[22:25], v[206:209], v[174:177], v[22:25]
	v_mfma_f32_16x16x32_f16 v[10:13], v[198:201], v[182:185], v[10:13]
	v_mfma_f32_16x16x32_f16 v[14:17], v[206:209], v[182:185], v[14:17]
	v_mfma_f32_16x16x32_f16 v[6:9], v[198:201], v[190:193], v[6:9]
	v_mfma_f32_16x16x32_f16 v[2:5], v[206:209], v[190:193], v[2:5]
	s_barrier
	ds_read_b128 v[146:149], v220
	ds_read_b128 v[150:153], v220 offset:1024
	ds_read_b128 v[154:157], v220 offset:2048
	ds_read_b128 v[158:161], v220 offset:3072
	s_add_u32 s14, s14, 0x40000
	s_addc_u32 s15, s15, 0
	s_mov_b32 m0, s25
	v_lshl_add_u64 v[194:195], s[14:15], 0, v[130:131]
	ds_read_b128 v[162:165], v142 offset:32768
	ds_read_b128 v[166:169], v142 offset:33792
	ds_read_b128 v[170:173], v142 offset:34816
	ds_read_b128 v[174:177], v142 offset:35840
	ds_read_b128 v[178:181], v142 offset:36864
	ds_read_b128 v[182:185], v142 offset:37888
	ds_read_b128 v[186:189], v142 offset:38912
	ds_read_b128 v[190:193], v142 offset:39936
	global_load_lds_dwordx4 v[194:195], off
	s_mov_b32 m0, s26
	v_lshl_add_u64 v[194:195], s[14:15], 0, v[134:135]
	global_load_lds_dwordx4 v[194:195], off
	s_waitcnt lgkmcnt(8)
	s_barrier
	s_waitcnt lgkmcnt(0)
	s_waitcnt lgkmcnt(0)
	v_mfma_f32_16x16x32_f16 v[122:125], v[146:149], v[162:165], v[122:125]
	v_mfma_f32_16x16x32_f16 v[126:129], v[154:157], v[162:165], v[126:129]
	v_mfma_f32_16x16x32_f16 v[114:117], v[146:149], v[170:173], v[114:117]
	v_mfma_f32_16x16x32_f16 v[118:121], v[154:157], v[170:173], v[118:121]
	v_mfma_f32_16x16x32_f16 v[106:109], v[146:149], v[178:181], v[106:109]
	v_mfma_f32_16x16x32_f16 v[110:113], v[154:157], v[178:181], v[110:113]
	v_mfma_f32_16x16x32_f16 v[98:101], v[146:149], v[186:189], v[98:101]
	v_mfma_f32_16x16x32_f16 v[102:105], v[154:157], v[186:189], v[102:105]
	v_mfma_f32_16x16x32_f16 v[122:125], v[150:153], v[166:169], v[122:125]
	v_mfma_f32_16x16x32_f16 v[126:129], v[158:161], v[166:169], v[126:129]
	v_mfma_f32_16x16x32_f16 v[114:117], v[150:153], v[174:177], v[114:117]
	v_mfma_f32_16x16x32_f16 v[118:121], v[158:161], v[174:177], v[118:121]
	v_mfma_f32_16x16x32_f16 v[106:109], v[150:153], v[182:185], v[106:109]
	v_mfma_f32_16x16x32_f16 v[110:113], v[158:161], v[182:185], v[110:113]
	v_mfma_f32_16x16x32_f16 v[98:101], v[150:153], v[190:193], v[98:101]
	v_mfma_f32_16x16x32_f16 v[102:105], v[158:161], v[190:193], v[102:105]
	s_barrier
	s_mov_b32 m0, s29
	v_lshl_add_u64 v[210:211], v[210:211], 0, s[86:87]
	ds_read_b128 v[194:197], v221
	ds_read_b128 v[198:201], v221 offset:1024
	ds_read_b128 v[202:205], v221 offset:2048
	ds_read_b128 v[206:209], v221 offset:3072
	global_load_lds_dwordx4 v[210:211], off
	s_mov_b32 m0, s30
	v_lshl_add_u64 v[210:211], v[212:213], 0, s[86:87]
	global_load_lds_dwordx4 v[210:211], off
	s_barrier
; #define G_STAGE(bufoff, gbase, v0, v1) do { \
;     __builtin_amdgcn_global_load_lds((const unsigned*)((const char*)(gbase) + (v0)), (LAS unsigned*)(lds + (bufoff) + ldsw), 16, 0, 0); \
;     __builtin_amdgcn_global_load_lds((const unsigned*)((const char*)(gbase) + (v1)), (LAS unsigned*)(lds + (bufoff) + ldsw + 8192), 16, 0, 0); } while (0)
; #define G_LDA(dst, b, h) do { _Pragma("unroll") for (int m = 0; m < 4; ++m) _Pragma("unroll") for (int k = 0; k < 2; ++k) dst[m][k] = *(const LAS h8*)(lds + G_SA(b, h) + aoff + m * 2048 + k * 1024); } while (0)
; #define G_MMA(ai, bj, At, Bt) do { __builtin_amdgcn_s_setprio(1); _Pragma("unroll") for (int m = 0; m < 4; ++m) _Pragma("unroll") for (int n = 0; n < 2; ++n) _Pragma("unroll") for (int k = 0; k < 2; ++k) \
;     acc[ai][bj][m][n] = __builtin_amdgcn_mfma_f32_16x16x32_f16(Bt[n][k], At[m][k], acc[ai][bj][m][n], 0, 0, 0); __builtin_amdgcn_s_setprio(0); } while (0)
; #define G_WAIT_V(n) asm volatile("s_waitcnt vmcnt(" #n ")" ::: "memory")
; #define G_WAIT_L(n) asm volatile("s_waitcnt lgkmcnt(" #n ")" ::: "memory")
; #define G_BAR __builtin_amdgcn_s_barrier()
; #define G_SCHED __builtin_amdgcn_sched_barrier(0)
; template <bool PERM, class Sched, class Epi>
; DI void gemm256(LAS unsigned char* lds, const Sched& S, const Epi& E, int wv_) {
;     ...
;       G_BAR; G_WAIT_L(0); G_MMA(0, 1, At, B1); G_BAR;
;       G_LDA(At, 1, 1); G_STAGE(G_SA(1, 0), a3, cvA0, cvA1);
;       G_BAR; G_WAIT_L(0); G_MMA(1, 0, At, B0); G_BAR; G_SCHED;
;       G_STAGE(G_SB(1, 1), b3 + chB, cvB0, cvB1);
;       G_WAIT_V(6); G_BAR; G_MMA(1, 1, At, B1); G_BAR;
;     }
;     bool keep = false;
;     if constexpr (Sched::CHAIN) keep = E(acc, cur, wr, wc, fr, fq); else E(acc, cur, wr, wc, fr, fq);
;     if (!has_next) break;
	s_waitcnt lgkmcnt(0)
	s_waitcnt lgkmcnt(0)
	v_mfma_f32_16x16x32_f16 v[58:61], v[194:197], v[162:165], v[58:61]
	v_mfma_f32_16x16x32_f16 v[62:65], v[202:205], v[162:165], v[62:65]
	v_mfma_f32_16x16x32_f16 v[50:53], v[194:197], v[170:173], v[50:53]
	v_mfma_f32_16x16x32_f16 v[54:57], v[202:205], v[170:173], v[54:57]
	v_mfma_f32_16x16x32_f16 v[42:45], v[194:197], v[178:181], v[42:45]
	v_mfma_f32_16x16x32_f16 v[46:49], v[202:205], v[178:181], v[46:49]
	v_mfma_f32_16x16x32_f16 v[34:37], v[194:197], v[186:189], v[34:37]
	v_mfma_f32_16x16x32_f16 v[38:41], v[202:205], v[186:189], v[38:41]
	v_mfma_f32_16x16x32_f16 v[58:61], v[198:201], v[166:169], v[58:61]
	v_mfma_f32_16x16x32_f16 v[62:65], v[206:209], v[166:169], v[62:65]
	v_mfma_f32_16x16x32_f16 v[50:53], v[198:201], v[174:177], v[50:53]
	v_mfma_f32_16x16x32_f16 v[54:57], v[206:209], v[174:177], v[54:57]
	v_mfma_f32_16x16x32_f16 v[42:45], v[198:201], v[182:185], v[42:45]
	v_mfma_f32_16x16x32_f16 v[46:49], v[206:209], v[182:185], v[46:49]
	v_mfma_f32_16x16x32_f16 v[34:37], v[198:201], v[190:193], v[34:37]
	v_mfma_f32_16x16x32_f16 v[38:41], v[206:209], v[190:193], v[38:41]
	s_mov_b32 m0, s31
	v_lshl_add_u64 v[210:211], v[214:215], 0, s[86:87]
	s_barrier
	ds_read_b128 v[162:165], v142 offset:49152
	ds_read_b128 v[166:169], v142 offset:50176
	ds_read_b128 v[170:173], v142 offset:51200
	ds_read_b128 v[174:177], v142 offset:52224
	ds_read_b128 v[178:181], v142 offset:53248
	ds_read_b128 v[182:185], v142 offset:54272
	ds_read_b128 v[186:189], v142 offset:55296
	ds_read_b128 v[190:193], v142 offset:56320
	global_load_lds_dwordx4 v[210:211], off
	s_mov_b32 m0, s34
	v_lshl_add_u64 v[210:211], v[216:217], 0, s[86:87]
	global_load_lds_dwordx4 v[210:211], off
	s_barrier
	s_waitcnt lgkmcnt(0)
	s_waitcnt lgkmcnt(0)
	v_mfma_f32_16x16x32_f16 v[90:93], v[146:149], v[162:165], v[90:93]
	v_mfma_f32_16x16x32_f16 v[94:97], v[154:157], v[162:165], v[94:97]
	v_mfma_f32_16x16x32_f16 v[82:85], v[146:149], v[170:173], v[82:85]
	v_mfma_f32_16x16x32_f16 v[86:89], v[154:157], v[170:173], v[86:89]
	v_mfma_f32_16x16x32_f16 v[74:77], v[146:149], v[178:181], v[74:77]
	v_mfma_f32_16x16x32_f16 v[78:81], v[154:157], v[178:181], v[78:81]
	v_mfma_f32_16x16x32_f16 v[66:69], v[146:149], v[186:189], v[66:69]
	v_mfma_f32_16x16x32_f16 v[70:73], v[154:157], v[186:189], v[70:73]
	v_mfma_f32_16x16x32_f16 v[90:93], v[150:153], v[166:169], v[90:93]
	v_mfma_f32_16x16x32_f16 v[94:97], v[158:161], v[166:169], v[94:97]
	v_mfma_f32_16x16x32_f16 v[82:85], v[150:153], v[174:177], v[82:85]
	v_mfma_f32_16x16x32_f16 v[86:89], v[158:161], v[174:177], v[86:89]
	v_mfma_f32_16x16x32_f16 v[74:77], v[150:153], v[182:185], v[74:77]
	v_mfma_f32_16x16x32_f16 v[78:81], v[158:161], v[182:185], v[78:81]
	v_mfma_f32_16x16x32_f16 v[66:69], v[150:153], v[190:193], v[66:69]
	v_mfma_f32_16x16x32_f16 v[70:73], v[158:161], v[190:193], v[70:73]
	s_barrier
	s_add_u32 s12, s12, 0x40080
	s_addc_u32 s13, s13, 0
	s_mov_b32 m0, s35
	v_lshl_add_u64 v[146:147], s[12:13], 0, v[132:133]
	global_load_lds_dwordx4 v[146:147], off
	s_mov_b32 m0, s36
	v_lshl_add_u64 v[146:147], s[12:13], 0, v[136:137]
	global_load_lds_dwordx4 v[146:147], off
	s_waitcnt vmcnt(6)
	s_barrier
	v_mfma_f32_16x16x32_f16 v[26:29], v[194:197], v[162:165], v[26:29]
	v_mfma_f32_16x16x32_f16 v[30:33], v[202:205], v[162:165], v[30:33]
	v_mfma_f32_16x16x32_f16 v[18:21], v[194:197], v[170:173], v[18:21]
	v_mfma_f32_16x16x32_f16 v[22:25], v[202:205], v[170:173], v[22:25]
	v_mfma_f32_16x16x32_f16 v[10:13], v[194:197], v[178:181], v[10:13]
	v_mfma_f32_16x16x32_f16 v[14:17], v[202:205], v[178:181], v[14:17]
	v_mfma_f32_16x16x32_f16 v[6:9], v[194:197], v[186:189], v[6:9]
	v_mfma_f32_16x16x32_f16 v[2:5], v[202:205], v[186:189], v[2:5]
	v_mfma_f32_16x16x32_f16 v[26:29], v[198:201], v[166:169], v[26:29]
	v_mfma_f32_16x16x32_f16 v[30:33], v[206:209], v[166:169], v[30:33]
	v_mfma_f32_16x16x32_f16 v[18:21], v[198:201], v[174:177], v[18:21]
	v_mfma_f32_16x16x32_f16 v[22:25], v[206:209], v[174:177], v[22:25]
	v_mfma_f32_16x16x32_f16 v[10:13], v[198:201], v[182:185], v[10:13]
	v_mfma_f32_16x16x32_f16 v[14:17], v[206:209], v[182:185], v[14:17]
	v_mfma_f32_16x16x32_f16 v[6:9], v[198:201], v[190:193], v[6:9]
	v_mfma_f32_16x16x32_f16 v[2:5], v[206:209], v[190:193], v[2:5]
	s_add_u32 s10, s10, 0x100
	s_addc_u32 s11, s11, 0
	s_add_u32 s46, s46, 0x100
	s_addc_u32 s74, s74, 0
	s_cmp_ge_i32 s91, s7
	s_mov_b32 s12, s91
	s_barrier
	s_cbranch_scc0 .LBB0_1503
	v_readlane_b32 s91, v254, 47
	s_movk_i32 s85, 0x800
	s_xor_b64 s[8:9], s[8:9], -1
	s_cmp_lg_u32 s84, 0
	s_cbranch_scc0 .LBB0_1509

; #define G_STAGE(bufoff, gbase, v0, v1) do { \
;     __builtin_amdgcn_global_load_lds((const unsigned*)((const char*)(gbase) + (v0)), (LAS unsigned*)(lds + (bufoff) + ldsw), 16, 0, 0); \
;     __builtin_amdgcn_global_load_lds((const unsigned*)((const char*)(gbase) + (v1)), (LAS unsigned*)(lds + (bufoff) + ldsw + 8192), 16, 0, 0); } while (0)
; #define G_LDA(dst, b, h) do { _Pragma("unroll") for (int m = 0; m < 4; ++m) _Pragma("unroll") for (int k = 0; k < 2; ++k) dst[m][k] = *(const LAS h8*)(lds + G_SA(b, h) + aoff + m * 2048 + k * 1024); } while (0)
; #define G_LDB(dst, b, h) do { _Pragma("unroll") for (int n = 0; n < 2; ++n) _Pragma("unroll") for (int k = 0; k < 2; ++k) dst[n][k] = *(const LAS h8*)(lds + G_SB(b, h) + boff + n * 2048 + k * 1024); } while (0)
; #define G_MMA(ai, bj, At, Bt) do { __builtin_amdgcn_s_setprio(1); _Pragma("unroll") for (int m = 0; m < 4; ++m) _Pragma("unroll") for (int n = 0; n < 2; ++n) _Pragma("unroll") for (int k = 0; k < 2; ++k) \
;     acc[ai][bj][m][n] = __builtin_amdgcn_mfma_f32_16x16x32_f16(Bt[n][k], At[m][k], acc[ai][bj][m][n], 0, 0, 0); __builtin_amdgcn_s_setprio(0); } while (0)
; #define G_WAIT_V(n) asm volatile("s_waitcnt vmcnt(" #n ")" ::: "memory")
; #define G_WAIT_L(n) asm volatile("s_waitcnt lgkmcnt(" #n ")" ::: "memory")
; #define G_BAR __builtin_amdgcn_s_barrier()
; #define G_SCHED __builtin_amdgcn_sched_barrier(0)
; template <bool PERM, class Sched, class Epi>
; DI void gemm256(LAS unsigned char* lds, const Sched& S, const Epi& E, int wv_) {
;     ...
;       const bool last = (t == nt - 2);
;       const char* a1 = cA + (size_t)(t + 1) * kstep;
;       const char* a2 = last ? nA : cA + (size_t)(t + 2) * kstep;
;       const char* b2 = last ? nB : cB + (size_t)(t + 2) * kstep;
;       const char* a3 = a2 + kstep;
;       const char* b3 = b2 + kstep;
;       G_LDB(B0, 0, 0); G_SCHED; G_LDA(At, 0, 0); G_STAGE(G_SA(1, 1), a1 + chA, cvA0, cvA1);
;       G_WAIT_L(8); G_BAR; G_WAIT_L(0); G_MMA(0, 0, At, B0); G_BAR; G_SCHED;
;       G_LDB(B1, 0, 1); G_STAGE(G_SB(0, 0), b2, cvB0, cvB1);
;       G_BAR; G_WAIT_L(0); G_MMA(0, 1, At, B1); G_BAR;
;       G_LDA(At, 0, 1); G_STAGE(G_SA(0, 0), a2, cvA0, cvA1);
;       G_BAR; G_WAIT_L(0); G_MMA(1, 0, At, B0); G_BAR; G_SCHED;
;       G_STAGE(G_SB(0, 1), b2 + chB, cvB0, cvB1);
;       G_WAIT_V(6); G_BAR; G_MMA(1, 1, At, B1); G_BAR;
.LBB0_1718:
	s_add_i32 s74, s12, 2
	ds_read_b128 v[144:147], v216
	ds_read_b128 v[148:151], v216 offset:1024
	ds_read_b128 v[152:155], v216 offset:2048
	ds_read_b128 v[156:159], v216 offset:3072
	v_lshl_add_u64 v[192:193], s[10:11], 0, v[138:139]
	s_add_i32 m0, s19, 0xc000
	ds_read_b128 v[160:163], v1
	ds_read_b128 v[164:167], v1 offset:1024
	ds_read_b128 v[168:171], v1 offset:2048
	ds_read_b128 v[172:175], v1 offset:3072
	ds_read_b128 v[176:179], v1 offset:4096
	ds_read_b128 v[180:183], v1 offset:5120
	ds_read_b128 v[184:187], v1 offset:6144
	ds_read_b128 v[188:191], v1 offset:7168
	global_load_lds_dwordx4 v[192:193], off
	s_add_i32 m0, s19, 0xe000
	v_lshl_add_u64 v[192:193], s[10:11], 0, v[140:141]
	global_load_lds_dwordx4 v[192:193], off
	s_waitcnt lgkmcnt(8)
	s_barrier
	s_waitcnt lgkmcnt(0)
	s_waitcnt lgkmcnt(0)
	v_mfma_f32_16x16x32_f16 v[122:125], v[144:147], v[160:163], v[122:125]
	s_add_u32 s13, s10, 0xfffea080
	s_addc_u32 s14, s11, -1
	s_cmp_eq_u32 vcc_lo, s12
	s_cselect_b32 s12, s93, s75
	s_cselect_b32 s15, s84, s14
	s_cselect_b32 s14, s85, s13
	s_cselect_b32 s13, s90, s46
	v_mfma_f32_16x16x32_f16 v[126:129], v[152:155], v[160:163], v[126:129]
	v_mfma_f32_16x16x32_f16 v[114:117], v[144:147], v[168:171], v[114:117]
	v_mfma_f32_16x16x32_f16 v[118:121], v[152:155], v[168:171], v[118:121]
	v_mfma_f32_16x16x32_f16 v[106:109], v[144:147], v[176:179], v[106:109]
	v_mfma_f32_16x16x32_f16 v[110:113], v[152:155], v[176:179], v[110:113]
	v_mfma_f32_16x16x32_f16 v[98:101], v[144:147], v[184:187], v[98:101]
	v_mfma_f32_16x16x32_f16 v[102:105], v[152:155], v[184:187], v[102:105]
	v_mfma_f32_16x16x32_f16 v[122:125], v[148:151], v[164:167], v[122:125]
	v_mfma_f32_16x16x32_f16 v[126:129], v[156:159], v[164:167], v[126:129]
	v_mfma_f32_16x16x32_f16 v[114:117], v[148:151], v[172:175], v[114:117]
	v_mfma_f32_16x16x32_f16 v[118:121], v[156:159], v[172:175], v[118:121]
	v_mfma_f32_16x16x32_f16 v[106:109], v[148:151], v[180:183], v[106:109]
	v_mfma_f32_16x16x32_f16 v[110:113], v[156:159], v[180:183], v[110:113]
	v_mfma_f32_16x16x32_f16 v[98:101], v[148:151], v[188:191], v[98:101]
	v_mfma_f32_16x16x32_f16 v[102:105], v[156:159], v[188:191], v[102:105]
	s_barrier
	s_mov_b32 m0, s20
	v_lshl_add_u64 v[208:209], s[12:13], 0, v[132:133]
	ds_read_b128 v[192:195], v217
	ds_read_b128 v[196:199], v217 offset:1024
	ds_read_b128 v[200:203], v217 offset:2048
	ds_read_b128 v[204:207], v217 offset:3072
	global_load_lds_dwordx4 v[208:209], off
	s_mov_b32 m0, s21
	v_lshl_add_u64 v[210:211], s[12:13], 0, v[136:137]
	global_load_lds_dwordx4 v[210:211], off
	s_barrier
	s_waitcnt lgkmcnt(0)
	s_waitcnt lgkmcnt(0)
	v_mfma_f32_16x16x32_f16 v[58:61], v[192:195], v[160:163], v[58:61]
	v_mfma_f32_16x16x32_f16 v[62:65], v[200:203], v[160:163], v[62:65]
	v_mfma_f32_16x16x32_f16 v[50:53], v[192:195], v[168:171], v[50:53]
	v_mfma_f32_16x16x32_f16 v[54:57], v[200:203], v[168:171], v[54:57]
	v_mfma_f32_16x16x32_f16 v[42:45], v[192:195], v[176:179], v[42:45]
	v_mfma_f32_16x16x32_f16 v[46:49], v[200:203], v[176:179], v[46:49]
	v_mfma_f32_16x16x32_f16 v[34:37], v[192:195], v[184:187], v[34:37]
	v_mfma_f32_16x16x32_f16 v[38:41], v[200:203], v[184:187], v[38:41]
	v_mfma_f32_16x16x32_f16 v[58:61], v[196:199], v[164:167], v[58:61]
	v_mfma_f32_16x16x32_f16 v[62:65], v[204:207], v[164:167], v[62:65]
	v_mfma_f32_16x16x32_f16 v[50:53], v[196:199], v[172:175], v[50:53]
	v_mfma_f32_16x16x32_f16 v[54:57], v[204:207], v[172:175], v[54:57]
	v_mfma_f32_16x16x32_f16 v[42:45], v[196:199], v[180:183], v[42:45]
	v_mfma_f32_16x16x32_f16 v[46:49], v[204:207], v[180:183], v[46:49]
	v_mfma_f32_16x16x32_f16 v[34:37], v[196:199], v[188:191], v[34:37]
	v_mfma_f32_16x16x32_f16 v[38:41], v[204:207], v[188:191], v[38:41]
	s_mov_b32 m0, s19
	v_lshl_add_u64 v[212:213], s[14:15], 0, v[130:131]
	s_barrier
	ds_read_b128 v[160:163], v1 offset:16384
	ds_read_b128 v[164:167], v1 offset:17408
	ds_read_b128 v[168:171], v1 offset:18432
	ds_read_b128 v[172:175], v1 offset:19456
	ds_read_b128 v[176:179], v1 offset:20480
	ds_read_b128 v[180:183], v1 offset:21504
	ds_read_b128 v[184:187], v1 offset:22528
	ds_read_b128 v[188:191], v1 offset:23552
	global_load_lds_dwordx4 v[212:213], off
	s_mov_b32 m0, s22
	v_lshl_add_u64 v[214:215], s[14:15], 0, v[134:135]
	global_load_lds_dwordx4 v[214:215], off
	s_barrier
	s_waitcnt lgkmcnt(0)
	s_waitcnt lgkmcnt(0)
	v_mfma_f32_16x16x32_f16 v[90:93], v[144:147], v[160:163], v[90:93]
	v_mfma_f32_16x16x32_f16 v[94:97], v[152:155], v[160:163], v[94:97]
	v_mfma_f32_16x16x32_f16 v[82:85], v[144:147], v[168:171], v[82:85]
	v_mfma_f32_16x16x32_f16 v[86:89], v[152:155], v[168:171], v[86:89]
	v_mfma_f32_16x16x32_f16 v[74:77], v[144:147], v[176:179], v[74:77]
	v_mfma_f32_16x16x32_f16 v[78:81], v[152:155], v[176:179], v[78:81]
	v_mfma_f32_16x16x32_f16 v[66:69], v[144:147], v[184:187], v[66:69]
	v_mfma_f32_16x16x32_f16 v[70:73], v[152:155], v[184:187], v[70:73]
	v_mfma_f32_16x16x32_f16 v[90:93], v[148:151], v[164:167], v[90:93]
	v_mfma_f32_16x16x32_f16 v[94:97], v[156:159], v[164:167], v[94:97]
	v_mfma_f32_16x16x32_f16 v[82:85], v[148:151], v[172:175], v[82:85]
	v_mfma_f32_16x16x32_f16 v[86:89], v[156:159], v[172:175], v[86:89]
	v_mfma_f32_16x16x32_f16 v[74:77], v[148:151], v[180:183], v[74:77]
	v_mfma_f32_16x16x32_f16 v[78:81], v[156:159], v[180:183], v[78:81]
	v_mfma_f32_16x16x32_f16 v[66:69], v[148:151], v[188:191], v[66:69]
	v_mfma_f32_16x16x32_f16 v[70:73], v[156:159], v[188:191], v[70:73]
	s_barrier
	s_add_u32 s68, s12, 0x10000
	s_addc_u32 s69, s13, 0
	s_mov_b32 m0, s23
	v_lshl_add_u64 v[144:145], s[68:69], 0, v[132:133]
	global_load_lds_dwordx4 v[144:145], off
	s_mov_b32 m0, s24
	v_lshl_add_u64 v[144:145], s[68:69], 0, v[136:137]
	global_load_lds_dwordx4 v[144:145], off
	s_waitcnt vmcnt(6)
	s_barrier
; #define G_STAGE(bufoff, gbase, v0, v1) do { \
;     __builtin_amdgcn_global_load_lds((const unsigned*)((const char*)(gbase) + (v0)), (LAS unsigned*)(lds + (bufoff) + ldsw), 16, 0, 0); \
;     __builtin_amdgcn_global_load_lds((const unsigned*)((const char*)(gbase) + (v1)), (LAS unsigned*)(lds + (bufoff) + ldsw + 8192), 16, 0, 0); } while (0)
; #define G_LDA(dst, b, h) do { _Pragma("unroll") for (int m = 0; m < 4; ++m) _Pragma("unroll") for (int k = 0; k < 2; ++k) dst[m][k] = *(const LAS h8*)(lds + G_SA(b, h) + aoff + m * 2048 + k * 1024); } while (0)
; #define G_LDB(dst, b, h) do { _Pragma("unroll") for (int n = 0; n < 2; ++n) _Pragma("unroll") for (int k = 0; k < 2; ++k) dst[n][k] = *(const LAS h8*)(lds + G_SB(b, h) + boff + n * 2048 + k * 1024); } while (0)
; #define G_MMA(ai, bj, At, Bt) do { __builtin_amdgcn_s_setprio(1); _Pragma("unroll") for (int m = 0; m < 4; ++m) _Pragma("unroll") for (int n = 0; n < 2; ++n) _Pragma("unroll") for (int k = 0; k < 2; ++k) \
;     acc[ai][bj][m][n] = __builtin_amdgcn_mfma_f32_16x16x32_f16(Bt[n][k], At[m][k], acc[ai][bj][m][n], 0, 0, 0); __builtin_amdgcn_s_setprio(0); } while (0)
; #define G_WAIT_V(n) asm volatile("s_waitcnt vmcnt(" #n ")" ::: "memory")
; #define G_WAIT_L(n) asm volatile("s_waitcnt lgkmcnt(" #n ")" ::: "memory")
; #define G_BAR __builtin_amdgcn_s_barrier()
; #define G_SCHED __builtin_amdgcn_sched_barrier(0)
; template <bool PERM, class Sched, class Epi>
; DI void gemm256(LAS unsigned char* lds, const Sched& S, const Epi& E, int wv_) {
;     ...
;       G_WAIT_V(6); G_BAR; G_MMA(1, 1, At, B1); G_BAR;
;       G_LDB(B0, 1, 0); G_SCHED; G_LDA(At, 1, 0); G_STAGE(G_SA(0, 1), a2 + chA, cvA0, cvA1);
;       G_WAIT_L(8); G_BAR; G_WAIT_L(0); G_MMA(0, 0, At, B0); G_BAR; G_SCHED;
;       G_LDB(B1, 1, 1); G_STAGE(G_SB(1, 0), b3, cvB0, cvB1);
	v_mfma_f32_16x16x32_f16 v[26:29], v[192:195], v[160:163], v[26:29]
	v_mfma_f32_16x16x32_f16 v[30:33], v[200:203], v[160:163], v[30:33]
	v_mfma_f32_16x16x32_f16 v[18:21], v[192:195], v[168:171], v[18:21]
	v_mfma_f32_16x16x32_f16 v[22:25], v[200:203], v[168:171], v[22:25]
	v_mfma_f32_16x16x32_f16 v[10:13], v[192:195], v[176:179], v[10:13]
	v_mfma_f32_16x16x32_f16 v[14:17], v[200:203], v[176:179], v[14:17]
	v_mfma_f32_16x16x32_f16 v[6:9], v[192:195], v[184:187], v[6:9]
	v_mfma_f32_16x16x32_f16 v[2:5], v[200:203], v[184:187], v[2:5]
	v_mfma_f32_16x16x32_f16 v[26:29], v[196:199], v[164:167], v[26:29]
	v_mfma_f32_16x16x32_f16 v[30:33], v[204:207], v[164:167], v[30:33]
	v_mfma_f32_16x16x32_f16 v[18:21], v[196:199], v[172:175], v[18:21]
	v_mfma_f32_16x16x32_f16 v[22:25], v[204:207], v[172:175], v[22:25]
	v_mfma_f32_16x16x32_f16 v[10:13], v[196:199], v[180:183], v[10:13]
	v_mfma_f32_16x16x32_f16 v[14:17], v[204:207], v[180:183], v[14:17]
	v_mfma_f32_16x16x32_f16 v[6:9], v[196:199], v[188:191], v[6:9]
	v_mfma_f32_16x16x32_f16 v[2:5], v[204:207], v[188:191], v[2:5]
	s_barrier
	ds_read_b128 v[144:147], v218
	ds_read_b128 v[148:151], v218 offset:1024
	ds_read_b128 v[152:155], v218 offset:2048
	ds_read_b128 v[156:159], v218 offset:3072
	s_add_u32 s14, s14, 0x16000
	s_addc_u32 s15, s15, 0
	s_mov_b32 m0, s25
	v_lshl_add_u64 v[192:193], s[14:15], 0, v[130:131]
	ds_read_b128 v[160:163], v1 offset:32768
	ds_read_b128 v[164:167], v1 offset:33792
	ds_read_b128 v[168:171], v1 offset:34816
	ds_read_b128 v[172:175], v1 offset:35840
	ds_read_b128 v[176:179], v1 offset:36864
	ds_read_b128 v[180:183], v1 offset:37888
	ds_read_b128 v[184:187], v1 offset:38912
	ds_read_b128 v[188:191], v1 offset:39936
	global_load_lds_dwordx4 v[192:193], off
	s_mov_b32 m0, s26
	v_lshl_add_u64 v[192:193], s[14:15], 0, v[134:135]
	global_load_lds_dwordx4 v[192:193], off
	s_waitcnt lgkmcnt(8)
	s_barrier
	s_waitcnt lgkmcnt(0)
	s_waitcnt lgkmcnt(0)
	v_mfma_f32_16x16x32_f16 v[122:125], v[144:147], v[160:163], v[122:125]
	v_mfma_f32_16x16x32_f16 v[126:129], v[152:155], v[160:163], v[126:129]
	v_mfma_f32_16x16x32_f16 v[114:117], v[144:147], v[168:171], v[114:117]
	v_mfma_f32_16x16x32_f16 v[118:121], v[152:155], v[168:171], v[118:121]
	v_mfma_f32_16x16x32_f16 v[106:109], v[144:147], v[176:179], v[106:109]
	v_mfma_f32_16x16x32_f16 v[110:113], v[152:155], v[176:179], v[110:113]
	v_mfma_f32_16x16x32_f16 v[98:101], v[144:147], v[184:187], v[98:101]
	v_mfma_f32_16x16x32_f16 v[102:105], v[152:155], v[184:187], v[102:105]
	v_mfma_f32_16x16x32_f16 v[122:125], v[148:151], v[164:167], v[122:125]
	v_mfma_f32_16x16x32_f16 v[126:129], v[156:159], v[164:167], v[126:129]
	v_mfma_f32_16x16x32_f16 v[114:117], v[148:151], v[172:175], v[114:117]
	v_mfma_f32_16x16x32_f16 v[118:121], v[156:159], v[172:175], v[118:121]
	v_mfma_f32_16x16x32_f16 v[106:109], v[148:151], v[180:183], v[106:109]
	v_mfma_f32_16x16x32_f16 v[110:113], v[156:159], v[180:183], v[110:113]
	v_mfma_f32_16x16x32_f16 v[98:101], v[148:151], v[188:191], v[98:101]
	v_mfma_f32_16x16x32_f16 v[102:105], v[156:159], v[188:191], v[102:105]
	s_barrier
	s_mov_b32 m0, s29
	v_lshl_add_u64 v[208:209], v[208:209], 0, s[86:87]
	ds_read_b128 v[192:195], v219
	ds_read_b128 v[196:199], v219 offset:1024
	ds_read_b128 v[200:203], v219 offset:2048
	ds_read_b128 v[204:207], v219 offset:3072
	global_load_lds_dwordx4 v[208:209], off
	s_mov_b32 m0, s30
	v_lshl_add_u64 v[208:209], v[210:211], 0, s[86:87]
	global_load_lds_dwordx4 v[208:209], off
	s_barrier
; #define G_STAGE(bufoff, gbase, v0, v1) do { \
;     __builtin_amdgcn_global_load_lds((const unsigned*)((const char*)(gbase) + (v0)), (LAS unsigned*)(lds + (bufoff) + ldsw), 16, 0, 0); \
;     __builtin_amdgcn_global_load_lds((const unsigned*)((const char*)(gbase) + (v1)), (LAS unsigned*)(lds + (bufoff) + ldsw + 8192), 16, 0, 0); } while (0)
; #define G_LDA(dst, b, h) do { _Pragma("unroll") for (int m = 0; m < 4; ++m) _Pragma("unroll") for (int k = 0; k < 2; ++k) dst[m][k] = *(const LAS h8*)(lds + G_SA(b, h) + aoff + m * 2048 + k * 1024); } while (0)
; #define G_LDB(dst, b, h) do { _Pragma("unroll") for (int n = 0; n < 2; ++n) _Pragma("unroll") for (int k = 0; k < 2; ++k) dst[n][k] = *(const LAS h8*)(lds + G_SB(b, h) + boff + n * 2048 + k * 1024); } while (0)
; #define G_MMA(ai, bj, At, Bt) do { __builtin_amdgcn_s_setprio(1); _Pragma("unroll") for (int m = 0; m < 4; ++m) _Pragma("unroll") for (int n = 0; n < 2; ++n) _Pragma("unroll") for (int k = 0; k < 2; ++k) \
;     acc[ai][bj][m][n] = __builtin_amdgcn_mfma_f32_16x16x32_f16(Bt[n][k], At[m][k], acc[ai][bj][m][n], 0, 0, 0); __builtin_amdgcn_s_setprio(0); } while (0)
; #define G_WAIT_V(n) asm volatile("s_waitcnt vmcnt(" #n ")" ::: "memory")
; #define G_WAIT_L(n) asm volatile("s_waitcnt lgkmcnt(" #n ")" ::: "memory")
; #define G_BAR __builtin_amdgcn_s_barrier()
; #define G_SCHED __builtin_amdgcn_sched_barrier(0)
; template <bool PERM, class Sched, class Epi>
; DI void gemm256(LAS unsigned char* lds, const Sched& S, const Epi& E, int wv_) {
;     ...
;       G_LDB(B1, 1, 1); G_STAGE(G_SB(1, 0), b3, cvB0, cvB1);
;       G_BAR; G_WAIT_L(0); G_MMA(0, 1, At, B1); G_BAR;
;       G_LDA(At, 1, 1); G_STAGE(G_SA(1, 0), a3, cvA0, cvA1);
;       G_BAR; G_WAIT_L(0); G_MMA(1, 0, At, B0); G_BAR; G_SCHED;
;       G_STAGE(G_SB(1, 1), b3 + chB, cvB0, cvB1);
;       G_WAIT_V(6); G_BAR; G_MMA(1, 1, At, B1); G_BAR;
;     }
	s_waitcnt lgkmcnt(0)
	s_waitcnt lgkmcnt(0)
	v_mfma_f32_16x16x32_f16 v[58:61], v[192:195], v[160:163], v[58:61]
	v_mfma_f32_16x16x32_f16 v[62:65], v[200:203], v[160:163], v[62:65]
	v_mfma_f32_16x16x32_f16 v[50:53], v[192:195], v[168:171], v[50:53]
	v_mfma_f32_16x16x32_f16 v[54:57], v[200:203], v[168:171], v[54:57]
	v_mfma_f32_16x16x32_f16 v[42:45], v[192:195], v[176:179], v[42:45]
	v_mfma_f32_16x16x32_f16 v[46:49], v[200:203], v[176:179], v[46:49]
	v_mfma_f32_16x16x32_f16 v[34:37], v[192:195], v[184:187], v[34:37]
	v_mfma_f32_16x16x32_f16 v[38:41], v[200:203], v[184:187], v[38:41]
	v_mfma_f32_16x16x32_f16 v[58:61], v[196:199], v[164:167], v[58:61]
	v_mfma_f32_16x16x32_f16 v[62:65], v[204:207], v[164:167], v[62:65]
	v_mfma_f32_16x16x32_f16 v[50:53], v[196:199], v[172:175], v[50:53]
	v_mfma_f32_16x16x32_f16 v[54:57], v[204:207], v[172:175], v[54:57]
	v_mfma_f32_16x16x32_f16 v[42:45], v[196:199], v[180:183], v[42:45]
	v_mfma_f32_16x16x32_f16 v[46:49], v[204:207], v[180:183], v[46:49]
	v_mfma_f32_16x16x32_f16 v[34:37], v[196:199], v[188:191], v[34:37]
	v_mfma_f32_16x16x32_f16 v[38:41], v[204:207], v[188:191], v[38:41]
	s_mov_b32 m0, s31
	v_lshl_add_u64 v[208:209], v[212:213], 0, s[86:87]
	s_barrier
	ds_read_b128 v[160:163], v1 offset:49152
	ds_read_b128 v[164:167], v1 offset:50176
	ds_read_b128 v[168:171], v1 offset:51200
	ds_read_b128 v[172:175], v1 offset:52224
	ds_read_b128 v[176:179], v1 offset:53248
	ds_read_b128 v[180:183], v1 offset:54272
	ds_read_b128 v[184:187], v1 offset:55296
	ds_read_b128 v[188:191], v1 offset:56320
	global_load_lds_dwordx4 v[208:209], off
	s_mov_b32 m0, s34
	v_lshl_add_u64 v[208:209], v[214:215], 0, s[86:87]
	global_load_lds_dwordx4 v[208:209], off
	s_barrier
	s_waitcnt lgkmcnt(0)
	s_waitcnt lgkmcnt(0)
	v_mfma_f32_16x16x32_f16 v[90:93], v[144:147], v[160:163], v[90:93]
	v_mfma_f32_16x16x32_f16 v[94:97], v[152:155], v[160:163], v[94:97]
	v_mfma_f32_16x16x32_f16 v[82:85], v[144:147], v[168:171], v[82:85]
	v_mfma_f32_16x16x32_f16 v[86:89], v[152:155], v[168:171], v[86:89]
	v_mfma_f32_16x16x32_f16 v[74:77], v[144:147], v[176:179], v[74:77]
	v_mfma_f32_16x16x32_f16 v[78:81], v[152:155], v[176:179], v[78:81]
	v_mfma_f32_16x16x32_f16 v[66:69], v[144:147], v[184:187], v[66:69]
	v_mfma_f32_16x16x32_f16 v[70:73], v[152:155], v[184:187], v[70:73]
	v_mfma_f32_16x16x32_f16 v[90:93], v[148:151], v[164:167], v[90:93]
	v_mfma_f32_16x16x32_f16 v[94:97], v[156:159], v[164:167], v[94:97]
	v_mfma_f32_16x16x32_f16 v[82:85], v[148:151], v[172:175], v[82:85]
	v_mfma_f32_16x16x32_f16 v[86:89], v[156:159], v[172:175], v[86:89]
	v_mfma_f32_16x16x32_f16 v[74:77], v[148:151], v[180:183], v[74:77]
	v_mfma_f32_16x16x32_f16 v[78:81], v[156:159], v[180:183], v[78:81]
	v_mfma_f32_16x16x32_f16 v[66:69], v[148:151], v[188:191], v[66:69]
	v_mfma_f32_16x16x32_f16 v[70:73], v[156:159], v[188:191], v[70:73]
	s_barrier
	s_add_u32 s12, s12, 0x10080
	s_addc_u32 s13, s13, 0
	s_mov_b32 m0, s35
	v_lshl_add_u64 v[144:145], s[12:13], 0, v[132:133]
	global_load_lds_dwordx4 v[144:145], off
	s_mov_b32 m0, s37
	v_lshl_add_u64 v[144:145], s[12:13], 0, v[136:137]
	global_load_lds_dwordx4 v[144:145], off
	s_waitcnt vmcnt(6)
	s_barrier
	v_mfma_f32_16x16x32_f16 v[26:29], v[192:195], v[160:163], v[26:29]
	v_mfma_f32_16x16x32_f16 v[30:33], v[200:203], v[160:163], v[30:33]
	v_mfma_f32_16x16x32_f16 v[18:21], v[192:195], v[168:171], v[18:21]
	v_mfma_f32_16x16x32_f16 v[22:25], v[200:203], v[168:171], v[22:25]
	v_mfma_f32_16x16x32_f16 v[10:13], v[192:195], v[176:179], v[10:13]
	v_mfma_f32_16x16x32_f16 v[14:17], v[200:203], v[176:179], v[14:17]
	v_mfma_f32_16x16x32_f16 v[6:9], v[192:195], v[184:187], v[6:9]
	v_mfma_f32_16x16x32_f16 v[2:5], v[200:203], v[184:187], v[2:5]
	v_mfma_f32_16x16x32_f16 v[26:29], v[196:199], v[164:167], v[26:29]
	v_mfma_f32_16x16x32_f16 v[30:33], v[204:207], v[164:167], v[30:33]
	v_mfma_f32_16x16x32_f16 v[18:21], v[196:199], v[172:175], v[18:21]
	v_mfma_f32_16x16x32_f16 v[22:25], v[204:207], v[172:175], v[22:25]
	v_mfma_f32_16x16x32_f16 v[10:13], v[196:199], v[180:183], v[10:13]
	v_mfma_f32_16x16x32_f16 v[14:17], v[204:207], v[180:183], v[14:17]
	v_mfma_f32_16x16x32_f16 v[6:9], v[196:199], v[188:191], v[6:9]
	v_mfma_f32_16x16x32_f16 v[2:5], v[204:207], v[188:191], v[2:5]
	s_add_u32 s10, s10, 0x100
	s_addc_u32 s11, s11, 0
	s_add_u32 s75, s75, 0x100
	s_addc_u32 s46, s46, 0
	s_cmp_ge_i32 s74, s79
	s_mov_b32 s12, s74
	s_barrier
	s_cbranch_scc0 .LBB0_1718
	s_mov_b32 s93, 0x23fff
	s_movk_i32 s85, 0x800
	s_branch .LBB0_1721

; #define G_STAGE(bufoff, gbase, v0, v1) do { \
;     __builtin_amdgcn_global_load_lds((const unsigned*)((const char*)(gbase) + (v0)), (LAS unsigned*)(lds + (bufoff) + ldsw), 16, 0, 0); \
;     __builtin_amdgcn_global_load_lds((const unsigned*)((const char*)(gbase) + (v1)), (LAS unsigned*)(lds + (bufoff) + ldsw + 8192), 16, 0, 0); } while (0)
; #define G_LDA(dst, b, h) do { _Pragma("unroll") for (int m = 0; m < 4; ++m) _Pragma("unroll") for (int k = 0; k < 2; ++k) dst[m][k] = *(const LAS h8*)(lds + G_SA(b, h) + aoff + m * 2048 + k * 1024); } while (0)
; #define G_LDB(dst, b, h) do { _Pragma("unroll") for (int n = 0; n < 2; ++n) _Pragma("unroll") for (int k = 0; k < 2; ++k) dst[n][k] = *(const LAS h8*)(lds + G_SB(b, h) + boff + n * 2048 + k * 1024); } while (0)
; #define G_MMA(ai, bj, At, Bt) do { __builtin_amdgcn_s_setprio(1); _Pragma("unroll") for (int m = 0; m < 4; ++m) _Pragma("unroll") for (int n = 0; n < 2; ++n) _Pragma("unroll") for (int k = 0; k < 2; ++k) \
;     acc[ai][bj][m][n] = __builtin_amdgcn_mfma_f32_16x16x32_f16(Bt[n][k], At[m][k], acc[ai][bj][m][n], 0, 0, 0); __builtin_amdgcn_s_setprio(0); } while (0)
; #define G_WAIT_L(n) asm volatile("s_waitcnt lgkmcnt(" #n ")" ::: "memory")
; #define G_BAR __builtin_amdgcn_s_barrier()
; #define G_SCHED __builtin_amdgcn_sched_barrier(0)
; template <bool PERM, class Sched, class Epi>
; DI void gemm256(LAS unsigned char* lds, const Sched& S, const Epi& E, int wv_) {
;     ...
;       const bool last = (t == nt - 2);
;       const char* a1 = cA + (size_t)(t + 1) * kstep;
;       const char* a2 = last ? nA : cA + (size_t)(t + 2) * kstep;
;       const char* b2 = last ? nB : cB + (size_t)(t + 2) * kstep;
;       const char* a3 = a2 + kstep;
;       const char* b3 = b2 + kstep;
;       G_LDB(B0, 0, 0); G_SCHED; G_LDA(At, 0, 0); G_STAGE(G_SA(1, 1), a1 + chA, cvA0, cvA1);
;       G_WAIT_L(8); G_BAR; G_WAIT_L(0); G_MMA(0, 0, At, B0); G_BAR; G_SCHED;
;       G_LDB(B1, 0, 1); G_STAGE(G_SB(0, 0), b2, cvB0, cvB1);
;       G_BAR; G_WAIT_L(0); G_MMA(0, 1, At, B1); G_BAR;
;       G_LDA(At, 0, 1); G_STAGE(G_SA(0, 0), a2, cvA0, cvA1);
;       G_BAR; G_WAIT_L(0); G_MMA(1, 0, At, B0); G_BAR; G_SCHED;
.LBB0_1748:
	s_add_i32 s60, s12, 2
	s_add_u32 s10, s8, 0x100
	s_addc_u32 s11, s9, 0
	s_add_u32 s13, s58, s8
	ds_read_b128 v[144:147], v216
	ds_read_b128 v[148:151], v216 offset:1024
	ds_read_b128 v[152:155], v216 offset:2048
	ds_read_b128 v[156:159], v216 offset:3072
	v_lshl_add_u64 v[192:193], v[138:139], 0, s[8:9]
	s_add_i32 m0, s17, 0xc000
	ds_read_b128 v[160:163], v1
	ds_read_b128 v[164:167], v1 offset:1024
	ds_read_b128 v[168:171], v1 offset:2048
	ds_read_b128 v[172:175], v1 offset:3072
	ds_read_b128 v[176:179], v1 offset:4096
	ds_read_b128 v[180:183], v1 offset:5120
	ds_read_b128 v[184:187], v1 offset:6144
	ds_read_b128 v[188:191], v1 offset:7168
	global_load_lds_dwordx4 v[192:193], off
	s_add_i32 m0, s17, 0xe000
	v_lshl_add_u64 v[192:193], v[140:141], 0, s[8:9]
	global_load_lds_dwordx4 v[192:193], off
	s_waitcnt lgkmcnt(8)
	s_barrier
	s_waitcnt lgkmcnt(0)
	s_waitcnt lgkmcnt(0)
	v_mfma_f32_16x16x32_f16 v[122:125], v[144:147], v[160:163], v[122:125]
	s_addc_u32 s14, s59, s9
	s_cmp_eq_u32 s56, s12
	s_cselect_b32 s40, 0, s10
	s_cselect_b32 s15, 0, s11
	s_cselect_b32 s12, s4, s13
	s_cselect_b32 s13, s5, s14
	s_add_u32 s14, s2, s40
	s_addc_u32 s15, s3, s15
	v_mfma_f32_16x16x32_f16 v[126:129], v[152:155], v[160:163], v[126:129]
	v_mfma_f32_16x16x32_f16 v[106:109], v[144:147], v[168:171], v[106:109]
	v_mfma_f32_16x16x32_f16 v[110:113], v[152:155], v[168:171], v[110:113]
	v_mfma_f32_16x16x32_f16 v[90:93], v[144:147], v[176:179], v[90:93]
	v_mfma_f32_16x16x32_f16 v[94:97], v[152:155], v[176:179], v[94:97]
	v_mfma_f32_16x16x32_f16 v[74:77], v[144:147], v[184:187], v[74:77]
	v_mfma_f32_16x16x32_f16 v[78:81], v[152:155], v[184:187], v[78:81]
	v_mfma_f32_16x16x32_f16 v[122:125], v[148:151], v[164:167], v[122:125]
	v_mfma_f32_16x16x32_f16 v[126:129], v[156:159], v[164:167], v[126:129]
	v_mfma_f32_16x16x32_f16 v[106:109], v[148:151], v[172:175], v[106:109]
	v_mfma_f32_16x16x32_f16 v[110:113], v[156:159], v[172:175], v[110:113]
	v_mfma_f32_16x16x32_f16 v[90:93], v[148:151], v[180:183], v[90:93]
	v_mfma_f32_16x16x32_f16 v[94:97], v[156:159], v[180:183], v[94:97]
	v_mfma_f32_16x16x32_f16 v[74:77], v[148:151], v[188:191], v[74:77]
	v_mfma_f32_16x16x32_f16 v[78:81], v[156:159], v[188:191], v[78:81]
	s_barrier
	s_mov_b32 m0, s18
	v_lshl_add_u64 v[208:209], s[12:13], 0, v[134:135]
	ds_read_b128 v[192:195], v217
	ds_read_b128 v[196:199], v217 offset:1024
	ds_read_b128 v[200:203], v217 offset:2048
	ds_read_b128 v[204:207], v217 offset:3072
	global_load_lds_dwordx4 v[208:209], off
	s_mov_b32 m0, s19
	v_lshl_add_u64 v[210:211], s[12:13], 0, v[130:131]
	global_load_lds_dwordx4 v[210:211], off
	s_barrier
	s_waitcnt lgkmcnt(0)
	s_waitcnt lgkmcnt(0)
	v_mfma_f32_16x16x32_f16 v[114:117], v[192:195], v[160:163], v[114:117]
	v_mfma_f32_16x16x32_f16 v[118:121], v[200:203], v[160:163], v[118:121]
	v_mfma_f32_16x16x32_f16 v[98:101], v[192:195], v[168:171], v[98:101]
	v_mfma_f32_16x16x32_f16 v[102:105], v[200:203], v[168:171], v[102:105]
	v_mfma_f32_16x16x32_f16 v[82:85], v[192:195], v[176:179], v[82:85]
	v_mfma_f32_16x16x32_f16 v[86:89], v[200:203], v[176:179], v[86:89]
	v_mfma_f32_16x16x32_f16 v[66:69], v[192:195], v[184:187], v[66:69]
	v_mfma_f32_16x16x32_f16 v[70:73], v[200:203], v[184:187], v[70:73]
	v_mfma_f32_16x16x32_f16 v[114:117], v[196:199], v[164:167], v[114:117]
	v_mfma_f32_16x16x32_f16 v[118:121], v[204:207], v[164:167], v[118:121]
	v_mfma_f32_16x16x32_f16 v[98:101], v[196:199], v[172:175], v[98:101]
	v_mfma_f32_16x16x32_f16 v[102:105], v[204:207], v[172:175], v[102:105]
	v_mfma_f32_16x16x32_f16 v[82:85], v[196:199], v[180:183], v[82:85]
	v_mfma_f32_16x16x32_f16 v[86:89], v[204:207], v[180:183], v[86:89]
	v_mfma_f32_16x16x32_f16 v[66:69], v[196:199], v[188:191], v[66:69]
	v_mfma_f32_16x16x32_f16 v[70:73], v[204:207], v[188:191], v[70:73]
	s_mov_b32 m0, s17
	v_lshl_add_u64 v[212:213], s[14:15], 0, v[136:137]
	s_barrier
	ds_read_b128 v[160:163], v1 offset:16384
	ds_read_b128 v[164:167], v1 offset:17408
	ds_read_b128 v[168:171], v1 offset:18432
	ds_read_b128 v[172:175], v1 offset:19456
	ds_read_b128 v[176:179], v1 offset:20480
	ds_read_b128 v[180:183], v1 offset:21504
	ds_read_b128 v[184:187], v1 offset:22528
	ds_read_b128 v[188:191], v1 offset:23552
	global_load_lds_dwordx4 v[212:213], off
	s_mov_b32 m0, s20
	v_lshl_add_u64 v[214:215], s[14:15], 0, v[132:133]
	global_load_lds_dwordx4 v[214:215], off
	s_barrier
	s_waitcnt lgkmcnt(0)
	s_waitcnt lgkmcnt(0)
	v_mfma_f32_16x16x32_f16 v[58:61], v[144:147], v[160:163], v[58:61]
	v_mfma_f32_16x16x32_f16 v[62:65], v[152:155], v[160:163], v[62:65]
	v_mfma_f32_16x16x32_f16 v[42:45], v[144:147], v[168:171], v[42:45]
	v_mfma_f32_16x16x32_f16 v[46:49], v[152:155], v[168:171], v[46:49]
	v_mfma_f32_16x16x32_f16 v[26:29], v[144:147], v[176:179], v[26:29]
	v_mfma_f32_16x16x32_f16 v[30:33], v[152:155], v[176:179], v[30:33]
	v_mfma_f32_16x16x32_f16 v[10:13], v[144:147], v[184:187], v[10:13]
	v_mfma_f32_16x16x32_f16 v[14:17], v[152:155], v[184:187], v[14:17]
	v_mfma_f32_16x16x32_f16 v[58:61], v[148:151], v[164:167], v[58:61]
	v_mfma_f32_16x16x32_f16 v[62:65], v[156:159], v[164:167], v[62:65]
	v_mfma_f32_16x16x32_f16 v[42:45], v[148:151], v[172:175], v[42:45]
	v_mfma_f32_16x16x32_f16 v[46:49], v[156:159], v[172:175], v[46:49]
	v_mfma_f32_16x16x32_f16 v[26:29], v[148:151], v[180:183], v[26:29]
	v_mfma_f32_16x16x32_f16 v[30:33], v[156:159], v[180:183], v[30:33]
	v_mfma_f32_16x16x32_f16 v[10:13], v[148:151], v[188:191], v[10:13]
	v_mfma_f32_16x16x32_f16 v[14:17], v[156:159], v[188:191], v[14:17]
	s_barrier
; #define G_STAGE(bufoff, gbase, v0, v1) do { \
;     __builtin_amdgcn_global_load_lds((const unsigned*)((const char*)(gbase) + (v0)), (LAS unsigned*)(lds + (bufoff) + ldsw), 16, 0, 0); \
;     __builtin_amdgcn_global_load_lds((const unsigned*)((const char*)(gbase) + (v1)), (LAS unsigned*)(lds + (bufoff) + ldsw + 8192), 16, 0, 0); } while (0)
; #define G_LDA(dst, b, h) do { _Pragma("unroll") for (int m = 0; m < 4; ++m) _Pragma("unroll") for (int k = 0; k < 2; ++k) dst[m][k] = *(const LAS h8*)(lds + G_SA(b, h) + aoff + m * 2048 + k * 1024); } while (0)
; #define G_LDB(dst, b, h) do { _Pragma("unroll") for (int n = 0; n < 2; ++n) _Pragma("unroll") for (int k = 0; k < 2; ++k) dst[n][k] = *(const LAS h8*)(lds + G_SB(b, h) + boff + n * 2048 + k * 1024); } while (0)
; #define G_MMA(ai, bj, At, Bt) do { __builtin_amdgcn_s_setprio(1); _Pragma("unroll") for (int m = 0; m < 4; ++m) _Pragma("unroll") for (int n = 0; n < 2; ++n) _Pragma("unroll") for (int k = 0; k < 2; ++k) \
;     acc[ai][bj][m][n] = __builtin_amdgcn_mfma_f32_16x16x32_f16(Bt[n][k], At[m][k], acc[ai][bj][m][n], 0, 0, 0); __builtin_amdgcn_s_setprio(0); } while (0)
; #define G_WAIT_V(n) asm volatile("s_waitcnt vmcnt(" #n ")" ::: "memory")
; #define G_WAIT_L(n) asm volatile("s_waitcnt lgkmcnt(" #n ")" ::: "memory")
; #define G_BAR __builtin_amdgcn_s_barrier()
; #define G_SCHED __builtin_amdgcn_sched_barrier(0)
; template <bool PERM, class Sched, class Epi>
; DI void gemm256(LAS unsigned char* lds, const Sched& S, const Epi& E, int wv_) {
;     ...
;       G_STAGE(G_SB(0, 1), b2 + chB, cvB0, cvB1);
;       G_WAIT_V(6); G_BAR; G_MMA(1, 1, At, B1); G_BAR;
;       G_LDB(B0, 1, 0); G_SCHED; G_LDA(At, 1, 0); G_STAGE(G_SA(0, 1), a2 + chA, cvA0, cvA1);
;       G_WAIT_L(8); G_BAR; G_WAIT_L(0); G_MMA(0, 0, At, B0); G_BAR; G_SCHED;
;       G_LDB(B1, 1, 1); G_STAGE(G_SB(1, 0), b3, cvB0, cvB1);
	s_add_u32 s8, s12, 0x16000
	s_addc_u32 s9, s13, 0
	s_mov_b32 m0, s21
	v_lshl_add_u64 v[144:145], s[8:9], 0, v[134:135]
	global_load_lds_dwordx4 v[144:145], off
	s_mov_b32 m0, s22
	v_lshl_add_u64 v[144:145], s[8:9], 0, v[130:131]
	global_load_lds_dwordx4 v[144:145], off
	s_waitcnt vmcnt(6)
	s_barrier
	v_mfma_f32_16x16x32_f16 v[50:53], v[192:195], v[160:163], v[50:53]
	v_mfma_f32_16x16x32_f16 v[54:57], v[200:203], v[160:163], v[54:57]
	v_mfma_f32_16x16x32_f16 v[34:37], v[192:195], v[168:171], v[34:37]
	v_mfma_f32_16x16x32_f16 v[38:41], v[200:203], v[168:171], v[38:41]
	v_mfma_f32_16x16x32_f16 v[18:21], v[192:195], v[176:179], v[18:21]
	v_mfma_f32_16x16x32_f16 v[22:25], v[200:203], v[176:179], v[22:25]
	v_mfma_f32_16x16x32_f16 v[6:9], v[192:195], v[184:187], v[6:9]
	v_mfma_f32_16x16x32_f16 v[2:5], v[200:203], v[184:187], v[2:5]
	v_mfma_f32_16x16x32_f16 v[50:53], v[196:199], v[164:167], v[50:53]
	v_mfma_f32_16x16x32_f16 v[54:57], v[204:207], v[164:167], v[54:57]
	v_mfma_f32_16x16x32_f16 v[34:37], v[196:199], v[172:175], v[34:37]
	v_mfma_f32_16x16x32_f16 v[38:41], v[204:207], v[172:175], v[38:41]
	v_mfma_f32_16x16x32_f16 v[18:21], v[196:199], v[180:183], v[18:21]
	v_mfma_f32_16x16x32_f16 v[22:25], v[204:207], v[180:183], v[22:25]
	v_mfma_f32_16x16x32_f16 v[6:9], v[196:199], v[188:191], v[6:9]
	v_mfma_f32_16x16x32_f16 v[2:5], v[204:207], v[188:191], v[2:5]
	s_barrier
	ds_read_b128 v[144:147], v218
	ds_read_b128 v[148:151], v218 offset:1024
	ds_read_b128 v[152:155], v218 offset:2048
	ds_read_b128 v[156:159], v218 offset:3072
	s_add_u32 s8, s14, 0x10000
	s_addc_u32 s9, s15, 0
	s_mov_b32 m0, s23
	v_lshl_add_u64 v[192:193], s[8:9], 0, v[136:137]
	ds_read_b128 v[160:163], v1 offset:32768
	ds_read_b128 v[164:167], v1 offset:33792
	ds_read_b128 v[168:171], v1 offset:34816
	ds_read_b128 v[172:175], v1 offset:35840
	ds_read_b128 v[176:179], v1 offset:36864
	ds_read_b128 v[180:183], v1 offset:37888
	ds_read_b128 v[184:187], v1 offset:38912
	ds_read_b128 v[188:191], v1 offset:39936
	global_load_lds_dwordx4 v[192:193], off
	s_mov_b32 m0, s24
	v_lshl_add_u64 v[192:193], s[8:9], 0, v[132:133]
	global_load_lds_dwordx4 v[192:193], off
	s_waitcnt lgkmcnt(8)
	s_barrier
	s_waitcnt lgkmcnt(0)
	s_waitcnt lgkmcnt(0)
	v_mfma_f32_16x16x32_f16 v[122:125], v[144:147], v[160:163], v[122:125]
	v_mfma_f32_16x16x32_f16 v[126:129], v[152:155], v[160:163], v[126:129]
	v_mfma_f32_16x16x32_f16 v[106:109], v[144:147], v[168:171], v[106:109]
	v_mfma_f32_16x16x32_f16 v[110:113], v[152:155], v[168:171], v[110:113]
	v_mfma_f32_16x16x32_f16 v[90:93], v[144:147], v[176:179], v[90:93]
	v_mfma_f32_16x16x32_f16 v[94:97], v[152:155], v[176:179], v[94:97]
	v_mfma_f32_16x16x32_f16 v[74:77], v[144:147], v[184:187], v[74:77]
	v_mfma_f32_16x16x32_f16 v[78:81], v[152:155], v[184:187], v[78:81]
	v_mfma_f32_16x16x32_f16 v[122:125], v[148:151], v[164:167], v[122:125]
	v_mfma_f32_16x16x32_f16 v[126:129], v[156:159], v[164:167], v[126:129]
	v_mfma_f32_16x16x32_f16 v[106:109], v[148:151], v[172:175], v[106:109]
	v_mfma_f32_16x16x32_f16 v[110:113], v[156:159], v[172:175], v[110:113]
	v_mfma_f32_16x16x32_f16 v[90:93], v[148:151], v[180:183], v[90:93]
	v_mfma_f32_16x16x32_f16 v[94:97], v[156:159], v[180:183], v[94:97]
	v_mfma_f32_16x16x32_f16 v[74:77], v[148:151], v[188:191], v[74:77]
	v_mfma_f32_16x16x32_f16 v[78:81], v[156:159], v[188:191], v[78:81]
	s_barrier
	s_mov_b32 m0, s25
	v_lshl_add_u64 v[208:209], v[208:209], 0, s[86:87]
	ds_read_b128 v[192:195], v219
	ds_read_b128 v[196:199], v219 offset:1024
	ds_read_b128 v[200:203], v219 offset:2048
	ds_read_b128 v[204:207], v219 offset:3072
	global_load_lds_dwordx4 v[208:209], off
	s_mov_b32 m0, s26
	v_lshl_add_u64 v[208:209], v[210:211], 0, s[86:87]
	global_load_lds_dwordx4 v[208:209], off
	s_barrier
; #define G_STAGE(bufoff, gbase, v0, v1) do { \
;     __builtin_amdgcn_global_load_lds((const unsigned*)((const char*)(gbase) + (v0)), (LAS unsigned*)(lds + (bufoff) + ldsw), 16, 0, 0); \
;     __builtin_amdgcn_global_load_lds((const unsigned*)((const char*)(gbase) + (v1)), (LAS unsigned*)(lds + (bufoff) + ldsw + 8192), 16, 0, 0); } while (0)
; #define G_LDA(dst, b, h) do { _Pragma("unroll") for (int m = 0; m < 4; ++m) _Pragma("unroll") for (int k = 0; k < 2; ++k) dst[m][k] = *(const LAS h8*)(lds + G_SA(b, h) + aoff + m * 2048 + k * 1024); } while (0)
; #define G_MMA(ai, bj, At, Bt) do { __builtin_amdgcn_s_setprio(1); _Pragma("unroll") for (int m = 0; m < 4; ++m) _Pragma("unroll") for (int n = 0; n < 2; ++n) _Pragma("unroll") for (int k = 0; k < 2; ++k) \
;     acc[ai][bj][m][n] = __builtin_amdgcn_mfma_f32_16x16x32_f16(Bt[n][k], At[m][k], acc[ai][bj][m][n], 0, 0, 0); __builtin_amdgcn_s_setprio(0); } while (0)
; #define G_WAIT_V(n) asm volatile("s_waitcnt vmcnt(" #n ")" ::: "memory")
; #define G_WAIT_L(n) asm volatile("s_waitcnt lgkmcnt(" #n ")" ::: "memory")
; #define G_BAR __builtin_amdgcn_s_barrier()
; #define G_SCHED __builtin_amdgcn_sched_barrier(0)
; template <bool PERM, class Sched, class Epi>
; DI void gemm256(LAS unsigned char* lds, const Sched& S, const Epi& E, int wv_) {
;     ...
;       G_BAR; G_WAIT_L(0); G_MMA(0, 1, At, B1); G_BAR;
;       G_LDA(At, 1, 1); G_STAGE(G_SA(1, 0), a3, cvA0, cvA1);
;       G_BAR; G_WAIT_L(0); G_MMA(1, 0, At, B0); G_BAR; G_SCHED;
;       G_STAGE(G_SB(1, 1), b3 + chB, cvB0, cvB1);
;       G_WAIT_V(6); G_BAR; G_MMA(1, 1, At, B1); G_BAR;
;     }
	s_waitcnt lgkmcnt(0)
	s_waitcnt lgkmcnt(0)
	v_mfma_f32_16x16x32_f16 v[114:117], v[192:195], v[160:163], v[114:117]
	v_mfma_f32_16x16x32_f16 v[118:121], v[200:203], v[160:163], v[118:121]
	v_mfma_f32_16x16x32_f16 v[98:101], v[192:195], v[168:171], v[98:101]
	v_mfma_f32_16x16x32_f16 v[102:105], v[200:203], v[168:171], v[102:105]
	v_mfma_f32_16x16x32_f16 v[82:85], v[192:195], v[176:179], v[82:85]
	v_mfma_f32_16x16x32_f16 v[86:89], v[200:203], v[176:179], v[86:89]
	v_mfma_f32_16x16x32_f16 v[66:69], v[192:195], v[184:187], v[66:69]
	v_mfma_f32_16x16x32_f16 v[70:73], v[200:203], v[184:187], v[70:73]
	v_mfma_f32_16x16x32_f16 v[114:117], v[196:199], v[164:167], v[114:117]
	v_mfma_f32_16x16x32_f16 v[118:121], v[204:207], v[164:167], v[118:121]
	v_mfma_f32_16x16x32_f16 v[98:101], v[196:199], v[172:175], v[98:101]
	v_mfma_f32_16x16x32_f16 v[102:105], v[204:207], v[172:175], v[102:105]
	v_mfma_f32_16x16x32_f16 v[82:85], v[196:199], v[180:183], v[82:85]
	v_mfma_f32_16x16x32_f16 v[86:89], v[204:207], v[180:183], v[86:89]
	v_mfma_f32_16x16x32_f16 v[66:69], v[196:199], v[188:191], v[66:69]
	v_mfma_f32_16x16x32_f16 v[70:73], v[204:207], v[188:191], v[70:73]
	s_mov_b32 m0, s27
	v_lshl_add_u64 v[208:209], v[212:213], 0, s[86:87]
	s_barrier
	ds_read_b128 v[160:163], v1 offset:49152
	ds_read_b128 v[164:167], v1 offset:50176
	ds_read_b128 v[168:171], v1 offset:51200
	ds_read_b128 v[172:175], v1 offset:52224
	ds_read_b128 v[176:179], v1 offset:53248
	ds_read_b128 v[180:183], v1 offset:54272
	ds_read_b128 v[184:187], v1 offset:55296
	ds_read_b128 v[188:191], v1 offset:56320
	global_load_lds_dwordx4 v[208:209], off
	s_mov_b32 m0, s28
	v_lshl_add_u64 v[208:209], v[214:215], 0, s[86:87]
	global_load_lds_dwordx4 v[208:209], off
	s_barrier
	s_waitcnt lgkmcnt(0)
	s_waitcnt lgkmcnt(0)
	v_mfma_f32_16x16x32_f16 v[58:61], v[144:147], v[160:163], v[58:61]
	v_mfma_f32_16x16x32_f16 v[62:65], v[152:155], v[160:163], v[62:65]
	v_mfma_f32_16x16x32_f16 v[42:45], v[144:147], v[168:171], v[42:45]
	v_mfma_f32_16x16x32_f16 v[46:49], v[152:155], v[168:171], v[46:49]
	v_mfma_f32_16x16x32_f16 v[26:29], v[144:147], v[176:179], v[26:29]
	v_mfma_f32_16x16x32_f16 v[30:33], v[152:155], v[176:179], v[30:33]
	v_mfma_f32_16x16x32_f16 v[10:13], v[144:147], v[184:187], v[10:13]
	v_mfma_f32_16x16x32_f16 v[14:17], v[152:155], v[184:187], v[14:17]
	v_mfma_f32_16x16x32_f16 v[58:61], v[148:151], v[164:167], v[58:61]
	v_mfma_f32_16x16x32_f16 v[62:65], v[156:159], v[164:167], v[62:65]
	v_mfma_f32_16x16x32_f16 v[42:45], v[148:151], v[172:175], v[42:45]
	v_mfma_f32_16x16x32_f16 v[46:49], v[156:159], v[172:175], v[46:49]
	v_mfma_f32_16x16x32_f16 v[26:29], v[148:151], v[180:183], v[26:29]
	v_mfma_f32_16x16x32_f16 v[30:33], v[156:159], v[180:183], v[30:33]
	v_mfma_f32_16x16x32_f16 v[10:13], v[148:151], v[188:191], v[10:13]
	v_mfma_f32_16x16x32_f16 v[14:17], v[156:159], v[188:191], v[14:17]
	s_barrier
	s_add_u32 s8, s12, 0x16080
	s_addc_u32 s9, s13, 0
	s_mov_b32 m0, s29
	v_lshl_add_u64 v[144:145], s[8:9], 0, v[134:135]
	global_load_lds_dwordx4 v[144:145], off
	s_mov_b32 m0, s30
	v_lshl_add_u64 v[144:145], s[8:9], 0, v[130:131]
	global_load_lds_dwordx4 v[144:145], off
	s_waitcnt vmcnt(6)
	s_barrier
	v_mfma_f32_16x16x32_f16 v[50:53], v[192:195], v[160:163], v[50:53]
	v_mfma_f32_16x16x32_f16 v[54:57], v[200:203], v[160:163], v[54:57]
	v_mfma_f32_16x16x32_f16 v[34:37], v[192:195], v[168:171], v[34:37]
	v_mfma_f32_16x16x32_f16 v[38:41], v[200:203], v[168:171], v[38:41]
	v_mfma_f32_16x16x32_f16 v[18:21], v[192:195], v[176:179], v[18:21]
	v_mfma_f32_16x16x32_f16 v[22:25], v[200:203], v[176:179], v[22:25]
	v_mfma_f32_16x16x32_f16 v[6:9], v[192:195], v[184:187], v[6:9]
	v_mfma_f32_16x16x32_f16 v[2:5], v[200:203], v[184:187], v[2:5]
	v_mfma_f32_16x16x32_f16 v[50:53], v[196:199], v[164:167], v[50:53]
	v_mfma_f32_16x16x32_f16 v[54:57], v[204:207], v[164:167], v[54:57]
	v_mfma_f32_16x16x32_f16 v[34:37], v[196:199], v[172:175], v[34:37]
	v_mfma_f32_16x16x32_f16 v[38:41], v[204:207], v[172:175], v[38:41]
	v_mfma_f32_16x16x32_f16 v[18:21], v[196:199], v[180:183], v[18:21]
	v_mfma_f32_16x16x32_f16 v[22:25], v[204:207], v[180:183], v[22:25]
	v_mfma_f32_16x16x32_f16 v[6:9], v[196:199], v[188:191], v[6:9]
	v_mfma_f32_16x16x32_f16 v[2:5], v[204:207], v[188:191], v[2:5]
	s_cmp_ge_i32 s60, s46
	s_mov_b64 s[8:9], s[10:11]
	s_mov_b32 s12, s60
	s_barrier
	s_cbranch_scc0 .LBB0_1748
	s_branch .LBB0_1743

; #define G_STAGE(bufoff, gbase, v0, v1) do { \
;     __builtin_amdgcn_global_load_lds((const unsigned*)((const char*)(gbase) + (v0)), (LAS unsigned*)(lds + (bufoff) + ldsw), 16, 0, 0); \
;     __builtin_amdgcn_global_load_lds((const unsigned*)((const char*)(gbase) + (v1)), (LAS unsigned*)(lds + (bufoff) + ldsw + 8192), 16, 0, 0); } while (0)
; #define G_LDA(dst, b, h) do { _Pragma("unroll") for (int m = 0; m < 4; ++m) _Pragma("unroll") for (int k = 0; k < 2; ++k) dst[m][k] = *(const LAS h8*)(lds + G_SA(b, h) + aoff + m * 2048 + k * 1024); } while (0)
; #define G_LDB(dst, b, h) do { _Pragma("unroll") for (int n = 0; n < 2; ++n) _Pragma("unroll") for (int k = 0; k < 2; ++k) dst[n][k] = *(const LAS h8*)(lds + G_SB(b, h) + boff + n * 2048 + k * 1024); } while (0)
; #define G_MMA(ai, bj, At, Bt) do { __builtin_amdgcn_s_setprio(1); _Pragma("unroll") for (int m = 0; m < 4; ++m) _Pragma("unroll") for (int n = 0; n < 2; ++n) _Pragma("unroll") for (int k = 0; k < 2; ++k) \
;     acc[ai][bj][m][n] = __builtin_amdgcn_mfma_f32_16x16x32_f16(Bt[n][k], At[m][k], acc[ai][bj][m][n], 0, 0, 0); __builtin_amdgcn_s_setprio(0); } while (0)
; #define G_WAIT_V(n) asm volatile("s_waitcnt vmcnt(" #n ")" ::: "memory")
; #define G_WAIT_L(n) asm volatile("s_waitcnt lgkmcnt(" #n ")" ::: "memory")
; #define G_BAR __builtin_amdgcn_s_barrier()
; #define G_SCHED __builtin_amdgcn_sched_barrier(0)
; template <bool PERM, class Sched, class Epi>
; DI void gemm256(LAS unsigned char* lds, const Sched& S, const Epi& E, int wv_) {
;     ...
;       const bool last = (t == nt - 2);
;       const char* a1 = cA + (size_t)(t + 1) * kstep;
;       const char* a2 = last ? nA : cA + (size_t)(t + 2) * kstep;
;       const char* b2 = last ? nB : cB + (size_t)(t + 2) * kstep;
;       const char* a3 = a2 + kstep;
;       const char* b3 = b2 + kstep;
;       G_LDB(B0, 0, 0); G_SCHED; G_LDA(At, 0, 0); G_STAGE(G_SA(1, 1), a1 + chA, cvA0, cvA1);
;       G_WAIT_L(8); G_BAR; G_WAIT_L(0); G_MMA(0, 0, At, B0); G_BAR; G_SCHED;
;       G_LDB(B1, 0, 1); G_STAGE(G_SB(0, 0), b2, cvB0, cvB1);
;       G_BAR; G_WAIT_L(0); G_MMA(0, 1, At, B1); G_BAR;
;       G_LDA(At, 0, 1); G_STAGE(G_SA(0, 0), a2, cvA0, cvA1);
;       G_BAR; G_WAIT_L(0); G_MMA(1, 0, At, B0); G_BAR; G_SCHED;
;       G_STAGE(G_SB(0, 1), b2 + chB, cvB0, cvB1);
;       G_WAIT_V(6); G_BAR; G_MMA(1, 1, At, B1); G_BAR;
.LBB0_2281:
	ds_read_b128 v[148:151], v239
	ds_read_b128 v[152:155], v239 offset:1024
	s_add_i32 s85, s14, 2
	ds_read_b128 v[156:159], v239 offset:2048
	ds_read_b128 v[160:163], v239 offset:3072
	v_lshl_add_u64 v[144:145], s[12:13], 0, v[140:141]
	s_add_i32 m0, s20, 0xc000
	ds_read_b128 v[164:167], v1
	ds_read_b128 v[168:171], v1 offset:1024
	ds_read_b128 v[172:175], v1 offset:2048
	ds_read_b128 v[176:179], v1 offset:3072
	ds_read_b128 v[180:183], v1 offset:4096
	ds_read_b128 v[184:187], v1 offset:5120
	ds_read_b128 v[188:191], v1 offset:6144
	ds_read_b128 v[192:195], v1 offset:7168
	global_load_lds_dwordx4 v[144:145], off
	s_add_i32 m0, s20, 0xe000
	v_lshl_add_u64 v[144:145], s[12:13], 0, v[142:143]
	global_load_lds_dwordx4 v[144:145], off
	s_waitcnt lgkmcnt(8)
	s_barrier
	s_waitcnt lgkmcnt(0)
	s_waitcnt lgkmcnt(0)
	v_mfma_f32_16x16x32_f16 v[114:117], v[148:151], v[164:167], v[114:117]
	s_add_u32 s15, s12, 0xfffc0080
	s_addc_u32 s16, s13, -1
	s_cmp_eq_u32 s75, s14
	s_cselect_b32 s14, s8, s46
	s_cselect_b32 s17, s7, s16
	s_cselect_b32 s16, s6, s15
	s_cselect_b32 s15, s9, s74
	v_mfma_f32_16x16x32_f16 v[126:129], v[156:159], v[164:167], v[126:129]
	v_mfma_f32_16x16x32_f16 v[98:101], v[148:151], v[172:175], v[98:101]
	v_mfma_f32_16x16x32_f16 v[110:113], v[156:159], v[172:175], v[110:113]
	v_mfma_f32_16x16x32_f16 v[82:85], v[148:151], v[180:183], v[82:85]
	v_mfma_f32_16x16x32_f16 v[94:97], v[156:159], v[180:183], v[94:97]
	v_mfma_f32_16x16x32_f16 v[66:69], v[148:151], v[188:191], v[66:69]
	v_mfma_f32_16x16x32_f16 v[78:81], v[156:159], v[188:191], v[78:81]
	v_mfma_f32_16x16x32_f16 v[114:117], v[152:155], v[168:171], v[114:117]
	v_mfma_f32_16x16x32_f16 v[126:129], v[160:163], v[168:171], v[126:129]
	v_mfma_f32_16x16x32_f16 v[98:101], v[152:155], v[176:179], v[98:101]
	v_mfma_f32_16x16x32_f16 v[110:113], v[160:163], v[176:179], v[110:113]
	v_mfma_f32_16x16x32_f16 v[82:85], v[152:155], v[184:187], v[82:85]
	v_mfma_f32_16x16x32_f16 v[94:97], v[160:163], v[184:187], v[94:97]
	v_mfma_f32_16x16x32_f16 v[66:69], v[152:155], v[192:195], v[66:69]
	v_mfma_f32_16x16x32_f16 v[78:81], v[160:163], v[192:195], v[78:81]
	s_barrier
	ds_read_b128 v[196:199], v243
	ds_read_b128 v[200:203], v243 offset:1024
	s_mov_b32 m0, s11
	ds_read_b128 v[204:207], v243 offset:2048
	ds_read_b128 v[208:211], v243 offset:3072
	v_lshl_add_u64 v[144:145], s[14:15], 0, v[132:133]
	global_load_lds_dwordx4 v[144:145], off
	s_mov_b32 m0, s21
	v_lshl_add_u64 v[212:213], s[14:15], 0, v[136:137]
	global_load_lds_dwordx4 v[212:213], off
	s_barrier
	s_waitcnt lgkmcnt(0)
	s_waitcnt lgkmcnt(0)
	v_mfma_f32_16x16x32_f16 v[122:125], v[196:199], v[164:167], v[122:125]
	v_mfma_f32_16x16x32_f16 v[118:121], v[204:207], v[164:167], v[118:121]
	v_mfma_f32_16x16x32_f16 v[106:109], v[196:199], v[172:175], v[106:109]
	v_mfma_f32_16x16x32_f16 v[102:105], v[204:207], v[172:175], v[102:105]
	v_mfma_f32_16x16x32_f16 v[90:93], v[196:199], v[180:183], v[90:93]
	v_mfma_f32_16x16x32_f16 v[86:89], v[204:207], v[180:183], v[86:89]
	v_mfma_f32_16x16x32_f16 v[74:77], v[196:199], v[188:191], v[74:77]
	v_mfma_f32_16x16x32_f16 v[70:73], v[204:207], v[188:191], v[70:73]
	v_mfma_f32_16x16x32_f16 v[122:125], v[200:203], v[168:171], v[122:125]
	v_mfma_f32_16x16x32_f16 v[118:121], v[208:211], v[168:171], v[118:121]
	v_mfma_f32_16x16x32_f16 v[106:109], v[200:203], v[176:179], v[106:109]
	v_mfma_f32_16x16x32_f16 v[102:105], v[208:211], v[176:179], v[102:105]
	v_mfma_f32_16x16x32_f16 v[90:93], v[200:203], v[184:187], v[90:93]
	v_mfma_f32_16x16x32_f16 v[86:89], v[208:211], v[184:187], v[86:89]
	v_mfma_f32_16x16x32_f16 v[74:77], v[200:203], v[192:195], v[74:77]
	v_mfma_f32_16x16x32_f16 v[70:73], v[208:211], v[192:195], v[70:73]
	s_mov_b32 m0, s20
	v_lshl_add_u64 v[214:215], s[16:17], 0, v[130:131]
	s_barrier
	ds_read_b128 v[164:167], v1 offset:16384
	ds_read_b128 v[168:171], v1 offset:17408
	ds_read_b128 v[172:175], v1 offset:18432
	ds_read_b128 v[176:179], v1 offset:19456
	ds_read_b128 v[180:183], v1 offset:20480
	ds_read_b128 v[184:187], v1 offset:21504
	ds_read_b128 v[188:191], v1 offset:22528
	ds_read_b128 v[192:195], v1 offset:23552
	global_load_lds_dwordx4 v[214:215], off
	s_mov_b32 m0, s22
	v_lshl_add_u64 v[216:217], s[16:17], 0, v[134:135]
	global_load_lds_dwordx4 v[216:217], off
	s_barrier
	s_waitcnt lgkmcnt(0)
	s_waitcnt lgkmcnt(0)
	v_mfma_f32_16x16x32_f16 v[50:53], v[148:151], v[164:167], v[50:53]
	v_mfma_f32_16x16x32_f16 v[62:65], v[156:159], v[164:167], v[62:65]
	v_mfma_f32_16x16x32_f16 v[34:37], v[148:151], v[172:175], v[34:37]
	v_mfma_f32_16x16x32_f16 v[46:49], v[156:159], v[172:175], v[46:49]
	v_mfma_f32_16x16x32_f16 v[18:21], v[148:151], v[180:183], v[18:21]
	v_mfma_f32_16x16x32_f16 v[30:33], v[156:159], v[180:183], v[30:33]
	v_mfma_f32_16x16x32_f16 v[2:5], v[148:151], v[188:191], v[2:5]
	v_mfma_f32_16x16x32_f16 v[14:17], v[156:159], v[188:191], v[14:17]
	v_mfma_f32_16x16x32_f16 v[50:53], v[152:155], v[168:171], v[50:53]
	v_mfma_f32_16x16x32_f16 v[62:65], v[160:163], v[168:171], v[62:65]
	v_mfma_f32_16x16x32_f16 v[34:37], v[152:155], v[176:179], v[34:37]
	v_mfma_f32_16x16x32_f16 v[46:49], v[160:163], v[176:179], v[46:49]
	v_mfma_f32_16x16x32_f16 v[18:21], v[152:155], v[184:187], v[18:21]
	v_mfma_f32_16x16x32_f16 v[30:33], v[160:163], v[184:187], v[30:33]
	v_mfma_f32_16x16x32_f16 v[2:5], v[152:155], v[192:195], v[2:5]
	v_mfma_f32_16x16x32_f16 v[14:17], v[160:163], v[192:195], v[14:17]
	s_barrier
	s_add_u32 s40, s14, 0x400000
	s_addc_u32 s41, s15, 0
	s_mov_b32 m0, s23
	v_lshl_add_u64 v[148:149], s[40:41], 0, v[132:133]
	global_load_lds_dwordx4 v[148:149], off
	s_mov_b32 m0, s24
	v_lshl_add_u64 v[148:149], s[40:41], 0, v[136:137]
	global_load_lds_dwordx4 v[148:149], off
	s_waitcnt vmcnt(6)
	s_barrier
; #define G_STAGE(bufoff, gbase, v0, v1) do { \
;     __builtin_amdgcn_global_load_lds((const unsigned*)((const char*)(gbase) + (v0)), (LAS unsigned*)(lds + (bufoff) + ldsw), 16, 0, 0); \
;     __builtin_amdgcn_global_load_lds((const unsigned*)((const char*)(gbase) + (v1)), (LAS unsigned*)(lds + (bufoff) + ldsw + 8192), 16, 0, 0); } while (0)
; #define G_LDA(dst, b, h) do { _Pragma("unroll") for (int m = 0; m < 4; ++m) _Pragma("unroll") for (int k = 0; k < 2; ++k) dst[m][k] = *(const LAS h8*)(lds + G_SA(b, h) + aoff + m * 2048 + k * 1024); } while (0)
; #define G_LDB(dst, b, h) do { _Pragma("unroll") for (int n = 0; n < 2; ++n) _Pragma("unroll") for (int k = 0; k < 2; ++k) dst[n][k] = *(const LAS h8*)(lds + G_SB(b, h) + boff + n * 2048 + k * 1024); } while (0)
; #define G_MMA(ai, bj, At, Bt) do { __builtin_amdgcn_s_setprio(1); _Pragma("unroll") for (int m = 0; m < 4; ++m) _Pragma("unroll") for (int n = 0; n < 2; ++n) _Pragma("unroll") for (int k = 0; k < 2; ++k) \
;     acc[ai][bj][m][n] = __builtin_amdgcn_mfma_f32_16x16x32_f16(Bt[n][k], At[m][k], acc[ai][bj][m][n], 0, 0, 0); __builtin_amdgcn_s_setprio(0); } while (0)
; #define G_WAIT_V(n) asm volatile("s_waitcnt vmcnt(" #n ")" ::: "memory")
; #define G_WAIT_L(n) asm volatile("s_waitcnt lgkmcnt(" #n ")" ::: "memory")
; #define G_BAR __builtin_amdgcn_s_barrier()
; #define G_SCHED __builtin_amdgcn_sched_barrier(0)
; template <bool PERM, class Sched, class Epi>
; DI void gemm256(LAS unsigned char* lds, const Sched& S, const Epi& E, int wv_) {
;     ...
;       G_WAIT_V(6); G_BAR; G_MMA(1, 1, At, B1); G_BAR;
;       G_LDB(B0, 1, 0); G_SCHED; G_LDA(At, 1, 0); G_STAGE(G_SA(0, 1), a2 + chA, cvA0, cvA1);
;       G_WAIT_L(8); G_BAR; G_WAIT_L(0); G_MMA(0, 0, At, B0); G_BAR; G_SCHED;
;       G_LDB(B1, 1, 1); G_STAGE(G_SB(1, 0), b3, cvB0, cvB1);
	v_mfma_f32_16x16x32_f16 v[58:61], v[196:199], v[164:167], v[58:61]
	v_mfma_f32_16x16x32_f16 v[54:57], v[204:207], v[164:167], v[54:57]
	v_mfma_f32_16x16x32_f16 v[42:45], v[196:199], v[172:175], v[42:45]
	v_mfma_f32_16x16x32_f16 v[38:41], v[204:207], v[172:175], v[38:41]
	v_mfma_f32_16x16x32_f16 v[26:29], v[196:199], v[180:183], v[26:29]
	v_mfma_f32_16x16x32_f16 v[22:25], v[204:207], v[180:183], v[22:25]
	v_mfma_f32_16x16x32_f16 v[10:13], v[196:199], v[188:191], v[10:13]
	v_mfma_f32_16x16x32_f16 v[6:9], v[204:207], v[188:191], v[6:9]
	v_mfma_f32_16x16x32_f16 v[58:61], v[200:203], v[168:171], v[58:61]
	v_mfma_f32_16x16x32_f16 v[54:57], v[208:211], v[168:171], v[54:57]
	v_mfma_f32_16x16x32_f16 v[42:45], v[200:203], v[176:179], v[42:45]
	v_mfma_f32_16x16x32_f16 v[38:41], v[208:211], v[176:179], v[38:41]
	v_mfma_f32_16x16x32_f16 v[26:29], v[200:203], v[184:187], v[26:29]
	v_mfma_f32_16x16x32_f16 v[22:25], v[208:211], v[184:187], v[22:25]
	v_mfma_f32_16x16x32_f16 v[10:13], v[200:203], v[192:195], v[10:13]
	v_mfma_f32_16x16x32_f16 v[6:9], v[208:211], v[192:195], v[6:9]
	s_barrier
	ds_read_b128 v[148:151], v244
	ds_read_b128 v[152:155], v244 offset:1024
	ds_read_b128 v[156:159], v244 offset:2048
	ds_read_b128 v[160:163], v244 offset:3072
	s_add_u32 s16, s16, 0x40000
	s_addc_u32 s17, s17, 0
	s_mov_b32 m0, s25
	v_lshl_add_u64 v[196:197], s[16:17], 0, v[130:131]
	ds_read_b128 v[164:167], v1 offset:32768
	ds_read_b128 v[168:171], v1 offset:33792
	ds_read_b128 v[172:175], v1 offset:34816
	ds_read_b128 v[176:179], v1 offset:35840
	ds_read_b128 v[180:183], v1 offset:36864
	ds_read_b128 v[184:187], v1 offset:37888
	ds_read_b128 v[188:191], v1 offset:38912
	ds_read_b128 v[192:195], v1 offset:39936
	global_load_lds_dwordx4 v[196:197], off
	s_mov_b32 m0, s26
	v_lshl_add_u64 v[196:197], s[16:17], 0, v[134:135]
	global_load_lds_dwordx4 v[196:197], off
	s_waitcnt lgkmcnt(8)
	s_barrier
	s_waitcnt lgkmcnt(0)
	s_waitcnt lgkmcnt(0)
	v_mfma_f32_16x16x32_f16 v[114:117], v[148:151], v[164:167], v[114:117]
	v_mfma_f32_16x16x32_f16 v[126:129], v[156:159], v[164:167], v[126:129]
	v_mfma_f32_16x16x32_f16 v[98:101], v[148:151], v[172:175], v[98:101]
	v_mfma_f32_16x16x32_f16 v[110:113], v[156:159], v[172:175], v[110:113]
	v_mfma_f32_16x16x32_f16 v[82:85], v[148:151], v[180:183], v[82:85]
	v_mfma_f32_16x16x32_f16 v[94:97], v[156:159], v[180:183], v[94:97]
	v_mfma_f32_16x16x32_f16 v[66:69], v[148:151], v[188:191], v[66:69]
	v_mfma_f32_16x16x32_f16 v[78:81], v[156:159], v[188:191], v[78:81]
	v_mfma_f32_16x16x32_f16 v[114:117], v[152:155], v[168:171], v[114:117]
	v_mfma_f32_16x16x32_f16 v[126:129], v[160:163], v[168:171], v[126:129]
	v_mfma_f32_16x16x32_f16 v[98:101], v[152:155], v[176:179], v[98:101]
	v_mfma_f32_16x16x32_f16 v[110:113], v[160:163], v[176:179], v[110:113]
	v_mfma_f32_16x16x32_f16 v[82:85], v[152:155], v[184:187], v[82:85]
	v_mfma_f32_16x16x32_f16 v[94:97], v[160:163], v[184:187], v[94:97]
	v_mfma_f32_16x16x32_f16 v[66:69], v[152:155], v[192:195], v[66:69]
	v_mfma_f32_16x16x32_f16 v[78:81], v[160:163], v[192:195], v[78:81]
	s_barrier
	s_mov_b32 m0, s28
	ds_read_b128 v[196:199], v246
	ds_read_b128 v[200:203], v246 offset:1024
	v_lshl_add_u64 v[144:145], v[144:145], 0, s[86:87]
	ds_read_b128 v[204:207], v246 offset:2048
	ds_read_b128 v[208:211], v246 offset:3072
	global_load_lds_dwordx4 v[144:145], off
	s_mov_b32 m0, s29
	v_lshl_add_u64 v[144:145], v[212:213], 0, s[86:87]
	global_load_lds_dwordx4 v[144:145], off
	s_barrier
; #define G_STAGE(bufoff, gbase, v0, v1) do { \
;     __builtin_amdgcn_global_load_lds((const unsigned*)((const char*)(gbase) + (v0)), (LAS unsigned*)(lds + (bufoff) + ldsw), 16, 0, 0); \
;     __builtin_amdgcn_global_load_lds((const unsigned*)((const char*)(gbase) + (v1)), (LAS unsigned*)(lds + (bufoff) + ldsw + 8192), 16, 0, 0); } while (0)
; #define G_LDA(dst, b, h) do { _Pragma("unroll") for (int m = 0; m < 4; ++m) _Pragma("unroll") for (int k = 0; k < 2; ++k) dst[m][k] = *(const LAS h8*)(lds + G_SA(b, h) + aoff + m * 2048 + k * 1024); } while (0)
; #define G_LDB(dst, b, h) do { _Pragma("unroll") for (int n = 0; n < 2; ++n) _Pragma("unroll") for (int k = 0; k < 2; ++k) dst[n][k] = *(const LAS h8*)(lds + G_SB(b, h) + boff + n * 2048 + k * 1024); } while (0)
; #define G_MMA(ai, bj, At, Bt) do { __builtin_amdgcn_s_setprio(1); _Pragma("unroll") for (int m = 0; m < 4; ++m) _Pragma("unroll") for (int n = 0; n < 2; ++n) _Pragma("unroll") for (int k = 0; k < 2; ++k) \
;     acc[ai][bj][m][n] = __builtin_amdgcn_mfma_f32_16x16x32_f16(Bt[n][k], At[m][k], acc[ai][bj][m][n], 0, 0, 0); __builtin_amdgcn_s_setprio(0); } while (0)
; #define G_WAIT_V(n) asm volatile("s_waitcnt vmcnt(" #n ")" ::: "memory")
; #define G_WAIT_L(n) asm volatile("s_waitcnt lgkmcnt(" #n ")" ::: "memory")
; #define G_BAR __builtin_amdgcn_s_barrier()
; #define G_SCHED __builtin_amdgcn_sched_barrier(0)
; template <bool PERM, class Sched, class Epi>
; DI void gemm256(LAS unsigned char* lds, const Sched& S, const Epi& E, int wv_) {
;     ...
;       G_LDB(B1, 1, 1); G_STAGE(G_SB(1, 0), b3, cvB0, cvB1);
;       G_BAR; G_WAIT_L(0); G_MMA(0, 1, At, B1); G_BAR;
;       G_LDA(At, 1, 1); G_STAGE(G_SA(1, 0), a3, cvA0, cvA1);
;       G_BAR; G_WAIT_L(0); G_MMA(1, 0, At, B0); G_BAR; G_SCHED;
;       G_STAGE(G_SB(1, 1), b3 + chB, cvB0, cvB1);
;       G_WAIT_V(6); G_BAR; G_MMA(1, 1, At, B1); G_BAR;
;     }
	s_waitcnt lgkmcnt(0)
	s_waitcnt lgkmcnt(0)
	v_mfma_f32_16x16x32_f16 v[122:125], v[196:199], v[164:167], v[122:125]
	v_mfma_f32_16x16x32_f16 v[118:121], v[204:207], v[164:167], v[118:121]
	v_mfma_f32_16x16x32_f16 v[106:109], v[196:199], v[172:175], v[106:109]
	v_mfma_f32_16x16x32_f16 v[102:105], v[204:207], v[172:175], v[102:105]
	v_mfma_f32_16x16x32_f16 v[90:93], v[196:199], v[180:183], v[90:93]
	v_mfma_f32_16x16x32_f16 v[86:89], v[204:207], v[180:183], v[86:89]
	v_mfma_f32_16x16x32_f16 v[74:77], v[196:199], v[188:191], v[74:77]
	v_mfma_f32_16x16x32_f16 v[70:73], v[204:207], v[188:191], v[70:73]
	v_mfma_f32_16x16x32_f16 v[122:125], v[200:203], v[168:171], v[122:125]
	v_mfma_f32_16x16x32_f16 v[118:121], v[208:211], v[168:171], v[118:121]
	v_mfma_f32_16x16x32_f16 v[106:109], v[200:203], v[176:179], v[106:109]
	v_mfma_f32_16x16x32_f16 v[102:105], v[208:211], v[176:179], v[102:105]
	v_mfma_f32_16x16x32_f16 v[90:93], v[200:203], v[184:187], v[90:93]
	v_mfma_f32_16x16x32_f16 v[86:89], v[208:211], v[184:187], v[86:89]
	v_mfma_f32_16x16x32_f16 v[74:77], v[200:203], v[192:195], v[74:77]
	v_mfma_f32_16x16x32_f16 v[70:73], v[208:211], v[192:195], v[70:73]
	s_mov_b32 m0, s30
	v_lshl_add_u64 v[144:145], v[214:215], 0, s[86:87]
	s_barrier
	ds_read_b128 v[164:167], v1 offset:49152
	ds_read_b128 v[168:171], v1 offset:50176
	ds_read_b128 v[172:175], v1 offset:51200
	ds_read_b128 v[176:179], v1 offset:52224
	ds_read_b128 v[180:183], v1 offset:53248
	ds_read_b128 v[184:187], v1 offset:54272
	ds_read_b128 v[188:191], v1 offset:55296
	ds_read_b128 v[192:195], v1 offset:56320
	global_load_lds_dwordx4 v[144:145], off
	s_mov_b32 m0, s31
	v_lshl_add_u64 v[144:145], v[216:217], 0, s[86:87]
	global_load_lds_dwordx4 v[144:145], off
	s_barrier
	s_waitcnt lgkmcnt(0)
	s_waitcnt lgkmcnt(0)
	v_mfma_f32_16x16x32_f16 v[50:53], v[148:151], v[164:167], v[50:53]
	v_mfma_f32_16x16x32_f16 v[62:65], v[156:159], v[164:167], v[62:65]
	v_mfma_f32_16x16x32_f16 v[34:37], v[148:151], v[172:175], v[34:37]
	v_mfma_f32_16x16x32_f16 v[46:49], v[156:159], v[172:175], v[46:49]
	v_mfma_f32_16x16x32_f16 v[18:21], v[148:151], v[180:183], v[18:21]
	v_mfma_f32_16x16x32_f16 v[30:33], v[156:159], v[180:183], v[30:33]
	v_mfma_f32_16x16x32_f16 v[2:5], v[148:151], v[188:191], v[2:5]
	v_mfma_f32_16x16x32_f16 v[14:17], v[156:159], v[188:191], v[14:17]
	v_mfma_f32_16x16x32_f16 v[50:53], v[152:155], v[168:171], v[50:53]
	v_mfma_f32_16x16x32_f16 v[62:65], v[160:163], v[168:171], v[62:65]
	v_mfma_f32_16x16x32_f16 v[34:37], v[152:155], v[176:179], v[34:37]
	v_mfma_f32_16x16x32_f16 v[46:49], v[160:163], v[176:179], v[46:49]
	v_mfma_f32_16x16x32_f16 v[18:21], v[152:155], v[184:187], v[18:21]
	v_mfma_f32_16x16x32_f16 v[30:33], v[160:163], v[184:187], v[30:33]
	v_mfma_f32_16x16x32_f16 v[2:5], v[152:155], v[192:195], v[2:5]
	v_mfma_f32_16x16x32_f16 v[14:17], v[160:163], v[192:195], v[14:17]
	s_barrier
	s_add_u32 s14, s14, 0x400080
	s_addc_u32 s15, s15, 0
	s_mov_b32 m0, s34
	v_lshl_add_u64 v[144:145], s[14:15], 0, v[132:133]
	global_load_lds_dwordx4 v[144:145], off
	s_mov_b32 m0, s35
	v_lshl_add_u64 v[144:145], s[14:15], 0, v[136:137]
	global_load_lds_dwordx4 v[144:145], off
	s_waitcnt vmcnt(6)
	s_barrier
	v_mfma_f32_16x16x32_f16 v[58:61], v[196:199], v[164:167], v[58:61]
	v_mfma_f32_16x16x32_f16 v[54:57], v[204:207], v[164:167], v[54:57]
	v_mfma_f32_16x16x32_f16 v[42:45], v[196:199], v[172:175], v[42:45]
	v_mfma_f32_16x16x32_f16 v[38:41], v[204:207], v[172:175], v[38:41]
	v_mfma_f32_16x16x32_f16 v[26:29], v[196:199], v[180:183], v[26:29]
	v_mfma_f32_16x16x32_f16 v[22:25], v[204:207], v[180:183], v[22:25]
	v_mfma_f32_16x16x32_f16 v[10:13], v[196:199], v[188:191], v[10:13]
	v_mfma_f32_16x16x32_f16 v[6:9], v[204:207], v[188:191], v[6:9]
	v_mfma_f32_16x16x32_f16 v[58:61], v[200:203], v[168:171], v[58:61]
	v_mfma_f32_16x16x32_f16 v[54:57], v[208:211], v[168:171], v[54:57]
	v_mfma_f32_16x16x32_f16 v[42:45], v[200:203], v[176:179], v[42:45]
	v_mfma_f32_16x16x32_f16 v[38:41], v[208:211], v[176:179], v[38:41]
	v_mfma_f32_16x16x32_f16 v[26:29], v[200:203], v[184:187], v[26:29]
	v_mfma_f32_16x16x32_f16 v[22:25], v[208:211], v[184:187], v[22:25]
	v_mfma_f32_16x16x32_f16 v[10:13], v[200:203], v[192:195], v[10:13]
	v_mfma_f32_16x16x32_f16 v[6:9], v[208:211], v[192:195], v[6:9]
	s_add_u32 s12, s12, 0x100
	s_addc_u32 s13, s13, 0
	s_add_u32 s46, s46, 0x100
	s_addc_u32 s74, s74, 0
	s_cmp_ge_i32 s85, s5
	s_mov_b32 s14, s85
	s_barrier
	s_cbranch_scc0 .LBB0_2281
	s_branch .LBB0_2268

; #define G_STAGE(bufoff, gbase, v0, v1) do { \
;     __builtin_amdgcn_global_load_lds((const unsigned*)((const char*)(gbase) + (v0)), (LAS unsigned*)(lds + (bufoff) + ldsw), 16, 0, 0); \
;     __builtin_amdgcn_global_load_lds((const unsigned*)((const char*)(gbase) + (v1)), (LAS unsigned*)(lds + (bufoff) + ldsw + 8192), 16, 0, 0); } while (0)
; #define G_LDA(dst, b, h) do { _Pragma("unroll") for (int m = 0; m < 4; ++m) _Pragma("unroll") for (int k = 0; k < 2; ++k) dst[m][k] = *(const LAS h8*)(lds + G_SA(b, h) + aoff + m * 2048 + k * 1024); } while (0)
; #define G_LDB(dst, b, h) do { _Pragma("unroll") for (int n = 0; n < 2; ++n) _Pragma("unroll") for (int k = 0; k < 2; ++k) dst[n][k] = *(const LAS h8*)(lds + G_SB(b, h) + boff + n * 2048 + k * 1024); } while (0)
; #define G_MMA(ai, bj, At, Bt) do { __builtin_amdgcn_s_setprio(1); _Pragma("unroll") for (int m = 0; m < 4; ++m) _Pragma("unroll") for (int n = 0; n < 2; ++n) _Pragma("unroll") for (int k = 0; k < 2; ++k) \
;     acc[ai][bj][m][n] = __builtin_amdgcn_mfma_f32_16x16x32_f16(Bt[n][k], At[m][k], acc[ai][bj][m][n], 0, 0, 0); __builtin_amdgcn_s_setprio(0); } while (0)
; #define G_WAIT_V(n) asm volatile("s_waitcnt vmcnt(" #n ")" ::: "memory")
; #define G_WAIT_L(n) asm volatile("s_waitcnt lgkmcnt(" #n ")" ::: "memory")
; #define G_BAR __builtin_amdgcn_s_barrier()
; #define G_SCHED __builtin_amdgcn_sched_barrier(0)
; template <bool PERM, class Sched, class Epi>
; DI void gemm256(LAS unsigned char* lds, const Sched& S, const Epi& E, int wv_) {
;     ...
;       const bool last = (t == nt - 2);
;       const char* a1 = cA + (size_t)(t + 1) * kstep;
;       const char* a2 = last ? nA : cA + (size_t)(t + 2) * kstep;
;       const char* b2 = last ? nB : cB + (size_t)(t + 2) * kstep;
;       const char* a3 = a2 + kstep;
;       const char* b3 = b2 + kstep;
;       G_LDB(B0, 0, 0); G_SCHED; G_LDA(At, 0, 0); G_STAGE(G_SA(1, 1), a1 + chA, cvA0, cvA1);
;       G_WAIT_L(8); G_BAR; G_WAIT_L(0); G_MMA(0, 0, At, B0); G_BAR; G_SCHED;
;       G_LDB(B1, 0, 1); G_STAGE(G_SB(0, 0), b2, cvB0, cvB1);
;       G_BAR; G_WAIT_L(0); G_MMA(0, 1, At, B1); G_BAR;
;       G_LDA(At, 0, 1); G_STAGE(G_SA(0, 0), a2, cvA0, cvA1);
;       G_BAR; G_WAIT_L(0); G_MMA(1, 0, At, B0); G_BAR; G_SCHED;
;       G_STAGE(G_SB(0, 1), b2 + chB, cvB0, cvB1);
;       G_WAIT_V(6); G_BAR; G_MMA(1, 1, At, B1); G_BAR;
.LBB0_2355:
	ds_read_b128 v[132:135], v201
	ds_read_b128 v[136:139], v201 offset:1024
	s_add_i32 s85, s10, 2
	ds_read_b128 v[140:143], v201 offset:2048
	ds_read_b128 v[144:147], v201 offset:3072
	v_lshl_add_u64 v[2:3], s[8:9], 0, v[196:197]
	s_add_i32 m0, s16, 0xc000
	ds_read_b128 v[148:151], v184
	ds_read_b128 v[152:155], v184 offset:1024
	ds_read_b128 v[156:159], v184 offset:2048
	ds_read_b128 v[160:163], v184 offset:3072
	ds_read_b128 v[164:167], v184 offset:4096
	ds_read_b128 v[168:171], v184 offset:5120
	ds_read_b128 v[172:175], v184 offset:6144
	ds_read_b128 v[176:179], v184 offset:7168
	global_load_lds_dwordx4 v[2:3], off
	s_add_i32 m0, s16, 0xe000
	v_lshl_add_u64 v[2:3], s[8:9], 0, v[198:199]
	global_load_lds_dwordx4 v[2:3], off
	s_waitcnt lgkmcnt(8)
	s_barrier
	s_waitcnt lgkmcnt(0)
	s_waitcnt lgkmcnt(0)
	v_mfma_f32_16x16x32_f16 v[128:131], v[132:135], v[148:151], v[128:131]
	s_add_u32 s11, s8, 0xfffc0080
	s_addc_u32 s12, s9, -1
	s_cmp_eq_u32 s69, s10
	s_cselect_b32 s10, s4, s74
	s_cselect_b32 s13, s3, s12
	s_cselect_b32 s12, s2, s11
	s_cselect_b32 s11, s5, s75
	v_mfma_f32_16x16x32_f16 v[124:127], v[140:143], v[148:151], v[124:127]
	v_mfma_f32_16x16x32_f16 v[120:123], v[132:135], v[156:159], v[120:123]
	v_mfma_f32_16x16x32_f16 v[116:119], v[140:143], v[156:159], v[116:119]
	v_mfma_f32_16x16x32_f16 v[112:115], v[132:135], v[164:167], v[112:115]
	v_mfma_f32_16x16x32_f16 v[108:111], v[140:143], v[164:167], v[108:111]
	v_mfma_f32_16x16x32_f16 v[104:107], v[132:135], v[172:175], v[104:107]
	v_mfma_f32_16x16x32_f16 v[100:103], v[140:143], v[172:175], v[100:103]
	v_mfma_f32_16x16x32_f16 v[128:131], v[136:139], v[152:155], v[128:131]
	v_mfma_f32_16x16x32_f16 v[124:127], v[144:147], v[152:155], v[124:127]
	v_mfma_f32_16x16x32_f16 v[120:123], v[136:139], v[160:163], v[120:123]
	v_mfma_f32_16x16x32_f16 v[116:119], v[144:147], v[160:163], v[116:119]
	v_mfma_f32_16x16x32_f16 v[112:115], v[136:139], v[168:171], v[112:115]
	v_mfma_f32_16x16x32_f16 v[108:111], v[144:147], v[168:171], v[108:111]
	v_mfma_f32_16x16x32_f16 v[104:107], v[136:139], v[176:179], v[104:107]
	v_mfma_f32_16x16x32_f16 v[100:103], v[144:147], v[176:179], v[100:103]
	s_barrier
	s_mov_b32 m0, s17
	ds_read_b128 v[180:183], v239
	ds_read_b128 v[202:205], v239 offset:1024
	v_lshl_add_u64 v[214:215], s[10:11], 0, v[188:189]
	ds_read_b128 v[206:209], v239 offset:2048
	ds_read_b128 v[210:213], v239 offset:3072
	global_load_lds_dwordx4 v[214:215], off
	s_mov_b32 m0, s18
	v_lshl_add_u64 v[216:217], s[10:11], 0, v[192:193]
	global_load_lds_dwordx4 v[216:217], off
	s_barrier
	s_waitcnt lgkmcnt(0)
	s_waitcnt lgkmcnt(0)
	v_mfma_f32_16x16x32_f16 v[96:99], v[180:183], v[148:151], v[96:99]
	v_mfma_f32_16x16x32_f16 v[92:95], v[206:209], v[148:151], v[92:95]
	v_mfma_f32_16x16x32_f16 v[88:91], v[180:183], v[156:159], v[88:91]
	v_mfma_f32_16x16x32_f16 v[84:87], v[206:209], v[156:159], v[84:87]
	v_mfma_f32_16x16x32_f16 v[80:83], v[180:183], v[164:167], v[80:83]
	v_mfma_f32_16x16x32_f16 v[76:79], v[206:209], v[164:167], v[76:79]
	v_mfma_f32_16x16x32_f16 v[72:75], v[180:183], v[172:175], v[72:75]
	v_mfma_f32_16x16x32_f16 v[68:71], v[206:209], v[172:175], v[68:71]
	v_mfma_f32_16x16x32_f16 v[96:99], v[202:205], v[152:155], v[96:99]
	v_mfma_f32_16x16x32_f16 v[92:95], v[210:213], v[152:155], v[92:95]
	v_mfma_f32_16x16x32_f16 v[88:91], v[202:205], v[160:163], v[88:91]
	v_mfma_f32_16x16x32_f16 v[84:87], v[210:213], v[160:163], v[84:87]
	v_mfma_f32_16x16x32_f16 v[80:83], v[202:205], v[168:171], v[80:83]
	v_mfma_f32_16x16x32_f16 v[76:79], v[210:213], v[168:171], v[76:79]
	v_mfma_f32_16x16x32_f16 v[72:75], v[202:205], v[176:179], v[72:75]
	v_mfma_f32_16x16x32_f16 v[68:71], v[210:213], v[176:179], v[68:71]
	s_mov_b32 m0, s16
	v_lshl_add_u64 v[218:219], s[12:13], 0, v[186:187]
	s_barrier
	ds_read_b128 v[148:151], v184 offset:16384
	ds_read_b128 v[152:155], v184 offset:17408
	ds_read_b128 v[156:159], v184 offset:18432
	ds_read_b128 v[160:163], v184 offset:19456
	ds_read_b128 v[164:167], v184 offset:20480
	ds_read_b128 v[168:171], v184 offset:21504
	ds_read_b128 v[172:175], v184 offset:22528
	ds_read_b128 v[176:179], v184 offset:23552
	global_load_lds_dwordx4 v[218:219], off
	s_mov_b32 m0, s19
	v_lshl_add_u64 v[220:221], s[12:13], 0, v[190:191]
	global_load_lds_dwordx4 v[220:221], off
	s_barrier
	s_waitcnt lgkmcnt(0)
	s_waitcnt lgkmcnt(0)
	v_mfma_f32_16x16x32_f16 v[64:67], v[132:135], v[148:151], v[64:67]
	v_mfma_f32_16x16x32_f16 v[60:63], v[140:143], v[148:151], v[60:63]
	v_mfma_f32_16x16x32_f16 v[56:59], v[132:135], v[156:159], v[56:59]
	v_mfma_f32_16x16x32_f16 v[52:55], v[140:143], v[156:159], v[52:55]
	v_mfma_f32_16x16x32_f16 v[48:51], v[132:135], v[164:167], v[48:51]
	v_mfma_f32_16x16x32_f16 v[44:47], v[140:143], v[164:167], v[44:47]
	v_mfma_f32_16x16x32_f16 v[40:43], v[132:135], v[172:175], v[40:43]
	v_mfma_f32_16x16x32_f16 v[36:39], v[140:143], v[172:175], v[36:39]
	v_mfma_f32_16x16x32_f16 v[64:67], v[136:139], v[152:155], v[64:67]
	v_mfma_f32_16x16x32_f16 v[60:63], v[144:147], v[152:155], v[60:63]
	v_mfma_f32_16x16x32_f16 v[56:59], v[136:139], v[160:163], v[56:59]
	v_mfma_f32_16x16x32_f16 v[52:55], v[144:147], v[160:163], v[52:55]
	v_mfma_f32_16x16x32_f16 v[48:51], v[136:139], v[168:171], v[48:51]
	v_mfma_f32_16x16x32_f16 v[44:47], v[144:147], v[168:171], v[44:47]
	v_mfma_f32_16x16x32_f16 v[40:43], v[136:139], v[176:179], v[40:43]
	v_mfma_f32_16x16x32_f16 v[36:39], v[144:147], v[176:179], v[36:39]
	s_barrier
	s_add_u32 s40, s10, 0x10000
	s_addc_u32 s41, s11, 0
	s_mov_b32 m0, s20
	v_lshl_add_u64 v[2:3], s[40:41], 0, v[188:189]
	global_load_lds_dwordx4 v[2:3], off
	s_mov_b32 m0, s21
	v_lshl_add_u64 v[2:3], s[40:41], 0, v[192:193]
	global_load_lds_dwordx4 v[2:3], off
	s_waitcnt vmcnt(6)
	s_barrier
; #define G_STAGE(bufoff, gbase, v0, v1) do { \
;     __builtin_amdgcn_global_load_lds((const unsigned*)((const char*)(gbase) + (v0)), (LAS unsigned*)(lds + (bufoff) + ldsw), 16, 0, 0); \
;     __builtin_amdgcn_global_load_lds((const unsigned*)((const char*)(gbase) + (v1)), (LAS unsigned*)(lds + (bufoff) + ldsw + 8192), 16, 0, 0); } while (0)
; #define G_LDA(dst, b, h) do { _Pragma("unroll") for (int m = 0; m < 4; ++m) _Pragma("unroll") for (int k = 0; k < 2; ++k) dst[m][k] = *(const LAS h8*)(lds + G_SA(b, h) + aoff + m * 2048 + k * 1024); } while (0)
; #define G_LDB(dst, b, h) do { _Pragma("unroll") for (int n = 0; n < 2; ++n) _Pragma("unroll") for (int k = 0; k < 2; ++k) dst[n][k] = *(const LAS h8*)(lds + G_SB(b, h) + boff + n * 2048 + k * 1024); } while (0)
; #define G_MMA(ai, bj, At, Bt) do { __builtin_amdgcn_s_setprio(1); _Pragma("unroll") for (int m = 0; m < 4; ++m) _Pragma("unroll") for (int n = 0; n < 2; ++n) _Pragma("unroll") for (int k = 0; k < 2; ++k) \
;     acc[ai][bj][m][n] = __builtin_amdgcn_mfma_f32_16x16x32_f16(Bt[n][k], At[m][k], acc[ai][bj][m][n], 0, 0, 0); __builtin_amdgcn_s_setprio(0); } while (0)
; #define G_WAIT_V(n) asm volatile("s_waitcnt vmcnt(" #n ")" ::: "memory")
; #define G_WAIT_L(n) asm volatile("s_waitcnt lgkmcnt(" #n ")" ::: "memory")
; #define G_BAR __builtin_amdgcn_s_barrier()
; #define G_SCHED __builtin_amdgcn_sched_barrier(0)
; template <bool PERM, class Sched, class Epi>
; DI void gemm256(LAS unsigned char* lds, const Sched& S, const Epi& E, int wv_) {
;     ...
;       G_WAIT_V(6); G_BAR; G_MMA(1, 1, At, B1); G_BAR;
;       G_LDB(B0, 1, 0); G_SCHED; G_LDA(At, 1, 0); G_STAGE(G_SA(0, 1), a2 + chA, cvA0, cvA1);
;       G_WAIT_L(8); G_BAR; G_WAIT_L(0); G_MMA(0, 0, At, B0); G_BAR; G_SCHED;
;       G_LDB(B1, 1, 1); G_STAGE(G_SB(1, 0), b3, cvB0, cvB1);
	v_mfma_f32_16x16x32_f16 v[32:35], v[180:183], v[148:151], v[32:35]
	v_mfma_f32_16x16x32_f16 v[28:31], v[206:209], v[148:151], v[28:31]
	v_mfma_f32_16x16x32_f16 v[24:27], v[180:183], v[156:159], v[24:27]
	v_mfma_f32_16x16x32_f16 v[20:23], v[206:209], v[156:159], v[20:23]
	v_mfma_f32_16x16x32_f16 v[16:19], v[180:183], v[164:167], v[16:19]
	v_mfma_f32_16x16x32_f16 v[12:15], v[206:209], v[164:167], v[12:15]
	v_mfma_f32_16x16x32_f16 v[8:11], v[180:183], v[172:175], v[8:11]
	v_mfma_f32_16x16x32_f16 v[2:5], v[206:209], v[172:175], v[4:7]
	v_mfma_f32_16x16x32_f16 v[32:35], v[202:205], v[152:155], v[32:35]
	v_mfma_f32_16x16x32_f16 v[28:31], v[210:213], v[152:155], v[28:31]
	v_mfma_f32_16x16x32_f16 v[24:27], v[202:205], v[160:163], v[24:27]
	v_mfma_f32_16x16x32_f16 v[20:23], v[210:213], v[160:163], v[20:23]
	v_mfma_f32_16x16x32_f16 v[16:19], v[202:205], v[168:171], v[16:19]
	v_mfma_f32_16x16x32_f16 v[12:15], v[210:213], v[168:171], v[12:15]
	v_mfma_f32_16x16x32_f16 v[8:11], v[202:205], v[176:179], v[8:11]
	v_mfma_f32_16x16x32_f16 v[2:5], v[210:213], v[176:179], v[2:5]
	s_barrier
	ds_read_b128 v[132:135], v243
	ds_read_b128 v[136:139], v243 offset:1024
	ds_read_b128 v[140:143], v243 offset:2048
	ds_read_b128 v[144:147], v243 offset:3072
	s_add_u32 s12, s12, 0x40000
	s_addc_u32 s13, s13, 0
	s_mov_b32 m0, s22
	v_lshl_add_u64 v[6:7], s[12:13], 0, v[186:187]
	ds_read_b128 v[148:151], v184 offset:32768
	ds_read_b128 v[152:155], v184 offset:33792
	ds_read_b128 v[156:159], v184 offset:34816
	ds_read_b128 v[160:163], v184 offset:35840
	ds_read_b128 v[164:167], v184 offset:36864
	ds_read_b128 v[168:171], v184 offset:37888
	ds_read_b128 v[172:175], v184 offset:38912
	ds_read_b128 v[176:179], v184 offset:39936
	global_load_lds_dwordx4 v[6:7], off
	s_mov_b32 m0, s23
	v_lshl_add_u64 v[6:7], s[12:13], 0, v[190:191]
	global_load_lds_dwordx4 v[6:7], off
	s_waitcnt lgkmcnt(8)
	s_barrier
	s_waitcnt lgkmcnt(0)
	s_waitcnt lgkmcnt(0)
	v_mfma_f32_16x16x32_f16 v[128:131], v[132:135], v[148:151], v[128:131]
	v_mfma_f32_16x16x32_f16 v[124:127], v[140:143], v[148:151], v[124:127]
	v_mfma_f32_16x16x32_f16 v[120:123], v[132:135], v[156:159], v[120:123]
	v_mfma_f32_16x16x32_f16 v[116:119], v[140:143], v[156:159], v[116:119]
	v_mfma_f32_16x16x32_f16 v[112:115], v[132:135], v[164:167], v[112:115]
	v_mfma_f32_16x16x32_f16 v[108:111], v[140:143], v[164:167], v[108:111]
	v_mfma_f32_16x16x32_f16 v[104:107], v[132:135], v[172:175], v[104:107]
	v_mfma_f32_16x16x32_f16 v[100:103], v[140:143], v[172:175], v[100:103]
	v_mfma_f32_16x16x32_f16 v[128:131], v[136:139], v[152:155], v[128:131]
	v_mfma_f32_16x16x32_f16 v[124:127], v[144:147], v[152:155], v[124:127]
	v_mfma_f32_16x16x32_f16 v[120:123], v[136:139], v[160:163], v[120:123]
	v_mfma_f32_16x16x32_f16 v[116:119], v[144:147], v[160:163], v[116:119]
	v_mfma_f32_16x16x32_f16 v[112:115], v[136:139], v[168:171], v[112:115]
	v_mfma_f32_16x16x32_f16 v[108:111], v[144:147], v[168:171], v[108:111]
	v_mfma_f32_16x16x32_f16 v[104:107], v[136:139], v[176:179], v[104:107]
	v_mfma_f32_16x16x32_f16 v[100:103], v[144:147], v[176:179], v[100:103]
	s_barrier
	ds_read_b128 v[180:183], v244
	ds_read_b128 v[202:205], v244 offset:1024
	s_mov_b32 m0, s26
	ds_read_b128 v[206:209], v244 offset:2048
	ds_read_b128 v[210:213], v244 offset:3072
	v_lshl_add_u64 v[6:7], v[214:215], 0, s[86:87]
	global_load_lds_dwordx4 v[6:7], off
	s_mov_b32 m0, s27
	v_lshl_add_u64 v[6:7], v[216:217], 0, s[86:87]
	global_load_lds_dwordx4 v[6:7], off
	s_barrier
; #define G_STAGE(bufoff, gbase, v0, v1) do { \
;     __builtin_amdgcn_global_load_lds((const unsigned*)((const char*)(gbase) + (v0)), (LAS unsigned*)(lds + (bufoff) + ldsw), 16, 0, 0); \
;     __builtin_amdgcn_global_load_lds((const unsigned*)((const char*)(gbase) + (v1)), (LAS unsigned*)(lds + (bufoff) + ldsw + 8192), 16, 0, 0); } while (0)
; #define G_LDA(dst, b, h) do { _Pragma("unroll") for (int m = 0; m < 4; ++m) _Pragma("unroll") for (int k = 0; k < 2; ++k) dst[m][k] = *(const LAS h8*)(lds + G_SA(b, h) + aoff + m * 2048 + k * 1024); } while (0)
; #define G_LDB(dst, b, h) do { _Pragma("unroll") for (int n = 0; n < 2; ++n) _Pragma("unroll") for (int k = 0; k < 2; ++k) dst[n][k] = *(const LAS h8*)(lds + G_SB(b, h) + boff + n * 2048 + k * 1024); } while (0)
; #define G_MMA(ai, bj, At, Bt) do { __builtin_amdgcn_s_setprio(1); _Pragma("unroll") for (int m = 0; m < 4; ++m) _Pragma("unroll") for (int n = 0; n < 2; ++n) _Pragma("unroll") for (int k = 0; k < 2; ++k) \
;     acc[ai][bj][m][n] = __builtin_amdgcn_mfma_f32_16x16x32_f16(Bt[n][k], At[m][k], acc[ai][bj][m][n], 0, 0, 0); __builtin_amdgcn_s_setprio(0); } while (0)
; #define G_WAIT_V(n) asm volatile("s_waitcnt vmcnt(" #n ")" ::: "memory")
; #define G_WAIT_L(n) asm volatile("s_waitcnt lgkmcnt(" #n ")" ::: "memory")
; #define G_BAR __builtin_amdgcn_s_barrier()
; #define G_SCHED __builtin_amdgcn_sched_barrier(0)
; template <bool PERM, class Sched, class Epi>
; DI void gemm256(LAS unsigned char* lds, const Sched& S, const Epi& E, int wv_) {
;     ...
;       G_LDB(B1, 1, 1); G_STAGE(G_SB(1, 0), b3, cvB0, cvB1);
;       G_BAR; G_WAIT_L(0); G_MMA(0, 1, At, B1); G_BAR;
;       G_LDA(At, 1, 1); G_STAGE(G_SA(1, 0), a3, cvA0, cvA1);
;       G_BAR; G_WAIT_L(0); G_MMA(1, 0, At, B0); G_BAR; G_SCHED;
;       G_STAGE(G_SB(1, 1), b3 + chB, cvB0, cvB1);
;       G_WAIT_V(6); G_BAR; G_MMA(1, 1, At, B1); G_BAR;
;     }
	s_waitcnt lgkmcnt(0)
	s_waitcnt lgkmcnt(0)
	v_mfma_f32_16x16x32_f16 v[96:99], v[180:183], v[148:151], v[96:99]
	v_mfma_f32_16x16x32_f16 v[92:95], v[206:209], v[148:151], v[92:95]
	v_mfma_f32_16x16x32_f16 v[88:91], v[180:183], v[156:159], v[88:91]
	v_mfma_f32_16x16x32_f16 v[84:87], v[206:209], v[156:159], v[84:87]
	v_mfma_f32_16x16x32_f16 v[80:83], v[180:183], v[164:167], v[80:83]
	v_mfma_f32_16x16x32_f16 v[76:79], v[206:209], v[164:167], v[76:79]
	v_mfma_f32_16x16x32_f16 v[72:75], v[180:183], v[172:175], v[72:75]
	v_mfma_f32_16x16x32_f16 v[68:71], v[206:209], v[172:175], v[68:71]
	v_mfma_f32_16x16x32_f16 v[96:99], v[202:205], v[152:155], v[96:99]
	v_mfma_f32_16x16x32_f16 v[92:95], v[210:213], v[152:155], v[92:95]
	v_mfma_f32_16x16x32_f16 v[88:91], v[202:205], v[160:163], v[88:91]
	v_mfma_f32_16x16x32_f16 v[84:87], v[210:213], v[160:163], v[84:87]
	v_mfma_f32_16x16x32_f16 v[80:83], v[202:205], v[168:171], v[80:83]
	v_mfma_f32_16x16x32_f16 v[76:79], v[210:213], v[168:171], v[76:79]
	v_mfma_f32_16x16x32_f16 v[72:75], v[202:205], v[176:179], v[72:75]
	v_mfma_f32_16x16x32_f16 v[68:71], v[210:213], v[176:179], v[68:71]
	s_mov_b32 m0, s28
	v_lshl_add_u64 v[6:7], v[218:219], 0, s[86:87]
	s_barrier
	ds_read_b128 v[148:151], v184 offset:49152
	ds_read_b128 v[152:155], v184 offset:50176
	ds_read_b128 v[156:159], v184 offset:51200
	ds_read_b128 v[160:163], v184 offset:52224
	ds_read_b128 v[164:167], v184 offset:53248
	ds_read_b128 v[168:171], v184 offset:54272
	ds_read_b128 v[172:175], v184 offset:55296
	ds_read_b128 v[176:179], v184 offset:56320
	global_load_lds_dwordx4 v[6:7], off
	s_mov_b32 m0, s29
	v_lshl_add_u64 v[6:7], v[220:221], 0, s[86:87]
	global_load_lds_dwordx4 v[6:7], off
	s_barrier
	s_waitcnt lgkmcnt(0)
	s_waitcnt lgkmcnt(0)
	v_mfma_f32_16x16x32_f16 v[64:67], v[132:135], v[148:151], v[64:67]
	v_mfma_f32_16x16x32_f16 v[60:63], v[140:143], v[148:151], v[60:63]
	v_mfma_f32_16x16x32_f16 v[56:59], v[132:135], v[156:159], v[56:59]
	v_mfma_f32_16x16x32_f16 v[52:55], v[140:143], v[156:159], v[52:55]
	v_mfma_f32_16x16x32_f16 v[48:51], v[132:135], v[164:167], v[48:51]
	v_mfma_f32_16x16x32_f16 v[44:47], v[140:143], v[164:167], v[44:47]
	v_mfma_f32_16x16x32_f16 v[40:43], v[132:135], v[172:175], v[40:43]
	v_mfma_f32_16x16x32_f16 v[36:39], v[140:143], v[172:175], v[36:39]
	v_mfma_f32_16x16x32_f16 v[64:67], v[136:139], v[152:155], v[64:67]
	v_mfma_f32_16x16x32_f16 v[60:63], v[144:147], v[152:155], v[60:63]
	v_mfma_f32_16x16x32_f16 v[56:59], v[136:139], v[160:163], v[56:59]
	v_mfma_f32_16x16x32_f16 v[52:55], v[144:147], v[160:163], v[52:55]
	v_mfma_f32_16x16x32_f16 v[48:51], v[136:139], v[168:171], v[48:51]
	v_mfma_f32_16x16x32_f16 v[44:47], v[144:147], v[168:171], v[44:47]
	v_mfma_f32_16x16x32_f16 v[40:43], v[136:139], v[176:179], v[40:43]
	v_mfma_f32_16x16x32_f16 v[36:39], v[144:147], v[176:179], v[36:39]
	s_barrier
	s_add_u32 s10, s10, 0x10080
	s_addc_u32 s11, s11, 0
	s_mov_b32 m0, s30
	v_lshl_add_u64 v[6:7], s[10:11], 0, v[188:189]
	global_load_lds_dwordx4 v[6:7], off
	s_mov_b32 m0, s31
	v_lshl_add_u64 v[6:7], s[10:11], 0, v[192:193]
	global_load_lds_dwordx4 v[6:7], off
	s_waitcnt vmcnt(6)
	s_barrier
	v_mfma_f32_16x16x32_f16 v[32:35], v[180:183], v[148:151], v[32:35]
	v_mfma_f32_16x16x32_f16 v[28:31], v[206:209], v[148:151], v[28:31]
	v_mfma_f32_16x16x32_f16 v[24:27], v[180:183], v[156:159], v[24:27]
	v_mfma_f32_16x16x32_f16 v[20:23], v[206:209], v[156:159], v[20:23]
	v_mfma_f32_16x16x32_f16 v[16:19], v[180:183], v[164:167], v[16:19]
	v_mfma_f32_16x16x32_f16 v[12:15], v[206:209], v[164:167], v[12:15]
	v_mfma_f32_16x16x32_f16 v[6:9], v[180:183], v[172:175], v[8:11]
	v_mfma_f32_16x16x32_f16 v[2:5], v[206:209], v[172:175], v[2:5]
	v_mfma_f32_16x16x32_f16 v[32:35], v[202:205], v[152:155], v[32:35]
	v_mfma_f32_16x16x32_f16 v[28:31], v[210:213], v[152:155], v[28:31]
	v_mfma_f32_16x16x32_f16 v[24:27], v[202:205], v[160:163], v[24:27]
	v_mfma_f32_16x16x32_f16 v[20:23], v[210:213], v[160:163], v[20:23]
	v_mfma_f32_16x16x32_f16 v[16:19], v[202:205], v[168:171], v[16:19]
	v_mfma_f32_16x16x32_f16 v[12:15], v[210:213], v[168:171], v[12:15]
	v_mfma_f32_16x16x32_f16 v[8:11], v[202:205], v[176:179], v[6:9]
	v_mfma_f32_16x16x32_f16 v[4:7], v[210:213], v[176:179], v[2:5]
	s_add_u32 s8, s8, 0x100
	s_addc_u32 s9, s9, 0
	s_add_u32 s74, s74, 0x100
	s_addc_u32 s75, s75, 0
	s_cmp_ge_i32 s85, s46
	s_mov_b32 s10, s85
	s_barrier
	s_cbranch_scc0 .LBB0_2355

; #define G_STAGE(bufoff, gbase, v0, v1) do { \
;     __builtin_amdgcn_global_load_lds((const unsigned*)((const char*)(gbase) + (v0)), (LAS unsigned*)(lds + (bufoff) + ldsw), 16, 0, 0); \
;     __builtin_amdgcn_global_load_lds((const unsigned*)((const char*)(gbase) + (v1)), (LAS unsigned*)(lds + (bufoff) + ldsw + 8192), 16, 0, 0); } while (0)
; #define G_LDA(dst, b, h) do { _Pragma("unroll") for (int m = 0; m < 4; ++m) _Pragma("unroll") for (int k = 0; k < 2; ++k) dst[m][k] = *(const LAS h8*)(lds + G_SA(b, h) + aoff + m * 2048 + k * 1024); } while (0)
; #define G_LDB(dst, b, h) do { _Pragma("unroll") for (int n = 0; n < 2; ++n) _Pragma("unroll") for (int k = 0; k < 2; ++k) dst[n][k] = *(const LAS h8*)(lds + G_SB(b, h) + boff + n * 2048 + k * 1024); } while (0)
; #define G_MMA(ai, bj, At, Bt) do { __builtin_amdgcn_s_setprio(1); _Pragma("unroll") for (int m = 0; m < 4; ++m) _Pragma("unroll") for (int n = 0; n < 2; ++n) _Pragma("unroll") for (int k = 0; k < 2; ++k) \
;     acc[ai][bj][m][n] = __builtin_amdgcn_mfma_f32_16x16x32_f16(Bt[n][k], At[m][k], acc[ai][bj][m][n], 0, 0, 0); __builtin_amdgcn_s_setprio(0); } while (0)
; #define G_WAIT_V(n) asm volatile("s_waitcnt vmcnt(" #n ")" ::: "memory")
; #define G_WAIT_L(n) asm volatile("s_waitcnt lgkmcnt(" #n ")" ::: "memory")
; #define G_BAR __builtin_amdgcn_s_barrier()
; #define G_SCHED __builtin_amdgcn_sched_barrier(0)
; template <bool PERM, class Sched, class Epi>
; DI void gemm256(LAS unsigned char* lds, const Sched& S, const Epi& E, int wv_) {
;     ...
;       const bool last = (t == nt - 2);
;       const char* a1 = cA + (size_t)(t + 1) * kstep;
;       const char* a2 = last ? nA : cA + (size_t)(t + 2) * kstep;
;       const char* b2 = last ? nB : cB + (size_t)(t + 2) * kstep;
;       const char* a3 = a2 + kstep;
;       const char* b3 = b2 + kstep;
;       G_LDB(B0, 0, 0); G_SCHED; G_LDA(At, 0, 0); G_STAGE(G_SA(1, 1), a1 + chA, cvA0, cvA1);
;       G_WAIT_L(8); G_BAR; G_WAIT_L(0); G_MMA(0, 0, At, B0); G_BAR; G_SCHED;
;       G_LDB(B1, 0, 1); G_STAGE(G_SB(0, 0), b2, cvB0, cvB1);
;       G_BAR; G_WAIT_L(0); G_MMA(0, 1, At, B1); G_BAR;
;       G_LDA(At, 0, 1); G_STAGE(G_SA(0, 0), a2, cvA0, cvA1);
;       G_BAR; G_WAIT_L(0); G_MMA(1, 0, At, B0); G_BAR; G_SCHED;
;       G_STAGE(G_SB(0, 1), b2 + chB, cvB0, cvB1);
;       G_WAIT_V(6); G_BAR; G_MMA(1, 1, At, B1); G_BAR;
.LBB0_2433:
	s_waitcnt vmcnt(0)
	s_add_i32 s74, s20, 2
	ds_read_b128 v[130:133], v216
	ds_read_b128 v[134:137], v216 offset:1024
	ds_read_b128 v[138:141], v216 offset:2048
	ds_read_b128 v[142:145], v216 offset:3072
	v_lshl_add_u64 v[192:193], s[18:19], 0, v[158:159]
	s_add_i32 m0, s31, 0xc000
	ds_read_b128 v[146:149], v1
	ds_read_b128 v[164:167], v1 offset:1024
	ds_read_b128 v[168:171], v1 offset:2048
	ds_read_b128 v[172:175], v1 offset:3072
	ds_read_b128 v[176:179], v1 offset:4096
	ds_read_b128 v[180:183], v1 offset:5120
	ds_read_b128 v[184:187], v1 offset:6144
	ds_read_b128 v[188:191], v1 offset:7168
	global_load_lds_dwordx4 v[192:193], off
	s_add_i32 m0, s31, 0xe000
	v_lshl_add_u64 v[192:193], s[18:19], 0, v[160:161]
	global_load_lds_dwordx4 v[192:193], off
	s_waitcnt lgkmcnt(8)
	s_barrier
	s_waitcnt lgkmcnt(0)
	s_waitcnt lgkmcnt(0)
	v_mfma_f32_16x16x32_f16 v[126:129], v[130:133], v[146:149], v[126:129]
	s_add_u32 s21, s18, 0xfffc0080
	s_addc_u32 s22, s19, -1
	s_cmp_eq_u32 vcc_lo, s20
	s_cselect_b32 s20, s85, s75
	s_cselect_b32 s23, s9, s22
	s_cselect_b32 s22, s27, s21
	s_cselect_b32 s21, s56, s46
	v_mfma_f32_16x16x32_f16 v[122:125], v[138:141], v[146:149], v[122:125]
	v_mfma_f32_16x16x32_f16 v[110:113], v[130:133], v[168:171], v[110:113]
	v_mfma_f32_16x16x32_f16 v[106:109], v[138:141], v[168:171], v[106:109]
	v_mfma_f32_16x16x32_f16 v[94:97], v[130:133], v[176:179], v[94:97]
	v_mfma_f32_16x16x32_f16 v[90:93], v[138:141], v[176:179], v[90:93]
	v_mfma_f32_16x16x32_f16 v[78:81], v[130:133], v[184:187], v[78:81]
	v_mfma_f32_16x16x32_f16 v[74:77], v[138:141], v[184:187], v[74:77]
	v_mfma_f32_16x16x32_f16 v[126:129], v[134:137], v[164:167], v[126:129]
	v_mfma_f32_16x16x32_f16 v[122:125], v[142:145], v[164:167], v[122:125]
	v_mfma_f32_16x16x32_f16 v[110:113], v[134:137], v[172:175], v[110:113]
	v_mfma_f32_16x16x32_f16 v[106:109], v[142:145], v[172:175], v[106:109]
	v_mfma_f32_16x16x32_f16 v[94:97], v[134:137], v[180:183], v[94:97]
	v_mfma_f32_16x16x32_f16 v[90:93], v[142:145], v[180:183], v[90:93]
	v_mfma_f32_16x16x32_f16 v[78:81], v[134:137], v[188:191], v[78:81]
	v_mfma_f32_16x16x32_f16 v[74:77], v[142:145], v[188:191], v[74:77]
	s_barrier
	s_mov_b32 m0, s34
	ds_read_b128 v[192:195], v217
	ds_read_b128 v[196:199], v217 offset:1024
	v_lshl_add_u64 v[208:209], s[20:21], 0, v[150:151]
	ds_read_b128 v[200:203], v217 offset:2048
	ds_read_b128 v[204:207], v217 offset:3072
	global_load_lds_dwordx4 v[208:209], off
	s_mov_b32 m0, s35
	v_lshl_add_u64 v[210:211], s[20:21], 0, v[152:153]
	global_load_lds_dwordx4 v[210:211], off
	s_barrier
	s_waitcnt lgkmcnt(0)
	s_waitcnt lgkmcnt(0)
	v_mfma_f32_16x16x32_f16 v[118:121], v[192:195], v[146:149], v[118:121]
	v_mfma_f32_16x16x32_f16 v[114:117], v[200:203], v[146:149], v[114:117]
	v_mfma_f32_16x16x32_f16 v[102:105], v[192:195], v[168:171], v[102:105]
	v_mfma_f32_16x16x32_f16 v[98:101], v[200:203], v[168:171], v[98:101]
	v_mfma_f32_16x16x32_f16 v[86:89], v[192:195], v[176:179], v[86:89]
	v_mfma_f32_16x16x32_f16 v[82:85], v[200:203], v[176:179], v[82:85]
	v_mfma_f32_16x16x32_f16 v[70:73], v[192:195], v[184:187], v[70:73]
	v_mfma_f32_16x16x32_f16 v[66:69], v[200:203], v[184:187], v[66:69]
	v_mfma_f32_16x16x32_f16 v[118:121], v[196:199], v[164:167], v[118:121]
	v_mfma_f32_16x16x32_f16 v[114:117], v[204:207], v[164:167], v[114:117]
	v_mfma_f32_16x16x32_f16 v[102:105], v[196:199], v[172:175], v[102:105]
	v_mfma_f32_16x16x32_f16 v[98:101], v[204:207], v[172:175], v[98:101]
	v_mfma_f32_16x16x32_f16 v[86:89], v[196:199], v[180:183], v[86:89]
	v_mfma_f32_16x16x32_f16 v[82:85], v[204:207], v[180:183], v[82:85]
	v_mfma_f32_16x16x32_f16 v[70:73], v[196:199], v[188:191], v[70:73]
	v_mfma_f32_16x16x32_f16 v[66:69], v[204:207], v[188:191], v[66:69]
	s_mov_b32 m0, s31
	v_lshl_add_u64 v[212:213], s[22:23], 0, v[150:151]
	s_barrier
	ds_read_b128 v[146:149], v1 offset:16384
	ds_read_b128 v[164:167], v1 offset:17408
	ds_read_b128 v[168:171], v1 offset:18432
	ds_read_b128 v[172:175], v1 offset:19456
	ds_read_b128 v[176:179], v1 offset:20480
	ds_read_b128 v[180:183], v1 offset:21504
	ds_read_b128 v[184:187], v1 offset:22528
	ds_read_b128 v[188:191], v1 offset:23552
	global_load_lds_dwordx4 v[212:213], off
	s_mov_b32 m0, s36
	v_lshl_add_u64 v[214:215], s[22:23], 0, v[152:153]
	global_load_lds_dwordx4 v[214:215], off
	s_barrier
	s_waitcnt lgkmcnt(0)
	s_waitcnt lgkmcnt(0)
	v_mfma_f32_16x16x32_f16 v[62:65], v[130:133], v[146:149], v[62:65]
	v_mfma_f32_16x16x32_f16 v[58:61], v[138:141], v[146:149], v[58:61]
	v_mfma_f32_16x16x32_f16 v[46:49], v[130:133], v[168:171], v[46:49]
	v_mfma_f32_16x16x32_f16 v[42:45], v[138:141], v[168:171], v[42:45]
	v_mfma_f32_16x16x32_f16 v[30:33], v[130:133], v[176:179], v[30:33]
	v_mfma_f32_16x16x32_f16 v[26:29], v[138:141], v[176:179], v[26:29]
	v_mfma_f32_16x16x32_f16 v[14:17], v[130:133], v[184:187], v[14:17]
	v_mfma_f32_16x16x32_f16 v[10:13], v[138:141], v[184:187], v[10:13]
	v_mfma_f32_16x16x32_f16 v[62:65], v[134:137], v[164:167], v[62:65]
	v_mfma_f32_16x16x32_f16 v[58:61], v[142:145], v[164:167], v[58:61]
	v_mfma_f32_16x16x32_f16 v[46:49], v[134:137], v[172:175], v[46:49]
	v_mfma_f32_16x16x32_f16 v[42:45], v[142:145], v[172:175], v[42:45]
	v_mfma_f32_16x16x32_f16 v[30:33], v[134:137], v[180:183], v[30:33]
	v_mfma_f32_16x16x32_f16 v[26:29], v[142:145], v[180:183], v[26:29]
	v_mfma_f32_16x16x32_f16 v[14:17], v[134:137], v[188:191], v[14:17]
	v_mfma_f32_16x16x32_f16 v[10:13], v[142:145], v[188:191], v[10:13]
	s_barrier
	s_add_u32 s40, s20, 0x40000
	s_addc_u32 s41, s21, 0
	s_mov_b32 m0, s37
	v_lshl_add_u64 v[130:131], s[40:41], 0, v[150:151]
	global_load_lds_dwordx4 v[130:131], off
	s_mov_b32 m0, s58
	v_lshl_add_u64 v[130:131], s[40:41], 0, v[152:153]
	global_load_lds_dwordx4 v[130:131], off
	s_waitcnt vmcnt(6)
	s_barrier
; #define G_STAGE(bufoff, gbase, v0, v1) do { \
;     __builtin_amdgcn_global_load_lds((const unsigned*)((const char*)(gbase) + (v0)), (LAS unsigned*)(lds + (bufoff) + ldsw), 16, 0, 0); \
;     __builtin_amdgcn_global_load_lds((const unsigned*)((const char*)(gbase) + (v1)), (LAS unsigned*)(lds + (bufoff) + ldsw + 8192), 16, 0, 0); } while (0)
; #define G_LDA(dst, b, h) do { _Pragma("unroll") for (int m = 0; m < 4; ++m) _Pragma("unroll") for (int k = 0; k < 2; ++k) dst[m][k] = *(const LAS h8*)(lds + G_SA(b, h) + aoff + m * 2048 + k * 1024); } while (0)
; #define G_LDB(dst, b, h) do { _Pragma("unroll") for (int n = 0; n < 2; ++n) _Pragma("unroll") for (int k = 0; k < 2; ++k) dst[n][k] = *(const LAS h8*)(lds + G_SB(b, h) + boff + n * 2048 + k * 1024); } while (0)
; #define G_MMA(ai, bj, At, Bt) do { __builtin_amdgcn_s_setprio(1); _Pragma("unroll") for (int m = 0; m < 4; ++m) _Pragma("unroll") for (int n = 0; n < 2; ++n) _Pragma("unroll") for (int k = 0; k < 2; ++k) \
;     acc[ai][bj][m][n] = __builtin_amdgcn_mfma_f32_16x16x32_f16(Bt[n][k], At[m][k], acc[ai][bj][m][n], 0, 0, 0); __builtin_amdgcn_s_setprio(0); } while (0)
; #define G_WAIT_V(n) asm volatile("s_waitcnt vmcnt(" #n ")" ::: "memory")
; #define G_WAIT_L(n) asm volatile("s_waitcnt lgkmcnt(" #n ")" ::: "memory")
; #define G_BAR __builtin_amdgcn_s_barrier()
; #define G_SCHED __builtin_amdgcn_sched_barrier(0)
; template <bool PERM, class Sched, class Epi>
; DI void gemm256(LAS unsigned char* lds, const Sched& S, const Epi& E, int wv_) {
;     ...
;       G_WAIT_V(6); G_BAR; G_MMA(1, 1, At, B1); G_BAR;
;       G_LDB(B0, 1, 0); G_SCHED; G_LDA(At, 1, 0); G_STAGE(G_SA(0, 1), a2 + chA, cvA0, cvA1);
;       G_WAIT_L(8); G_BAR; G_WAIT_L(0); G_MMA(0, 0, At, B0); G_BAR; G_SCHED;
;       G_LDB(B1, 1, 1); G_STAGE(G_SB(1, 0), b3, cvB0, cvB1);
	v_mfma_f32_16x16x32_f16 v[54:57], v[192:195], v[146:149], v[54:57]
	v_mfma_f32_16x16x32_f16 v[50:53], v[200:203], v[146:149], v[50:53]
	v_mfma_f32_16x16x32_f16 v[38:41], v[192:195], v[168:171], v[38:41]
	v_mfma_f32_16x16x32_f16 v[34:37], v[200:203], v[168:171], v[34:37]
	v_mfma_f32_16x16x32_f16 v[22:25], v[192:195], v[176:179], v[22:25]
	v_mfma_f32_16x16x32_f16 v[18:21], v[200:203], v[176:179], v[18:21]
	v_mfma_f32_16x16x32_f16 v[6:9], v[192:195], v[184:187], v[6:9]
	v_mfma_f32_16x16x32_f16 v[2:5], v[200:203], v[184:187], v[2:5]
	v_mfma_f32_16x16x32_f16 v[54:57], v[196:199], v[164:167], v[54:57]
	v_mfma_f32_16x16x32_f16 v[50:53], v[204:207], v[164:167], v[50:53]
	v_mfma_f32_16x16x32_f16 v[38:41], v[196:199], v[172:175], v[38:41]
	v_mfma_f32_16x16x32_f16 v[34:37], v[204:207], v[172:175], v[34:37]
	v_mfma_f32_16x16x32_f16 v[22:25], v[196:199], v[180:183], v[22:25]
	v_mfma_f32_16x16x32_f16 v[18:21], v[204:207], v[180:183], v[18:21]
	v_mfma_f32_16x16x32_f16 v[6:9], v[196:199], v[188:191], v[6:9]
	v_mfma_f32_16x16x32_f16 v[2:5], v[204:207], v[188:191], v[2:5]
	s_barrier
	ds_read_b128 v[130:133], v218
	ds_read_b128 v[134:137], v218 offset:1024
	ds_read_b128 v[138:141], v218 offset:2048
	ds_read_b128 v[142:145], v218 offset:3072
	s_add_u32 s22, s22, 0x40000
	s_addc_u32 s23, s23, 0
	s_mov_b32 m0, s59
	v_lshl_add_u64 v[192:193], s[22:23], 0, v[150:151]
	ds_read_b128 v[146:149], v1 offset:32768
	ds_read_b128 v[164:167], v1 offset:33792
	ds_read_b128 v[168:171], v1 offset:34816
	ds_read_b128 v[172:175], v1 offset:35840
	ds_read_b128 v[176:179], v1 offset:36864
	ds_read_b128 v[180:183], v1 offset:37888
	ds_read_b128 v[184:187], v1 offset:38912
	ds_read_b128 v[188:191], v1 offset:39936
	global_load_lds_dwordx4 v[192:193], off
	s_mov_b32 m0, s61
	v_lshl_add_u64 v[192:193], s[22:23], 0, v[152:153]
	global_load_lds_dwordx4 v[192:193], off
	s_waitcnt lgkmcnt(8)
	s_barrier
	s_waitcnt lgkmcnt(0)
	s_waitcnt lgkmcnt(0)
	v_mfma_f32_16x16x32_f16 v[126:129], v[130:133], v[146:149], v[126:129]
	v_mfma_f32_16x16x32_f16 v[122:125], v[138:141], v[146:149], v[122:125]
	v_mfma_f32_16x16x32_f16 v[110:113], v[130:133], v[168:171], v[110:113]
	v_mfma_f32_16x16x32_f16 v[106:109], v[138:141], v[168:171], v[106:109]
	v_mfma_f32_16x16x32_f16 v[94:97], v[130:133], v[176:179], v[94:97]
	v_mfma_f32_16x16x32_f16 v[90:93], v[138:141], v[176:179], v[90:93]
	v_mfma_f32_16x16x32_f16 v[78:81], v[130:133], v[184:187], v[78:81]
	v_mfma_f32_16x16x32_f16 v[74:77], v[138:141], v[184:187], v[74:77]
	v_mfma_f32_16x16x32_f16 v[126:129], v[134:137], v[164:167], v[126:129]
	v_mfma_f32_16x16x32_f16 v[122:125], v[142:145], v[164:167], v[122:125]
	v_mfma_f32_16x16x32_f16 v[110:113], v[134:137], v[172:175], v[110:113]
	v_mfma_f32_16x16x32_f16 v[106:109], v[142:145], v[172:175], v[106:109]
	v_mfma_f32_16x16x32_f16 v[94:97], v[134:137], v[180:183], v[94:97]
	v_mfma_f32_16x16x32_f16 v[90:93], v[142:145], v[180:183], v[90:93]
	v_mfma_f32_16x16x32_f16 v[78:81], v[134:137], v[188:191], v[78:81]
	v_mfma_f32_16x16x32_f16 v[74:77], v[142:145], v[188:191], v[74:77]
	s_barrier
	s_mov_b32 m0, s69
	ds_read_b128 v[192:195], v219
	ds_read_b128 v[196:199], v219 offset:1024
	v_lshl_add_u64 v[208:209], v[208:209], 0, s[86:87]
	ds_read_b128 v[200:203], v219 offset:2048
	ds_read_b128 v[204:207], v219 offset:3072
	global_load_lds_dwordx4 v[208:209], off
	s_mov_b32 m0, s78
	v_lshl_add_u64 v[208:209], v[210:211], 0, s[86:87]
	global_load_lds_dwordx4 v[208:209], off
	s_barrier
; #define G_STAGE(bufoff, gbase, v0, v1) do { \
;     __builtin_amdgcn_global_load_lds((const unsigned*)((const char*)(gbase) + (v0)), (LAS unsigned*)(lds + (bufoff) + ldsw), 16, 0, 0); \
;     __builtin_amdgcn_global_load_lds((const unsigned*)((const char*)(gbase) + (v1)), (LAS unsigned*)(lds + (bufoff) + ldsw + 8192), 16, 0, 0); } while (0)
; #define G_LDA(dst, b, h) do { _Pragma("unroll") for (int m = 0; m < 4; ++m) _Pragma("unroll") for (int k = 0; k < 2; ++k) dst[m][k] = *(const LAS h8*)(lds + G_SA(b, h) + aoff + m * 2048 + k * 1024); } while (0)
; #define G_LDB(dst, b, h) do { _Pragma("unroll") for (int n = 0; n < 2; ++n) _Pragma("unroll") for (int k = 0; k < 2; ++k) dst[n][k] = *(const LAS h8*)(lds + G_SB(b, h) + boff + n * 2048 + k * 1024); } while (0)
; #define G_MMA(ai, bj, At, Bt) do { __builtin_amdgcn_s_setprio(1); _Pragma("unroll") for (int m = 0; m < 4; ++m) _Pragma("unroll") for (int n = 0; n < 2; ++n) _Pragma("unroll") for (int k = 0; k < 2; ++k) \
;     acc[ai][bj][m][n] = __builtin_amdgcn_mfma_f32_16x16x32_f16(Bt[n][k], At[m][k], acc[ai][bj][m][n], 0, 0, 0); __builtin_amdgcn_s_setprio(0); } while (0)
; #define G_WAIT_V(n) asm volatile("s_waitcnt vmcnt(" #n ")" ::: "memory")
; #define G_WAIT_L(n) asm volatile("s_waitcnt lgkmcnt(" #n ")" ::: "memory")
; #define G_BAR __builtin_amdgcn_s_barrier()
; #define G_SCHED __builtin_amdgcn_sched_barrier(0)
; template <bool PERM, class Sched, class Epi>
; DI void gemm256(LAS unsigned char* lds, const Sched& S, const Epi& E, int wv_) {
;     ...
;       G_LDB(B1, 1, 1); G_STAGE(G_SB(1, 0), b3, cvB0, cvB1);
;       G_BAR; G_WAIT_L(0); G_MMA(0, 1, At, B1); G_BAR;
;       G_LDA(At, 1, 1); G_STAGE(G_SA(1, 0), a3, cvA0, cvA1);
;       G_BAR; G_WAIT_L(0); G_MMA(1, 0, At, B0); G_BAR; G_SCHED;
;       G_STAGE(G_SB(1, 1), b3 + chB, cvB0, cvB1);
;       G_WAIT_V(6); G_BAR; G_MMA(1, 1, At, B1); G_BAR;
;     }
	s_waitcnt lgkmcnt(0)
	s_waitcnt lgkmcnt(0)
	v_mfma_f32_16x16x32_f16 v[118:121], v[192:195], v[146:149], v[118:121]
	v_mfma_f32_16x16x32_f16 v[114:117], v[200:203], v[146:149], v[114:117]
	v_mfma_f32_16x16x32_f16 v[102:105], v[192:195], v[168:171], v[102:105]
	v_mfma_f32_16x16x32_f16 v[98:101], v[200:203], v[168:171], v[98:101]
	v_mfma_f32_16x16x32_f16 v[86:89], v[192:195], v[176:179], v[86:89]
	v_mfma_f32_16x16x32_f16 v[82:85], v[200:203], v[176:179], v[82:85]
	v_mfma_f32_16x16x32_f16 v[70:73], v[192:195], v[184:187], v[70:73]
	v_mfma_f32_16x16x32_f16 v[66:69], v[200:203], v[184:187], v[66:69]
	v_mfma_f32_16x16x32_f16 v[118:121], v[196:199], v[164:167], v[118:121]
	v_mfma_f32_16x16x32_f16 v[114:117], v[204:207], v[164:167], v[114:117]
	v_mfma_f32_16x16x32_f16 v[102:105], v[196:199], v[172:175], v[102:105]
	v_mfma_f32_16x16x32_f16 v[98:101], v[204:207], v[172:175], v[98:101]
	v_mfma_f32_16x16x32_f16 v[86:89], v[196:199], v[180:183], v[86:89]
	v_mfma_f32_16x16x32_f16 v[82:85], v[204:207], v[180:183], v[82:85]
	v_mfma_f32_16x16x32_f16 v[70:73], v[196:199], v[188:191], v[70:73]
	v_mfma_f32_16x16x32_f16 v[66:69], v[204:207], v[188:191], v[66:69]
	s_mov_b32 m0, s79
	v_lshl_add_u64 v[208:209], v[212:213], 0, s[86:87]
	s_barrier
	ds_read_b128 v[146:149], v1 offset:49152
	ds_read_b128 v[164:167], v1 offset:50176
	ds_read_b128 v[168:171], v1 offset:51200
	ds_read_b128 v[172:175], v1 offset:52224
	ds_read_b128 v[176:179], v1 offset:53248
	ds_read_b128 v[180:183], v1 offset:54272
	ds_read_b128 v[184:187], v1 offset:55296
	ds_read_b128 v[188:191], v1 offset:56320
	global_load_lds_dwordx4 v[208:209], off
	s_mov_b32 m0, s83
	v_lshl_add_u64 v[208:209], v[214:215], 0, s[86:87]
	global_load_lds_dwordx4 v[208:209], off
	s_barrier
	s_waitcnt lgkmcnt(0)
	s_waitcnt lgkmcnt(0)
	v_mfma_f32_16x16x32_f16 v[62:65], v[130:133], v[146:149], v[62:65]
	v_mfma_f32_16x16x32_f16 v[58:61], v[138:141], v[146:149], v[58:61]
	v_mfma_f32_16x16x32_f16 v[46:49], v[130:133], v[168:171], v[46:49]
	v_mfma_f32_16x16x32_f16 v[42:45], v[138:141], v[168:171], v[42:45]
	v_mfma_f32_16x16x32_f16 v[30:33], v[130:133], v[176:179], v[30:33]
	v_mfma_f32_16x16x32_f16 v[26:29], v[138:141], v[176:179], v[26:29]
	v_mfma_f32_16x16x32_f16 v[14:17], v[130:133], v[184:187], v[14:17]
	v_mfma_f32_16x16x32_f16 v[10:13], v[138:141], v[184:187], v[10:13]
	v_mfma_f32_16x16x32_f16 v[62:65], v[134:137], v[164:167], v[62:65]
	v_mfma_f32_16x16x32_f16 v[58:61], v[142:145], v[164:167], v[58:61]
	v_mfma_f32_16x16x32_f16 v[46:49], v[134:137], v[172:175], v[46:49]
	v_mfma_f32_16x16x32_f16 v[42:45], v[142:145], v[172:175], v[42:45]
	v_mfma_f32_16x16x32_f16 v[30:33], v[134:137], v[180:183], v[30:33]
	v_mfma_f32_16x16x32_f16 v[26:29], v[142:145], v[180:183], v[26:29]
	v_mfma_f32_16x16x32_f16 v[14:17], v[134:137], v[188:191], v[14:17]
	v_mfma_f32_16x16x32_f16 v[10:13], v[142:145], v[188:191], v[10:13]
	s_barrier
	s_add_u32 s20, s20, 0x40080
	s_addc_u32 s21, s21, 0
	s_mov_b32 m0, s90
	v_lshl_add_u64 v[130:131], s[20:21], 0, v[150:151]
	global_load_lds_dwordx4 v[130:131], off
	s_mov_b32 m0, s93
	v_lshl_add_u64 v[130:131], s[20:21], 0, v[152:153]
	global_load_lds_dwordx4 v[130:131], off
	s_waitcnt vmcnt(6)
	s_barrier
	v_mfma_f32_16x16x32_f16 v[54:57], v[192:195], v[146:149], v[54:57]
	v_mfma_f32_16x16x32_f16 v[50:53], v[200:203], v[146:149], v[50:53]
	v_mfma_f32_16x16x32_f16 v[38:41], v[192:195], v[168:171], v[38:41]
	v_mfma_f32_16x16x32_f16 v[34:37], v[200:203], v[168:171], v[34:37]
	v_mfma_f32_16x16x32_f16 v[22:25], v[192:195], v[176:179], v[22:25]
	v_mfma_f32_16x16x32_f16 v[18:21], v[200:203], v[176:179], v[18:21]
	v_mfma_f32_16x16x32_f16 v[6:9], v[192:195], v[184:187], v[6:9]
	v_mfma_f32_16x16x32_f16 v[2:5], v[200:203], v[184:187], v[2:5]
	v_mfma_f32_16x16x32_f16 v[54:57], v[196:199], v[164:167], v[54:57]
	v_mfma_f32_16x16x32_f16 v[50:53], v[204:207], v[164:167], v[50:53]
	v_mfma_f32_16x16x32_f16 v[38:41], v[196:199], v[172:175], v[38:41]
	v_mfma_f32_16x16x32_f16 v[34:37], v[204:207], v[172:175], v[34:37]
	v_mfma_f32_16x16x32_f16 v[22:25], v[196:199], v[180:183], v[22:25]
	v_mfma_f32_16x16x32_f16 v[18:21], v[204:207], v[180:183], v[18:21]
	v_mfma_f32_16x16x32_f16 v[6:9], v[196:199], v[188:191], v[6:9]
	v_mfma_f32_16x16x32_f16 v[2:5], v[204:207], v[188:191], v[2:5]
	s_add_u32 s18, s18, 0x100
	s_addc_u32 s19, s19, 0
	s_add_u32 s75, s75, 0x100
	s_addc_u32 s46, s46, 0
	s_cmp_ge_i32 s74, s25
	s_mov_b32 s20, s74
	s_barrier
	s_cbranch_scc0 .LBB0_2433
	s_mov_b32 s56, 0x8fff
	s_branch .LBB0_2436

; #define G_STAGE(bufoff, gbase, v0, v1) do { \
;     __builtin_amdgcn_global_load_lds((const unsigned*)((const char*)(gbase) + (v0)), (LAS unsigned*)(lds + (bufoff) + ldsw), 16, 0, 0); \
;     __builtin_amdgcn_global_load_lds((const unsigned*)((const char*)(gbase) + (v1)), (LAS unsigned*)(lds + (bufoff) + ldsw + 8192), 16, 0, 0); } while (0)
; #define G_LDA(dst, b, h) do { _Pragma("unroll") for (int m = 0; m < 4; ++m) _Pragma("unroll") for (int k = 0; k < 2; ++k) dst[m][k] = *(const LAS h8*)(lds + G_SA(b, h) + aoff + m * 2048 + k * 1024); } while (0)
; #define G_LDB(dst, b, h) do { _Pragma("unroll") for (int n = 0; n < 2; ++n) _Pragma("unroll") for (int k = 0; k < 2; ++k) dst[n][k] = *(const LAS h8*)(lds + G_SB(b, h) + boff + n * 2048 + k * 1024); } while (0)
; #define G_MMA(ai, bj, At, Bt) do { __builtin_amdgcn_s_setprio(1); _Pragma("unroll") for (int m = 0; m < 4; ++m) _Pragma("unroll") for (int n = 0; n < 2; ++n) _Pragma("unroll") for (int k = 0; k < 2; ++k) \
;     acc[ai][bj][m][n] = __builtin_amdgcn_mfma_f32_16x16x32_f16(Bt[n][k], At[m][k], acc[ai][bj][m][n], 0, 0, 0); __builtin_amdgcn_s_setprio(0); } while (0)
; #define G_WAIT_V(n) asm volatile("s_waitcnt vmcnt(" #n ")" ::: "memory")
; #define G_WAIT_L(n) asm volatile("s_waitcnt lgkmcnt(" #n ")" ::: "memory")
; #define G_BAR __builtin_amdgcn_s_barrier()
; #define G_SCHED __builtin_amdgcn_sched_barrier(0)
; template <bool PERM, class Sched, class Epi>
; DI void gemm256(LAS unsigned char* lds, const Sched& S, const Epi& E, int wv_) {
;     ...
;       const bool last = (t == nt - 2);
;       const char* a1 = cA + (size_t)(t + 1) * kstep;
;       const char* a2 = last ? nA : cA + (size_t)(t + 2) * kstep;
;       const char* b2 = last ? nB : cB + (size_t)(t + 2) * kstep;
;       const char* a3 = a2 + kstep;
;       const char* b3 = b2 + kstep;
;       G_LDB(B0, 0, 0); G_SCHED; G_LDA(At, 0, 0); G_STAGE(G_SA(1, 1), a1 + chA, cvA0, cvA1);
;       G_WAIT_L(8); G_BAR; G_WAIT_L(0); G_MMA(0, 0, At, B0); G_BAR; G_SCHED;
;       G_LDB(B1, 0, 1); G_STAGE(G_SB(0, 0), b2, cvB0, cvB1);
;       G_BAR; G_WAIT_L(0); G_MMA(0, 1, At, B1); G_BAR;
;       G_LDA(At, 0, 1); G_STAGE(G_SA(0, 0), a2, cvA0, cvA1);
;       G_BAR; G_WAIT_L(0); G_MMA(1, 0, At, B0); G_BAR; G_SCHED;
;       G_STAGE(G_SB(0, 1), b2 + chB, cvB0, cvB1);
;       G_WAIT_V(6); G_BAR; G_MMA(1, 1, At, B1); G_BAR;
.LBB0_2581:
	s_add_i32 s68, s14, 2
	ds_read_b128 v[144:147], v216
	ds_read_b128 v[148:151], v216 offset:1024
	ds_read_b128 v[152:155], v216 offset:2048
	ds_read_b128 v[156:159], v216 offset:3072
	v_lshl_add_u64 v[192:193], s[12:13], 0, v[138:139]
	s_add_i32 m0, s24, 0xc000
	ds_read_b128 v[160:163], v1
	ds_read_b128 v[164:167], v1 offset:1024
	ds_read_b128 v[168:171], v1 offset:2048
	ds_read_b128 v[172:175], v1 offset:3072
	ds_read_b128 v[176:179], v1 offset:4096
	ds_read_b128 v[180:183], v1 offset:5120
	ds_read_b128 v[184:187], v1 offset:6144
	ds_read_b128 v[188:191], v1 offset:7168
	global_load_lds_dwordx4 v[192:193], off
	s_add_i32 m0, s24, 0xe000
	v_lshl_add_u64 v[192:193], s[12:13], 0, v[140:141]
	global_load_lds_dwordx4 v[192:193], off
	s_waitcnt lgkmcnt(8)
	s_barrier
	s_waitcnt lgkmcnt(0)
	s_waitcnt lgkmcnt(0)
	v_mfma_f32_16x16x32_f16 v[126:129], v[144:147], v[160:163], v[126:129]
	s_add_u32 s15, s12, 0xfffc0080
	s_addc_u32 s16, s13, -1
	s_cmp_eq_u32 s11, s14
	s_cselect_b32 s14, s8, s66
	s_cselect_b32 s17, s7, s16
	s_cselect_b32 s16, s6, s15
	s_cselect_b32 s15, s9, s46
	v_mfma_f32_16x16x32_f16 v[122:125], v[152:155], v[160:163], v[122:125]
	v_mfma_f32_16x16x32_f16 v[110:113], v[144:147], v[168:171], v[110:113]
	v_mfma_f32_16x16x32_f16 v[106:109], v[152:155], v[168:171], v[106:109]
	v_mfma_f32_16x16x32_f16 v[94:97], v[144:147], v[176:179], v[94:97]
	v_mfma_f32_16x16x32_f16 v[90:93], v[152:155], v[176:179], v[90:93]
	v_mfma_f32_16x16x32_f16 v[78:81], v[144:147], v[184:187], v[78:81]
	v_mfma_f32_16x16x32_f16 v[74:77], v[152:155], v[184:187], v[74:77]
	v_mfma_f32_16x16x32_f16 v[126:129], v[148:151], v[164:167], v[126:129]
	v_mfma_f32_16x16x32_f16 v[122:125], v[156:159], v[164:167], v[122:125]
	v_mfma_f32_16x16x32_f16 v[110:113], v[148:151], v[172:175], v[110:113]
	v_mfma_f32_16x16x32_f16 v[106:109], v[156:159], v[172:175], v[106:109]
	v_mfma_f32_16x16x32_f16 v[94:97], v[148:151], v[180:183], v[94:97]
	v_mfma_f32_16x16x32_f16 v[90:93], v[156:159], v[180:183], v[90:93]
	v_mfma_f32_16x16x32_f16 v[78:81], v[148:151], v[188:191], v[78:81]
	v_mfma_f32_16x16x32_f16 v[74:77], v[156:159], v[188:191], v[74:77]
	s_barrier
	s_mov_b32 m0, s25
	v_lshl_add_u64 v[208:209], s[14:15], 0, v[132:133]
	ds_read_b128 v[192:195], v217
	ds_read_b128 v[196:199], v217 offset:1024
	ds_read_b128 v[200:203], v217 offset:2048
	ds_read_b128 v[204:207], v217 offset:3072
	global_load_lds_dwordx4 v[208:209], off
	s_mov_b32 m0, s26
	v_lshl_add_u64 v[210:211], s[14:15], 0, v[136:137]
	global_load_lds_dwordx4 v[210:211], off
	s_barrier
	s_waitcnt lgkmcnt(0)
	s_waitcnt lgkmcnt(0)
	v_mfma_f32_16x16x32_f16 v[118:121], v[192:195], v[160:163], v[118:121]
	v_mfma_f32_16x16x32_f16 v[114:117], v[200:203], v[160:163], v[114:117]
	v_mfma_f32_16x16x32_f16 v[102:105], v[192:195], v[168:171], v[102:105]
	v_mfma_f32_16x16x32_f16 v[98:101], v[200:203], v[168:171], v[98:101]
	v_mfma_f32_16x16x32_f16 v[86:89], v[192:195], v[176:179], v[86:89]
	v_mfma_f32_16x16x32_f16 v[82:85], v[200:203], v[176:179], v[82:85]
	v_mfma_f32_16x16x32_f16 v[70:73], v[192:195], v[184:187], v[70:73]
	v_mfma_f32_16x16x32_f16 v[66:69], v[200:203], v[184:187], v[66:69]
	v_mfma_f32_16x16x32_f16 v[118:121], v[196:199], v[164:167], v[118:121]
	v_mfma_f32_16x16x32_f16 v[114:117], v[204:207], v[164:167], v[114:117]
	v_mfma_f32_16x16x32_f16 v[102:105], v[196:199], v[172:175], v[102:105]
	v_mfma_f32_16x16x32_f16 v[98:101], v[204:207], v[172:175], v[98:101]
	v_mfma_f32_16x16x32_f16 v[86:89], v[196:199], v[180:183], v[86:89]
	v_mfma_f32_16x16x32_f16 v[82:85], v[204:207], v[180:183], v[82:85]
	v_mfma_f32_16x16x32_f16 v[70:73], v[196:199], v[188:191], v[70:73]
	v_mfma_f32_16x16x32_f16 v[66:69], v[204:207], v[188:191], v[66:69]
	s_mov_b32 m0, s24
	v_lshl_add_u64 v[212:213], s[16:17], 0, v[130:131]
	s_barrier
	ds_read_b128 v[160:163], v1 offset:16384
	ds_read_b128 v[164:167], v1 offset:17408
	ds_read_b128 v[168:171], v1 offset:18432
	ds_read_b128 v[172:175], v1 offset:19456
	ds_read_b128 v[176:179], v1 offset:20480
	ds_read_b128 v[180:183], v1 offset:21504
	ds_read_b128 v[184:187], v1 offset:22528
	ds_read_b128 v[188:191], v1 offset:23552
	global_load_lds_dwordx4 v[212:213], off
	s_mov_b32 m0, s27
	v_lshl_add_u64 v[214:215], s[16:17], 0, v[134:135]
	global_load_lds_dwordx4 v[214:215], off
	s_barrier
	s_waitcnt lgkmcnt(0)
	s_waitcnt lgkmcnt(0)
	v_mfma_f32_16x16x32_f16 v[62:65], v[144:147], v[160:163], v[62:65]
	v_mfma_f32_16x16x32_f16 v[58:61], v[152:155], v[160:163], v[58:61]
	v_mfma_f32_16x16x32_f16 v[46:49], v[144:147], v[168:171], v[46:49]
	v_mfma_f32_16x16x32_f16 v[42:45], v[152:155], v[168:171], v[42:45]
	v_mfma_f32_16x16x32_f16 v[30:33], v[144:147], v[176:179], v[30:33]
	v_mfma_f32_16x16x32_f16 v[26:29], v[152:155], v[176:179], v[26:29]
	v_mfma_f32_16x16x32_f16 v[14:17], v[144:147], v[184:187], v[14:17]
	v_mfma_f32_16x16x32_f16 v[10:13], v[152:155], v[184:187], v[10:13]
	v_mfma_f32_16x16x32_f16 v[62:65], v[148:151], v[164:167], v[62:65]
	v_mfma_f32_16x16x32_f16 v[58:61], v[156:159], v[164:167], v[58:61]
	v_mfma_f32_16x16x32_f16 v[46:49], v[148:151], v[172:175], v[46:49]
	v_mfma_f32_16x16x32_f16 v[42:45], v[156:159], v[172:175], v[42:45]
	v_mfma_f32_16x16x32_f16 v[30:33], v[148:151], v[180:183], v[30:33]
	v_mfma_f32_16x16x32_f16 v[26:29], v[156:159], v[180:183], v[26:29]
	v_mfma_f32_16x16x32_f16 v[14:17], v[148:151], v[188:191], v[14:17]
	v_mfma_f32_16x16x32_f16 v[10:13], v[156:159], v[188:191], v[10:13]
	s_barrier
	s_add_u32 s40, s14, 0x40000
	s_addc_u32 s41, s15, 0
	s_mov_b32 m0, s28
	v_lshl_add_u64 v[144:145], s[40:41], 0, v[132:133]
	global_load_lds_dwordx4 v[144:145], off
	s_mov_b32 m0, s29
	v_lshl_add_u64 v[144:145], s[40:41], 0, v[136:137]
	global_load_lds_dwordx4 v[144:145], off
	s_waitcnt vmcnt(6)
	s_barrier
; #define G_STAGE(bufoff, gbase, v0, v1) do { \
;     __builtin_amdgcn_global_load_lds((const unsigned*)((const char*)(gbase) + (v0)), (LAS unsigned*)(lds + (bufoff) + ldsw), 16, 0, 0); \
;     __builtin_amdgcn_global_load_lds((const unsigned*)((const char*)(gbase) + (v1)), (LAS unsigned*)(lds + (bufoff) + ldsw + 8192), 16, 0, 0); } while (0)
; #define G_LDA(dst, b, h) do { _Pragma("unroll") for (int m = 0; m < 4; ++m) _Pragma("unroll") for (int k = 0; k < 2; ++k) dst[m][k] = *(const LAS h8*)(lds + G_SA(b, h) + aoff + m * 2048 + k * 1024); } while (0)
; #define G_LDB(dst, b, h) do { _Pragma("unroll") for (int n = 0; n < 2; ++n) _Pragma("unroll") for (int k = 0; k < 2; ++k) dst[n][k] = *(const LAS h8*)(lds + G_SB(b, h) + boff + n * 2048 + k * 1024); } while (0)
; #define G_MMA(ai, bj, At, Bt) do { __builtin_amdgcn_s_setprio(1); _Pragma("unroll") for (int m = 0; m < 4; ++m) _Pragma("unroll") for (int n = 0; n < 2; ++n) _Pragma("unroll") for (int k = 0; k < 2; ++k) \
;     acc[ai][bj][m][n] = __builtin_amdgcn_mfma_f32_16x16x32_f16(Bt[n][k], At[m][k], acc[ai][bj][m][n], 0, 0, 0); __builtin_amdgcn_s_setprio(0); } while (0)
; #define G_WAIT_V(n) asm volatile("s_waitcnt vmcnt(" #n ")" ::: "memory")
; #define G_WAIT_L(n) asm volatile("s_waitcnt lgkmcnt(" #n ")" ::: "memory")
; #define G_BAR __builtin_amdgcn_s_barrier()
; #define G_SCHED __builtin_amdgcn_sched_barrier(0)
; template <bool PERM, class Sched, class Epi>
; DI void gemm256(LAS unsigned char* lds, const Sched& S, const Epi& E, int wv_) {
;     ...
;       G_WAIT_V(6); G_BAR; G_MMA(1, 1, At, B1); G_BAR;
;       G_LDB(B0, 1, 0); G_SCHED; G_LDA(At, 1, 0); G_STAGE(G_SA(0, 1), a2 + chA, cvA0, cvA1);
;       G_WAIT_L(8); G_BAR; G_WAIT_L(0); G_MMA(0, 0, At, B0); G_BAR; G_SCHED;
;       G_LDB(B1, 1, 1); G_STAGE(G_SB(1, 0), b3, cvB0, cvB1);
	v_mfma_f32_16x16x32_f16 v[54:57], v[192:195], v[160:163], v[54:57]
	v_mfma_f32_16x16x32_f16 v[50:53], v[200:203], v[160:163], v[50:53]
	v_mfma_f32_16x16x32_f16 v[38:41], v[192:195], v[168:171], v[38:41]
	v_mfma_f32_16x16x32_f16 v[34:37], v[200:203], v[168:171], v[34:37]
	v_mfma_f32_16x16x32_f16 v[22:25], v[192:195], v[176:179], v[22:25]
	v_mfma_f32_16x16x32_f16 v[18:21], v[200:203], v[176:179], v[18:21]
	v_mfma_f32_16x16x32_f16 v[6:9], v[192:195], v[184:187], v[6:9]
	v_mfma_f32_16x16x32_f16 v[2:5], v[200:203], v[184:187], v[2:5]
	v_mfma_f32_16x16x32_f16 v[54:57], v[196:199], v[164:167], v[54:57]
	v_mfma_f32_16x16x32_f16 v[50:53], v[204:207], v[164:167], v[50:53]
	v_mfma_f32_16x16x32_f16 v[38:41], v[196:199], v[172:175], v[38:41]
	v_mfma_f32_16x16x32_f16 v[34:37], v[204:207], v[172:175], v[34:37]
	v_mfma_f32_16x16x32_f16 v[22:25], v[196:199], v[180:183], v[22:25]
	v_mfma_f32_16x16x32_f16 v[18:21], v[204:207], v[180:183], v[18:21]
	v_mfma_f32_16x16x32_f16 v[6:9], v[196:199], v[188:191], v[6:9]
	v_mfma_f32_16x16x32_f16 v[2:5], v[204:207], v[188:191], v[2:5]
	s_barrier
	ds_read_b128 v[144:147], v218
	ds_read_b128 v[148:151], v218 offset:1024
	ds_read_b128 v[152:155], v218 offset:2048
	ds_read_b128 v[156:159], v218 offset:3072
	s_add_u32 s16, s16, 0x40000
	s_addc_u32 s17, s17, 0
	s_mov_b32 m0, s30
	v_lshl_add_u64 v[192:193], s[16:17], 0, v[130:131]
	ds_read_b128 v[160:163], v1 offset:32768
	ds_read_b128 v[164:167], v1 offset:33792
	ds_read_b128 v[168:171], v1 offset:34816
	ds_read_b128 v[172:175], v1 offset:35840
	ds_read_b128 v[176:179], v1 offset:36864
	ds_read_b128 v[180:183], v1 offset:37888
	ds_read_b128 v[184:187], v1 offset:38912
	ds_read_b128 v[188:191], v1 offset:39936
	global_load_lds_dwordx4 v[192:193], off
	s_mov_b32 m0, s31
	v_lshl_add_u64 v[192:193], s[16:17], 0, v[134:135]
	global_load_lds_dwordx4 v[192:193], off
	s_waitcnt lgkmcnt(8)
	s_barrier
	s_waitcnt lgkmcnt(0)
	s_waitcnt lgkmcnt(0)
	v_mfma_f32_16x16x32_f16 v[126:129], v[144:147], v[160:163], v[126:129]
	v_mfma_f32_16x16x32_f16 v[122:125], v[152:155], v[160:163], v[122:125]
	v_mfma_f32_16x16x32_f16 v[110:113], v[144:147], v[168:171], v[110:113]
	v_mfma_f32_16x16x32_f16 v[106:109], v[152:155], v[168:171], v[106:109]
	v_mfma_f32_16x16x32_f16 v[94:97], v[144:147], v[176:179], v[94:97]
	v_mfma_f32_16x16x32_f16 v[90:93], v[152:155], v[176:179], v[90:93]
	v_mfma_f32_16x16x32_f16 v[78:81], v[144:147], v[184:187], v[78:81]
	v_mfma_f32_16x16x32_f16 v[74:77], v[152:155], v[184:187], v[74:77]
	v_mfma_f32_16x16x32_f16 v[126:129], v[148:151], v[164:167], v[126:129]
	v_mfma_f32_16x16x32_f16 v[122:125], v[156:159], v[164:167], v[122:125]
	v_mfma_f32_16x16x32_f16 v[110:113], v[148:151], v[172:175], v[110:113]
	v_mfma_f32_16x16x32_f16 v[106:109], v[156:159], v[172:175], v[106:109]
	v_mfma_f32_16x16x32_f16 v[94:97], v[148:151], v[180:183], v[94:97]
	v_mfma_f32_16x16x32_f16 v[90:93], v[156:159], v[180:183], v[90:93]
	v_mfma_f32_16x16x32_f16 v[78:81], v[148:151], v[188:191], v[78:81]
	v_mfma_f32_16x16x32_f16 v[74:77], v[156:159], v[188:191], v[74:77]
	s_barrier
	s_mov_b32 m0, s35
	v_lshl_add_u64 v[208:209], v[208:209], 0, s[86:87]
	ds_read_b128 v[192:195], v219
	ds_read_b128 v[196:199], v219 offset:1024
	ds_read_b128 v[200:203], v219 offset:2048
	ds_read_b128 v[204:207], v219 offset:3072
	global_load_lds_dwordx4 v[208:209], off
	s_mov_b32 m0, s36
	v_lshl_add_u64 v[208:209], v[210:211], 0, s[86:87]
	global_load_lds_dwordx4 v[208:209], off
	s_barrier
; #define G_STAGE(bufoff, gbase, v0, v1) do { \
;     __builtin_amdgcn_global_load_lds((const unsigned*)((const char*)(gbase) + (v0)), (LAS unsigned*)(lds + (bufoff) + ldsw), 16, 0, 0); \
;     __builtin_amdgcn_global_load_lds((const unsigned*)((const char*)(gbase) + (v1)), (LAS unsigned*)(lds + (bufoff) + ldsw + 8192), 16, 0, 0); } while (0)
; #define G_LDA(dst, b, h) do { _Pragma("unroll") for (int m = 0; m < 4; ++m) _Pragma("unroll") for (int k = 0; k < 2; ++k) dst[m][k] = *(const LAS h8*)(lds + G_SA(b, h) + aoff + m * 2048 + k * 1024); } while (0)
; #define G_LDB(dst, b, h) do { _Pragma("unroll") for (int n = 0; n < 2; ++n) _Pragma("unroll") for (int k = 0; k < 2; ++k) dst[n][k] = *(const LAS h8*)(lds + G_SB(b, h) + boff + n * 2048 + k * 1024); } while (0)
; #define G_MMA(ai, bj, At, Bt) do { __builtin_amdgcn_s_setprio(1); _Pragma("unroll") for (int m = 0; m < 4; ++m) _Pragma("unroll") for (int n = 0; n < 2; ++n) _Pragma("unroll") for (int k = 0; k < 2; ++k) \
;     acc[ai][bj][m][n] = __builtin_amdgcn_mfma_f32_16x16x32_f16(Bt[n][k], At[m][k], acc[ai][bj][m][n], 0, 0, 0); __builtin_amdgcn_s_setprio(0); } while (0)
; #define G_WAIT_V(n) asm volatile("s_waitcnt vmcnt(" #n ")" ::: "memory")
; #define G_WAIT_L(n) asm volatile("s_waitcnt lgkmcnt(" #n ")" ::: "memory")
; #define G_BAR __builtin_amdgcn_s_barrier()
; #define G_SCHED __builtin_amdgcn_sched_barrier(0)
; template <bool PERM, class Sched, class Epi>
; DI void gemm256(LAS unsigned char* lds, const Sched& S, const Epi& E, int wv_) {
;     ...
;       G_LDB(B1, 1, 1); G_STAGE(G_SB(1, 0), b3, cvB0, cvB1);
;       G_BAR; G_WAIT_L(0); G_MMA(0, 1, At, B1); G_BAR;
;       G_LDA(At, 1, 1); G_STAGE(G_SA(1, 0), a3, cvA0, cvA1);
;       G_BAR; G_WAIT_L(0); G_MMA(1, 0, At, B0); G_BAR; G_SCHED;
;       G_STAGE(G_SB(1, 1), b3 + chB, cvB0, cvB1);
;       G_WAIT_V(6); G_BAR; G_MMA(1, 1, At, B1); G_BAR;
;     }
	s_waitcnt lgkmcnt(0)
	s_waitcnt lgkmcnt(0)
	v_mfma_f32_16x16x32_f16 v[118:121], v[192:195], v[160:163], v[118:121]
	v_mfma_f32_16x16x32_f16 v[114:117], v[200:203], v[160:163], v[114:117]
	v_mfma_f32_16x16x32_f16 v[102:105], v[192:195], v[168:171], v[102:105]
	v_mfma_f32_16x16x32_f16 v[98:101], v[200:203], v[168:171], v[98:101]
	v_mfma_f32_16x16x32_f16 v[86:89], v[192:195], v[176:179], v[86:89]
	v_mfma_f32_16x16x32_f16 v[82:85], v[200:203], v[176:179], v[82:85]
	v_mfma_f32_16x16x32_f16 v[70:73], v[192:195], v[184:187], v[70:73]
	v_mfma_f32_16x16x32_f16 v[66:69], v[200:203], v[184:187], v[66:69]
	v_mfma_f32_16x16x32_f16 v[118:121], v[196:199], v[164:167], v[118:121]
	v_mfma_f32_16x16x32_f16 v[114:117], v[204:207], v[164:167], v[114:117]
	v_mfma_f32_16x16x32_f16 v[102:105], v[196:199], v[172:175], v[102:105]
	v_mfma_f32_16x16x32_f16 v[98:101], v[204:207], v[172:175], v[98:101]
	v_mfma_f32_16x16x32_f16 v[86:89], v[196:199], v[180:183], v[86:89]
	v_mfma_f32_16x16x32_f16 v[82:85], v[204:207], v[180:183], v[82:85]
	v_mfma_f32_16x16x32_f16 v[70:73], v[196:199], v[188:191], v[70:73]
	v_mfma_f32_16x16x32_f16 v[66:69], v[204:207], v[188:191], v[66:69]
	s_mov_b32 m0, s37
	v_lshl_add_u64 v[208:209], v[212:213], 0, s[86:87]
	s_barrier
	ds_read_b128 v[160:163], v1 offset:49152
	ds_read_b128 v[164:167], v1 offset:50176
	ds_read_b128 v[168:171], v1 offset:51200
	ds_read_b128 v[172:175], v1 offset:52224
	ds_read_b128 v[176:179], v1 offset:53248
	ds_read_b128 v[180:183], v1 offset:54272
	ds_read_b128 v[184:187], v1 offset:55296
	ds_read_b128 v[188:191], v1 offset:56320
	global_load_lds_dwordx4 v[208:209], off
	s_mov_b32 m0, s52
	v_lshl_add_u64 v[208:209], v[214:215], 0, s[86:87]
	global_load_lds_dwordx4 v[208:209], off
	s_barrier
	s_waitcnt lgkmcnt(0)
	s_waitcnt lgkmcnt(0)
	v_mfma_f32_16x16x32_f16 v[62:65], v[144:147], v[160:163], v[62:65]
	v_mfma_f32_16x16x32_f16 v[58:61], v[152:155], v[160:163], v[58:61]
	v_mfma_f32_16x16x32_f16 v[46:49], v[144:147], v[168:171], v[46:49]
	v_mfma_f32_16x16x32_f16 v[42:45], v[152:155], v[168:171], v[42:45]
	v_mfma_f32_16x16x32_f16 v[30:33], v[144:147], v[176:179], v[30:33]
	v_mfma_f32_16x16x32_f16 v[26:29], v[152:155], v[176:179], v[26:29]
	v_mfma_f32_16x16x32_f16 v[14:17], v[144:147], v[184:187], v[14:17]
	v_mfma_f32_16x16x32_f16 v[10:13], v[152:155], v[184:187], v[10:13]
	v_mfma_f32_16x16x32_f16 v[62:65], v[148:151], v[164:167], v[62:65]
	v_mfma_f32_16x16x32_f16 v[58:61], v[156:159], v[164:167], v[58:61]
	v_mfma_f32_16x16x32_f16 v[46:49], v[148:151], v[172:175], v[46:49]
	v_mfma_f32_16x16x32_f16 v[42:45], v[156:159], v[172:175], v[42:45]
	v_mfma_f32_16x16x32_f16 v[30:33], v[148:151], v[180:183], v[30:33]
	v_mfma_f32_16x16x32_f16 v[26:29], v[156:159], v[180:183], v[26:29]
	v_mfma_f32_16x16x32_f16 v[14:17], v[148:151], v[188:191], v[14:17]
	v_mfma_f32_16x16x32_f16 v[10:13], v[156:159], v[188:191], v[10:13]
	s_barrier
	s_add_u32 s14, s14, 0x40080
	s_addc_u32 s15, s15, 0
	s_mov_b32 m0, s53
	v_lshl_add_u64 v[144:145], s[14:15], 0, v[132:133]
	global_load_lds_dwordx4 v[144:145], off
	s_mov_b32 m0, s56
	v_lshl_add_u64 v[144:145], s[14:15], 0, v[136:137]
	global_load_lds_dwordx4 v[144:145], off
	s_waitcnt vmcnt(6)
	s_barrier
	v_mfma_f32_16x16x32_f16 v[54:57], v[192:195], v[160:163], v[54:57]
	v_mfma_f32_16x16x32_f16 v[50:53], v[200:203], v[160:163], v[50:53]
	v_mfma_f32_16x16x32_f16 v[38:41], v[192:195], v[168:171], v[38:41]
	v_mfma_f32_16x16x32_f16 v[34:37], v[200:203], v[168:171], v[34:37]
	v_mfma_f32_16x16x32_f16 v[22:25], v[192:195], v[176:179], v[22:25]
	v_mfma_f32_16x16x32_f16 v[18:21], v[200:203], v[176:179], v[18:21]
	v_mfma_f32_16x16x32_f16 v[6:9], v[192:195], v[184:187], v[6:9]
	v_mfma_f32_16x16x32_f16 v[2:5], v[200:203], v[184:187], v[2:5]
	v_mfma_f32_16x16x32_f16 v[54:57], v[196:199], v[164:167], v[54:57]
	v_mfma_f32_16x16x32_f16 v[50:53], v[204:207], v[164:167], v[50:53]
	v_mfma_f32_16x16x32_f16 v[38:41], v[196:199], v[172:175], v[38:41]
	v_mfma_f32_16x16x32_f16 v[34:37], v[204:207], v[172:175], v[34:37]
	v_mfma_f32_16x16x32_f16 v[22:25], v[196:199], v[180:183], v[22:25]
	v_mfma_f32_16x16x32_f16 v[18:21], v[204:207], v[180:183], v[18:21]
	v_mfma_f32_16x16x32_f16 v[6:9], v[196:199], v[188:191], v[6:9]
	v_mfma_f32_16x16x32_f16 v[2:5], v[204:207], v[188:191], v[2:5]
	s_add_u32 s12, s12, 0x100
	s_addc_u32 s13, s13, 0
	s_add_u32 s66, s66, 0x100
	s_addc_u32 s46, s46, 0
	s_cmp_ge_i32 s68, s5
	s_mov_b32 s14, s68
	s_barrier
	s_cbranch_scc0 .LBB0_2581
	s_branch .LBB0_2583

; #define G_STAGE(bufoff, gbase, v0, v1) do { \
;     __builtin_amdgcn_global_load_lds((const unsigned*)((const char*)(gbase) + (v0)), (LAS unsigned*)(lds + (bufoff) + ldsw), 16, 0, 0); \
;     __builtin_amdgcn_global_load_lds((const unsigned*)((const char*)(gbase) + (v1)), (LAS unsigned*)(lds + (bufoff) + ldsw + 8192), 16, 0, 0); } while (0)
; #define G_LDA(dst, b, h) do { _Pragma("unroll") for (int m = 0; m < 4; ++m) _Pragma("unroll") for (int k = 0; k < 2; ++k) dst[m][k] = *(const LAS h8*)(lds + G_SA(b, h) + aoff + m * 2048 + k * 1024); } while (0)
; #define G_LDB(dst, b, h) do { _Pragma("unroll") for (int n = 0; n < 2; ++n) _Pragma("unroll") for (int k = 0; k < 2; ++k) dst[n][k] = *(const LAS h8*)(lds + G_SB(b, h) + boff + n * 2048 + k * 1024); } while (0)
; #define G_MMA(ai, bj, At, Bt) do { __builtin_amdgcn_s_setprio(1); _Pragma("unroll") for (int m = 0; m < 4; ++m) _Pragma("unroll") for (int n = 0; n < 2; ++n) _Pragma("unroll") for (int k = 0; k < 2; ++k) \
;     acc[ai][bj][m][n] = __builtin_amdgcn_mfma_f32_16x16x32_f16(Bt[n][k], At[m][k], acc[ai][bj][m][n], 0, 0, 0); __builtin_amdgcn_s_setprio(0); } while (0)
; #define G_WAIT_V(n) asm volatile("s_waitcnt vmcnt(" #n ")" ::: "memory")
; #define G_WAIT_L(n) asm volatile("s_waitcnt lgkmcnt(" #n ")" ::: "memory")
; #define G_BAR __builtin_amdgcn_s_barrier()
; #define G_SCHED __builtin_amdgcn_sched_barrier(0)
; template <bool PERM, class Sched, class Epi>
; DI void gemm256(LAS unsigned char* lds, const Sched& S, const Epi& E, int wv_) {
;     ...
;       const bool last = (t == nt - 2);
;       const char* a1 = cA + (size_t)(t + 1) * kstep;
;       const char* a2 = last ? nA : cA + (size_t)(t + 2) * kstep;
;       const char* b2 = last ? nB : cB + (size_t)(t + 2) * kstep;
;       const char* a3 = a2 + kstep;
;       const char* b3 = b2 + kstep;
;       G_LDB(B0, 0, 0); G_SCHED; G_LDA(At, 0, 0); G_STAGE(G_SA(1, 1), a1 + chA, cvA0, cvA1);
;       G_WAIT_L(8); G_BAR; G_WAIT_L(0); G_MMA(0, 0, At, B0); G_BAR; G_SCHED;
;       G_LDB(B1, 0, 1); G_STAGE(G_SB(0, 0), b2, cvB0, cvB1);
;       G_BAR; G_WAIT_L(0); G_MMA(0, 1, At, B1); G_BAR;
;       G_LDA(At, 0, 1); G_STAGE(G_SA(0, 0), a2, cvA0, cvA1);
;       G_BAR; G_WAIT_L(0); G_MMA(1, 0, At, B0); G_BAR; G_SCHED;
;       G_STAGE(G_SB(0, 1), b2 + chB, cvB0, cvB1);
;       G_WAIT_V(6); G_BAR; G_MMA(1, 1, At, B1); G_BAR;
.LBB0_2656:
	s_waitcnt vmcnt(0)
	s_add_i32 s91, s22, 2
	ds_read_b128 v[130:133], v216
	ds_read_b128 v[134:137], v216 offset:1024
	ds_read_b128 v[138:141], v216 offset:2048
	ds_read_b128 v[142:145], v216 offset:3072
	v_lshl_add_u64 v[192:193], s[20:21], 0, v[158:159]
	s_add_i32 m0, s35, 0xc000
	ds_read_b128 v[146:149], v1
	ds_read_b128 v[164:167], v1 offset:1024
	ds_read_b128 v[168:171], v1 offset:2048
	ds_read_b128 v[172:175], v1 offset:3072
	ds_read_b128 v[176:179], v1 offset:4096
	ds_read_b128 v[180:183], v1 offset:5120
	ds_read_b128 v[184:187], v1 offset:6144
	ds_read_b128 v[188:191], v1 offset:7168
	global_load_lds_dwordx4 v[192:193], off
	s_add_i32 m0, s35, 0xe000
	v_lshl_add_u64 v[192:193], s[20:21], 0, v[160:161]
	global_load_lds_dwordx4 v[192:193], off
	s_waitcnt lgkmcnt(8)
	s_barrier
	s_waitcnt lgkmcnt(0)
	s_waitcnt lgkmcnt(0)
	v_mfma_f32_16x16x32_f16 v[126:129], v[130:133], v[146:149], v[126:129]
	s_add_u32 s23, s20, 0xfff00080
	s_addc_u32 s24, s21, -1
	s_cmp_eq_u32 s27, s22
	s_cselect_b32 s22, vcc_hi, s46
	s_cselect_b32 s25, s29, s24
	s_cselect_b32 s24, s56, s23
	s_cselect_b32 s23, vcc_lo, s74
	v_mfma_f32_16x16x32_f16 v[122:125], v[138:141], v[146:149], v[122:125]
	v_mfma_f32_16x16x32_f16 v[110:113], v[130:133], v[168:171], v[110:113]
	v_mfma_f32_16x16x32_f16 v[106:109], v[138:141], v[168:171], v[106:109]
	v_mfma_f32_16x16x32_f16 v[94:97], v[130:133], v[176:179], v[94:97]
	v_mfma_f32_16x16x32_f16 v[90:93], v[138:141], v[176:179], v[90:93]
	v_mfma_f32_16x16x32_f16 v[78:81], v[130:133], v[184:187], v[78:81]
	v_mfma_f32_16x16x32_f16 v[74:77], v[138:141], v[184:187], v[74:77]
	v_mfma_f32_16x16x32_f16 v[126:129], v[134:137], v[164:167], v[126:129]
	v_mfma_f32_16x16x32_f16 v[122:125], v[142:145], v[164:167], v[122:125]
	v_mfma_f32_16x16x32_f16 v[110:113], v[134:137], v[172:175], v[110:113]
	v_mfma_f32_16x16x32_f16 v[106:109], v[142:145], v[172:175], v[106:109]
	v_mfma_f32_16x16x32_f16 v[94:97], v[134:137], v[180:183], v[94:97]
	v_mfma_f32_16x16x32_f16 v[90:93], v[142:145], v[180:183], v[90:93]
	v_mfma_f32_16x16x32_f16 v[78:81], v[134:137], v[188:191], v[78:81]
	v_mfma_f32_16x16x32_f16 v[74:77], v[142:145], v[188:191], v[74:77]
	s_barrier
	s_mov_b32 m0, s36
	ds_read_b128 v[192:195], v217
	ds_read_b128 v[196:199], v217 offset:1024
	v_lshl_add_u64 v[208:209], s[22:23], 0, v[150:151]
	ds_read_b128 v[200:203], v217 offset:2048
	ds_read_b128 v[204:207], v217 offset:3072
	global_load_lds_dwordx4 v[208:209], off
	s_mov_b32 m0, s37
	v_lshl_add_u64 v[210:211], s[22:23], 0, v[152:153]
	global_load_lds_dwordx4 v[210:211], off
	s_barrier
	s_waitcnt lgkmcnt(0)
	s_waitcnt lgkmcnt(0)
	v_mfma_f32_16x16x32_f16 v[118:121], v[192:195], v[146:149], v[118:121]
	v_mfma_f32_16x16x32_f16 v[114:117], v[200:203], v[146:149], v[114:117]
	v_mfma_f32_16x16x32_f16 v[102:105], v[192:195], v[168:171], v[102:105]
	v_mfma_f32_16x16x32_f16 v[98:101], v[200:203], v[168:171], v[98:101]
	v_mfma_f32_16x16x32_f16 v[86:89], v[192:195], v[176:179], v[86:89]
	v_mfma_f32_16x16x32_f16 v[82:85], v[200:203], v[176:179], v[82:85]
	v_mfma_f32_16x16x32_f16 v[70:73], v[192:195], v[184:187], v[70:73]
	v_mfma_f32_16x16x32_f16 v[66:69], v[200:203], v[184:187], v[66:69]
	v_mfma_f32_16x16x32_f16 v[118:121], v[196:199], v[164:167], v[118:121]
	v_mfma_f32_16x16x32_f16 v[114:117], v[204:207], v[164:167], v[114:117]
	v_mfma_f32_16x16x32_f16 v[102:105], v[196:199], v[172:175], v[102:105]
	v_mfma_f32_16x16x32_f16 v[98:101], v[204:207], v[172:175], v[98:101]
	v_mfma_f32_16x16x32_f16 v[86:89], v[196:199], v[180:183], v[86:89]
	v_mfma_f32_16x16x32_f16 v[82:85], v[204:207], v[180:183], v[82:85]
	v_mfma_f32_16x16x32_f16 v[70:73], v[196:199], v[188:191], v[70:73]
	v_mfma_f32_16x16x32_f16 v[66:69], v[204:207], v[188:191], v[66:69]
	s_mov_b32 m0, s35
	v_lshl_add_u64 v[212:213], s[24:25], 0, v[150:151]
	s_barrier
	ds_read_b128 v[146:149], v1 offset:16384
	ds_read_b128 v[164:167], v1 offset:17408
	ds_read_b128 v[168:171], v1 offset:18432
	ds_read_b128 v[172:175], v1 offset:19456
	ds_read_b128 v[176:179], v1 offset:20480
	ds_read_b128 v[180:183], v1 offset:21504
	ds_read_b128 v[184:187], v1 offset:22528
	ds_read_b128 v[188:191], v1 offset:23552
	global_load_lds_dwordx4 v[212:213], off
	s_mov_b32 m0, s52
	v_lshl_add_u64 v[214:215], s[24:25], 0, v[152:153]
	global_load_lds_dwordx4 v[214:215], off
	s_barrier
	s_waitcnt lgkmcnt(0)
	s_waitcnt lgkmcnt(0)
	v_mfma_f32_16x16x32_f16 v[62:65], v[130:133], v[146:149], v[62:65]
	v_mfma_f32_16x16x32_f16 v[58:61], v[138:141], v[146:149], v[58:61]
	v_mfma_f32_16x16x32_f16 v[46:49], v[130:133], v[168:171], v[46:49]
	v_mfma_f32_16x16x32_f16 v[42:45], v[138:141], v[168:171], v[42:45]
	v_mfma_f32_16x16x32_f16 v[30:33], v[130:133], v[176:179], v[30:33]
	v_mfma_f32_16x16x32_f16 v[26:29], v[138:141], v[176:179], v[26:29]
	v_mfma_f32_16x16x32_f16 v[14:17], v[130:133], v[184:187], v[14:17]
	v_mfma_f32_16x16x32_f16 v[10:13], v[138:141], v[184:187], v[10:13]
	v_mfma_f32_16x16x32_f16 v[62:65], v[134:137], v[164:167], v[62:65]
	v_mfma_f32_16x16x32_f16 v[58:61], v[142:145], v[164:167], v[58:61]
	v_mfma_f32_16x16x32_f16 v[46:49], v[134:137], v[172:175], v[46:49]
	v_mfma_f32_16x16x32_f16 v[42:45], v[142:145], v[172:175], v[42:45]
	v_mfma_f32_16x16x32_f16 v[30:33], v[134:137], v[180:183], v[30:33]
	v_mfma_f32_16x16x32_f16 v[26:29], v[142:145], v[180:183], v[26:29]
	v_mfma_f32_16x16x32_f16 v[14:17], v[134:137], v[188:191], v[14:17]
	v_mfma_f32_16x16x32_f16 v[10:13], v[142:145], v[188:191], v[10:13]
	s_barrier
	s_add_u32 s40, s22, 0x100000
	s_addc_u32 s41, s23, 0
	s_mov_b32 m0, s53
	v_lshl_add_u64 v[130:131], s[40:41], 0, v[150:151]
	global_load_lds_dwordx4 v[130:131], off
	s_mov_b32 m0, s58
	v_lshl_add_u64 v[130:131], s[40:41], 0, v[152:153]
	global_load_lds_dwordx4 v[130:131], off
	s_waitcnt vmcnt(6)
	s_barrier
; #define G_STAGE(bufoff, gbase, v0, v1) do { \
;     __builtin_amdgcn_global_load_lds((const unsigned*)((const char*)(gbase) + (v0)), (LAS unsigned*)(lds + (bufoff) + ldsw), 16, 0, 0); \
;     __builtin_amdgcn_global_load_lds((const unsigned*)((const char*)(gbase) + (v1)), (LAS unsigned*)(lds + (bufoff) + ldsw + 8192), 16, 0, 0); } while (0)
; #define G_LDA(dst, b, h) do { _Pragma("unroll") for (int m = 0; m < 4; ++m) _Pragma("unroll") for (int k = 0; k < 2; ++k) dst[m][k] = *(const LAS h8*)(lds + G_SA(b, h) + aoff + m * 2048 + k * 1024); } while (0)
; #define G_LDB(dst, b, h) do { _Pragma("unroll") for (int n = 0; n < 2; ++n) _Pragma("unroll") for (int k = 0; k < 2; ++k) dst[n][k] = *(const LAS h8*)(lds + G_SB(b, h) + boff + n * 2048 + k * 1024); } while (0)
; #define G_MMA(ai, bj, At, Bt) do { __builtin_amdgcn_s_setprio(1); _Pragma("unroll") for (int m = 0; m < 4; ++m) _Pragma("unroll") for (int n = 0; n < 2; ++n) _Pragma("unroll") for (int k = 0; k < 2; ++k) \
;     acc[ai][bj][m][n] = __builtin_amdgcn_mfma_f32_16x16x32_f16(Bt[n][k], At[m][k], acc[ai][bj][m][n], 0, 0, 0); __builtin_amdgcn_s_setprio(0); } while (0)
; #define G_WAIT_V(n) asm volatile("s_waitcnt vmcnt(" #n ")" ::: "memory")
; #define G_WAIT_L(n) asm volatile("s_waitcnt lgkmcnt(" #n ")" ::: "memory")
; #define G_BAR __builtin_amdgcn_s_barrier()
; #define G_SCHED __builtin_amdgcn_sched_barrier(0)
; template <bool PERM, class Sched, class Epi>
; DI void gemm256(LAS unsigned char* lds, const Sched& S, const Epi& E, int wv_) {
;     ...
;       G_WAIT_V(6); G_BAR; G_MMA(1, 1, At, B1); G_BAR;
;       G_LDB(B0, 1, 0); G_SCHED; G_LDA(At, 1, 0); G_STAGE(G_SA(0, 1), a2 + chA, cvA0, cvA1);
;       G_WAIT_L(8); G_BAR; G_WAIT_L(0); G_MMA(0, 0, At, B0); G_BAR; G_SCHED;
;       G_LDB(B1, 1, 1); G_STAGE(G_SB(1, 0), b3, cvB0, cvB1);
	v_mfma_f32_16x16x32_f16 v[54:57], v[192:195], v[146:149], v[54:57]
	v_mfma_f32_16x16x32_f16 v[50:53], v[200:203], v[146:149], v[50:53]
	v_mfma_f32_16x16x32_f16 v[38:41], v[192:195], v[168:171], v[38:41]
	v_mfma_f32_16x16x32_f16 v[34:37], v[200:203], v[168:171], v[34:37]
	v_mfma_f32_16x16x32_f16 v[22:25], v[192:195], v[176:179], v[22:25]
	v_mfma_f32_16x16x32_f16 v[18:21], v[200:203], v[176:179], v[18:21]
	v_mfma_f32_16x16x32_f16 v[6:9], v[192:195], v[184:187], v[6:9]
	v_mfma_f32_16x16x32_f16 v[2:5], v[200:203], v[184:187], v[2:5]
	v_mfma_f32_16x16x32_f16 v[54:57], v[196:199], v[164:167], v[54:57]
	v_mfma_f32_16x16x32_f16 v[50:53], v[204:207], v[164:167], v[50:53]
	v_mfma_f32_16x16x32_f16 v[38:41], v[196:199], v[172:175], v[38:41]
	v_mfma_f32_16x16x32_f16 v[34:37], v[204:207], v[172:175], v[34:37]
	v_mfma_f32_16x16x32_f16 v[22:25], v[196:199], v[180:183], v[22:25]
	v_mfma_f32_16x16x32_f16 v[18:21], v[204:207], v[180:183], v[18:21]
	v_mfma_f32_16x16x32_f16 v[6:9], v[196:199], v[188:191], v[6:9]
	v_mfma_f32_16x16x32_f16 v[2:5], v[204:207], v[188:191], v[2:5]
	s_barrier
	ds_read_b128 v[130:133], v218
	ds_read_b128 v[134:137], v218 offset:1024
	ds_read_b128 v[138:141], v218 offset:2048
	ds_read_b128 v[142:145], v218 offset:3072
	s_add_u32 s24, s24, 0x100000
	s_addc_u32 s25, s25, 0
	s_mov_b32 m0, s59
	v_lshl_add_u64 v[192:193], s[24:25], 0, v[150:151]
	ds_read_b128 v[146:149], v1 offset:32768
	ds_read_b128 v[164:167], v1 offset:33792
	ds_read_b128 v[168:171], v1 offset:34816
	ds_read_b128 v[172:175], v1 offset:35840
	ds_read_b128 v[176:179], v1 offset:36864
	ds_read_b128 v[180:183], v1 offset:37888
	ds_read_b128 v[184:187], v1 offset:38912
	ds_read_b128 v[188:191], v1 offset:39936
	global_load_lds_dwordx4 v[192:193], off
	s_mov_b32 m0, s61
	v_lshl_add_u64 v[192:193], s[24:25], 0, v[152:153]
	global_load_lds_dwordx4 v[192:193], off
	s_waitcnt lgkmcnt(8)
	s_barrier
	s_waitcnt lgkmcnt(0)
	s_waitcnt lgkmcnt(0)
	v_mfma_f32_16x16x32_f16 v[126:129], v[130:133], v[146:149], v[126:129]
	v_mfma_f32_16x16x32_f16 v[122:125], v[138:141], v[146:149], v[122:125]
	v_mfma_f32_16x16x32_f16 v[110:113], v[130:133], v[168:171], v[110:113]
	v_mfma_f32_16x16x32_f16 v[106:109], v[138:141], v[168:171], v[106:109]
	v_mfma_f32_16x16x32_f16 v[94:97], v[130:133], v[176:179], v[94:97]
	v_mfma_f32_16x16x32_f16 v[90:93], v[138:141], v[176:179], v[90:93]
	v_mfma_f32_16x16x32_f16 v[78:81], v[130:133], v[184:187], v[78:81]
	v_mfma_f32_16x16x32_f16 v[74:77], v[138:141], v[184:187], v[74:77]
	v_mfma_f32_16x16x32_f16 v[126:129], v[134:137], v[164:167], v[126:129]
	v_mfma_f32_16x16x32_f16 v[122:125], v[142:145], v[164:167], v[122:125]
	v_mfma_f32_16x16x32_f16 v[110:113], v[134:137], v[172:175], v[110:113]
	v_mfma_f32_16x16x32_f16 v[106:109], v[142:145], v[172:175], v[106:109]
	v_mfma_f32_16x16x32_f16 v[94:97], v[134:137], v[180:183], v[94:97]
	v_mfma_f32_16x16x32_f16 v[90:93], v[142:145], v[180:183], v[90:93]
	v_mfma_f32_16x16x32_f16 v[78:81], v[134:137], v[188:191], v[78:81]
	v_mfma_f32_16x16x32_f16 v[74:77], v[142:145], v[188:191], v[74:77]
	s_barrier
	s_mov_b32 m0, s69
	ds_read_b128 v[192:195], v219
	ds_read_b128 v[196:199], v219 offset:1024
	v_lshl_add_u64 v[208:209], v[208:209], 0, s[86:87]
	ds_read_b128 v[200:203], v219 offset:2048
	ds_read_b128 v[204:207], v219 offset:3072
	global_load_lds_dwordx4 v[208:209], off
	s_mov_b32 m0, s78
	v_lshl_add_u64 v[208:209], v[210:211], 0, s[86:87]
	global_load_lds_dwordx4 v[208:209], off
	s_barrier
; #define G_STAGE(bufoff, gbase, v0, v1) do { \
;     __builtin_amdgcn_global_load_lds((const unsigned*)((const char*)(gbase) + (v0)), (LAS unsigned*)(lds + (bufoff) + ldsw), 16, 0, 0); \
;     __builtin_amdgcn_global_load_lds((const unsigned*)((const char*)(gbase) + (v1)), (LAS unsigned*)(lds + (bufoff) + ldsw + 8192), 16, 0, 0); } while (0)
; #define G_LDA(dst, b, h) do { _Pragma("unroll") for (int m = 0; m < 4; ++m) _Pragma("unroll") for (int k = 0; k < 2; ++k) dst[m][k] = *(const LAS h8*)(lds + G_SA(b, h) + aoff + m * 2048 + k * 1024); } while (0)
; #define G_LDB(dst, b, h) do { _Pragma("unroll") for (int n = 0; n < 2; ++n) _Pragma("unroll") for (int k = 0; k < 2; ++k) dst[n][k] = *(const LAS h8*)(lds + G_SB(b, h) + boff + n * 2048 + k * 1024); } while (0)
; #define G_MMA(ai, bj, At, Bt) do { __builtin_amdgcn_s_setprio(1); _Pragma("unroll") for (int m = 0; m < 4; ++m) _Pragma("unroll") for (int n = 0; n < 2; ++n) _Pragma("unroll") for (int k = 0; k < 2; ++k) \
;     acc[ai][bj][m][n] = __builtin_amdgcn_mfma_f32_16x16x32_f16(Bt[n][k], At[m][k], acc[ai][bj][m][n], 0, 0, 0); __builtin_amdgcn_s_setprio(0); } while (0)
; #define G_WAIT_V(n) asm volatile("s_waitcnt vmcnt(" #n ")" ::: "memory")
; #define G_WAIT_L(n) asm volatile("s_waitcnt lgkmcnt(" #n ")" ::: "memory")
; #define G_BAR __builtin_amdgcn_s_barrier()
; #define G_SCHED __builtin_amdgcn_sched_barrier(0)
; template <bool PERM, class Sched, class Epi>
; DI void gemm256(LAS unsigned char* lds, const Sched& S, const Epi& E, int wv_) {
;     ...
;       G_LDB(B1, 1, 1); G_STAGE(G_SB(1, 0), b3, cvB0, cvB1);
;       G_BAR; G_WAIT_L(0); G_MMA(0, 1, At, B1); G_BAR;
;       G_LDA(At, 1, 1); G_STAGE(G_SA(1, 0), a3, cvA0, cvA1);
;       G_BAR; G_WAIT_L(0); G_MMA(1, 0, At, B0); G_BAR; G_SCHED;
;       G_STAGE(G_SB(1, 1), b3 + chB, cvB0, cvB1);
;       G_WAIT_V(6); G_BAR; G_MMA(1, 1, At, B1); G_BAR;
;     }
	s_waitcnt lgkmcnt(0)
	s_waitcnt lgkmcnt(0)
	v_mfma_f32_16x16x32_f16 v[118:121], v[192:195], v[146:149], v[118:121]
	v_mfma_f32_16x16x32_f16 v[114:117], v[200:203], v[146:149], v[114:117]
	v_mfma_f32_16x16x32_f16 v[102:105], v[192:195], v[168:171], v[102:105]
	v_mfma_f32_16x16x32_f16 v[98:101], v[200:203], v[168:171], v[98:101]
	v_mfma_f32_16x16x32_f16 v[86:89], v[192:195], v[176:179], v[86:89]
	v_mfma_f32_16x16x32_f16 v[82:85], v[200:203], v[176:179], v[82:85]
	v_mfma_f32_16x16x32_f16 v[70:73], v[192:195], v[184:187], v[70:73]
	v_mfma_f32_16x16x32_f16 v[66:69], v[200:203], v[184:187], v[66:69]
	v_mfma_f32_16x16x32_f16 v[118:121], v[196:199], v[164:167], v[118:121]
	v_mfma_f32_16x16x32_f16 v[114:117], v[204:207], v[164:167], v[114:117]
	v_mfma_f32_16x16x32_f16 v[102:105], v[196:199], v[172:175], v[102:105]
	v_mfma_f32_16x16x32_f16 v[98:101], v[204:207], v[172:175], v[98:101]
	v_mfma_f32_16x16x32_f16 v[86:89], v[196:199], v[180:183], v[86:89]
	v_mfma_f32_16x16x32_f16 v[82:85], v[204:207], v[180:183], v[82:85]
	v_mfma_f32_16x16x32_f16 v[70:73], v[196:199], v[188:191], v[70:73]
	v_mfma_f32_16x16x32_f16 v[66:69], v[204:207], v[188:191], v[66:69]
	s_mov_b32 m0, s79
	v_lshl_add_u64 v[208:209], v[212:213], 0, s[86:87]
	s_barrier
	ds_read_b128 v[146:149], v1 offset:49152
	ds_read_b128 v[164:167], v1 offset:50176
	ds_read_b128 v[168:171], v1 offset:51200
	ds_read_b128 v[172:175], v1 offset:52224
	ds_read_b128 v[176:179], v1 offset:53248
	ds_read_b128 v[180:183], v1 offset:54272
	ds_read_b128 v[184:187], v1 offset:55296
	ds_read_b128 v[188:191], v1 offset:56320
	global_load_lds_dwordx4 v[208:209], off
	s_mov_b32 m0, s83
	v_lshl_add_u64 v[208:209], v[214:215], 0, s[86:87]
	global_load_lds_dwordx4 v[208:209], off
	s_barrier
	s_waitcnt lgkmcnt(0)
	s_waitcnt lgkmcnt(0)
	v_mfma_f32_16x16x32_f16 v[62:65], v[130:133], v[146:149], v[62:65]
	v_mfma_f32_16x16x32_f16 v[58:61], v[138:141], v[146:149], v[58:61]
	v_mfma_f32_16x16x32_f16 v[46:49], v[130:133], v[168:171], v[46:49]
	v_mfma_f32_16x16x32_f16 v[42:45], v[138:141], v[168:171], v[42:45]
	v_mfma_f32_16x16x32_f16 v[30:33], v[130:133], v[176:179], v[30:33]
	v_mfma_f32_16x16x32_f16 v[26:29], v[138:141], v[176:179], v[26:29]
	v_mfma_f32_16x16x32_f16 v[14:17], v[130:133], v[184:187], v[14:17]
	v_mfma_f32_16x16x32_f16 v[10:13], v[138:141], v[184:187], v[10:13]
	v_mfma_f32_16x16x32_f16 v[62:65], v[134:137], v[164:167], v[62:65]
	v_mfma_f32_16x16x32_f16 v[58:61], v[142:145], v[164:167], v[58:61]
	v_mfma_f32_16x16x32_f16 v[46:49], v[134:137], v[172:175], v[46:49]
	v_mfma_f32_16x16x32_f16 v[42:45], v[142:145], v[172:175], v[42:45]
	v_mfma_f32_16x16x32_f16 v[30:33], v[134:137], v[180:183], v[30:33]
	v_mfma_f32_16x16x32_f16 v[26:29], v[142:145], v[180:183], v[26:29]
	v_mfma_f32_16x16x32_f16 v[14:17], v[134:137], v[188:191], v[14:17]
	v_mfma_f32_16x16x32_f16 v[10:13], v[142:145], v[188:191], v[10:13]
	s_barrier
	s_add_u32 s22, s22, 0x100080
	s_addc_u32 s23, s23, 0
	s_mov_b32 m0, s84
	v_lshl_add_u64 v[130:131], s[22:23], 0, v[150:151]
	global_load_lds_dwordx4 v[130:131], off
	s_mov_b32 m0, s85
	v_lshl_add_u64 v[130:131], s[22:23], 0, v[152:153]
	global_load_lds_dwordx4 v[130:131], off
	s_waitcnt vmcnt(6)
	s_barrier
	v_mfma_f32_16x16x32_f16 v[54:57], v[192:195], v[146:149], v[54:57]
	v_mfma_f32_16x16x32_f16 v[50:53], v[200:203], v[146:149], v[50:53]
	v_mfma_f32_16x16x32_f16 v[38:41], v[192:195], v[168:171], v[38:41]
	v_mfma_f32_16x16x32_f16 v[34:37], v[200:203], v[168:171], v[34:37]
	v_mfma_f32_16x16x32_f16 v[22:25], v[192:195], v[176:179], v[22:25]
	v_mfma_f32_16x16x32_f16 v[18:21], v[200:203], v[176:179], v[18:21]
	v_mfma_f32_16x16x32_f16 v[6:9], v[192:195], v[184:187], v[6:9]
	v_mfma_f32_16x16x32_f16 v[2:5], v[200:203], v[184:187], v[2:5]
	v_mfma_f32_16x16x32_f16 v[54:57], v[196:199], v[164:167], v[54:57]
	v_mfma_f32_16x16x32_f16 v[50:53], v[204:207], v[164:167], v[50:53]
	v_mfma_f32_16x16x32_f16 v[38:41], v[196:199], v[172:175], v[38:41]
	v_mfma_f32_16x16x32_f16 v[34:37], v[204:207], v[172:175], v[34:37]
	v_mfma_f32_16x16x32_f16 v[22:25], v[196:199], v[180:183], v[22:25]
	v_mfma_f32_16x16x32_f16 v[18:21], v[204:207], v[180:183], v[18:21]
	v_mfma_f32_16x16x32_f16 v[6:9], v[196:199], v[188:191], v[6:9]
	v_mfma_f32_16x16x32_f16 v[2:5], v[204:207], v[188:191], v[2:5]
	s_add_u32 s20, s20, 0x100
	s_addc_u32 s21, s21, 0
	s_add_u32 s46, s46, 0x100
	s_addc_u32 s74, s74, 0
	s_cmp_ge_i32 s91, s75
	s_mov_b32 s22, s91
	s_barrier
	s_cbranch_scc0 .LBB0_2656
	v_readlane_b32 s91, v254, 47
	s_mov_b32 s56, 0x8fff
	s_branch .LBB0_2659
